# GEMM K-loops: LDS-DMA source addresses formed as SGPR base + 32-bit VGPR offset (no per-load 64-bit VALU add); out-proj epilogue x loads prefetched 7 steps ahead
# speedup vs baseline: 1.0097x; 1.0097x over previous
; #define PG8_STAGE(bufoff, gbase, voff) do { _Pragma("unroll") for (int _i = 0; _i < 2; ++_i) \
;         __builtin_amdgcn_global_load_lds((const unsigned*)((const char*)(gbase) + (voff)[_i]), (PG8_LAS unsigned*)(lds + (bufoff) + ldsw + _i * 8192), 16, 0, 0); } while (0)
; #define PG8_WAIT_V(n) asm volatile("s_waitcnt vmcnt(" #n ")" ::: "memory")
; #define PG8_BAR __builtin_amdgcn_s_barrier()
; template <class Epi, class Sched, bool ALIGN_EPI = false, bool SP2 = false>
; __device__ __forceinline__ void gemm_phase(PG8_LAS unsigned char* lds, const Gemm g, const Sched& S, const Epi& E) {
;     const int tid = threadIdx.x, wid = __builtin_amdgcn_readfirstlane(tid >> 6), lane = tid & 63, wr = wid >> 2, wc = wid & 3, fr = lane & 15, fq = lane >> 4;
;     const int K = g.K, nt = K / BK;
;     unsigned voffA[2], voffB[2];
; #pragma unroll
;     for (int i = 0; i < 2; ++i) { int R, C; stage_rc(tid * 16 + i * 8192, R, C); const int Rb = Epi::PERM ? ((R & ~31) + perm32(R & 31)) : R;
;         voffA[i] = (unsigned)(R * K + C) * 2u; voffB[i] = (unsigned)(Rb * K + C) * 2u; }
;     const size_t kstep = (size_t)(BK * 2);
;     const size_t hstep = (size_t)HALF * K * 2;
;     const size_t tstep = 2 * hstep;
;     const unsigned ldsw = (unsigned)wid * 1024u;
;     const int aoff = lds_byte(wr * 64 + fr, fq * 8), boff = lds_byte(wc * 32 + fr, fq * 8);
;     ...
;     if constexpr (SP2) {
;         PG8_STAGE(PG8_SB(0, 0), cB, voffB); PG8_STAGE(PG8_SB(0, 1), cB + hstep, voffB); PG8_STAGE(PG8_SA(0, 0), cA, voffA); PG8_STAGE(PG8_SA(0, 1), cA + hstep, voffA);
;         if (wr == 1) PG8_BAR;
;         PG8_WAIT_V(2); PG8_BAR;
;         PG8_STAGE(PG8_SB(1, 0), cB + kstep, voffB); PG8_STAGE(PG8_SA(1, 0), cA + kstep, voffA); PG8_STAGE(PG8_SB(1, 1), cB + hstep + kstep, voffB);
;         PG8_WAIT_V(6); PG8_BAR;
.LBB0_225:
	s_mov_b64 s[26:27], 0x80
	s_and_b32 s10, s1, 3
	s_add_i32 m0, s49, 0x18000
	v_lshl_add_u64 v[6:7], v[6:7], 0, s[26:27]
	s_lshl_b32 s76, s8, 6
	s_lshl_b32 s11, s8, 13
	s_lshl_b32 s89, s10, 5
	s_lshl_b32 s28, s10, 12
	s_waitcnt vmcnt(2)
	s_barrier
	global_load_lds_dwordx4 v[6:7], off
	v_lshl_add_u64 v[4:5], v[4:5], 0, s[26:27]
	s_add_i32 m0, s49, 0x1a000
	s_add_i32 s78, s49, 0x8000
	s_add_i32 s79, s49, 0xa000
	global_load_lds_dwordx4 v[4:5], off
	v_lshl_add_u64 v[0:1], v[0:1], 0, s[26:27]
	s_mov_b32 m0, s78
	s_add_u32 s8, s6, 0x80080
	global_load_lds_dwordx4 v[0:1], off
	v_lshl_add_u64 v[0:1], v[2:3], 0, s[26:27]
	s_mov_b32 m0, s79
	s_addc_u32 s9, s7, 0
	global_load_lds_dwordx4 v[0:1], off
	s_add_i32 m0, s49, 0x1c000
	s_nop 0
	global_load_lds_dwordx4 v136, s[8:9]
	v_lshl_add_u64 v[0:1], s[8:9], 0, v[140:141]
	s_add_i32 m0, s49, 0x1e000
	v_bfe_u32 v155, v186, 4, 2
	global_load_lds_dwordx4 v[0:1], off
	v_and_b32_e32 v133, 15, v186
	v_lshlrev_b32_e32 v0, 4, v155
	v_lshlrev_b32_e32 v2, 2, v186
	v_lshlrev_b32_e32 v3, 6, v186
	s_movk_i32 s8, 0x3c0
	v_lshl_or_b32 v1, v133, 6, v0
	v_and_b32_e32 v2, 32, v2
	v_and_or_b32 v0, v3, s8, v0
	s_cmpk_lt_u32 s0, 0x100
	v_bitop3_b32 v168, s28, v0, v2 bitop3:0xf6
	s_cselect_b64 s[28:29], -1, 0
	s_add_i32 s68, s76, 0xfffff000
	s_or_b32 s69, s89, 0xffffe800
	s_cmp_eq_u32 s10, 0
	v_lshlrev_b32_e32 v0, 9, v186
	v_bitop3_b32 v1, v1, s11, v2 bitop3:0xde
	s_cselect_b64 s[30:31], -1, 0
	s_cmpk_gt_u32 s0, 0xff
	v_and_b32_e32 v0, 0x70000, v0
	v_lshlrev_b32_e32 v2, 12, v11
	s_cselect_b64 s[34:35], -1, 0
	s_bfe_u32 s0, s1, 0x10001
	v_or3_b32 v0, v8, v0, v2
	v_writelane_b32 v238, s0, 25
	s_lshl_b32 s0, s1, 6
	v_add_u32_e32 v144, v0, v9
	v_lshlrev_b32_e32 v0, 5, v10
	s_and_b32 s0, s0, 64
	s_ashr_i32 s90, s3, 31
	s_ashr_i32 s91, s2, 31
	v_and_b32_e32 v0, 0xf0000, v0
	s_waitcnt vmcnt(6)
	s_add_u32 s36, s86, 0x183e1000
	v_or3_b32 v0, v8, v0, v2
	s_addc_u32 s37, s87, 0
	v_add_u32_e32 v146, v0, v9
	s_add_i32 s70, 0, 0x10000
	s_add_i32 s72, 0, 0x14000
	v_mbcnt_lo_u32_b32 v0, -1, 0
	v_mov_b32_e32 v145, v143
	v_mov_b32_e32 v147, v143
	v_mov_b64_e32 v[148:149], 0x600
	v_mov_b64_e32 v[150:151], 0x5ff
	v_add_u32_e32 v169, s70, v168
	v_add_u32_e32 v170, s72, v168
	v_add_u32_e32 v171, 0, v1
	s_mov_b32 s77, 0x8200
	s_movk_i32 s71, 0x82
	v_mov_b32_e32 v172, 0x358637bd
	s_mov_b32 s82, 0x800000
	s_mov_b64 s[38:39], 0x1000
	v_mov_b64_e32 v[152:153], 0x3ff
	v_mov_b32_e32 v173, 0x3e0293ee
	v_mov_b32_e32 v174, 0x3e38aa3b
	v_mbcnt_hi_u32_b32 v175, -1, v0
	s_barrier
	v_writelane_b32 v238, s0, 26
	s_branch .LBB0_228

; #define PG8_STAGE(bufoff, gbase, voff) do { _Pragma("unroll") for (int _i = 0; _i < 2; ++_i) \
;         __builtin_amdgcn_global_load_lds((const unsigned*)((const char*)(gbase) + (voff)[_i]), (PG8_LAS unsigned*)(lds + (bufoff) + ldsw + _i * 8192), 16, 0, 0); } while (0)
; #define PG8_LDA(dst, b, h) do { _Pragma("unroll") for (int m = 0; m < 4; ++m) _Pragma("unroll") for (int k = 0; k < 2; ++k) dst[m][k] = *(const PG8_LAS bf16x8*)(lds + PG8_SA(b, h) + aoff + m * 2048 + k * 1024); } while (0)
; #define PG8_LDB(dst, b, h) do { _Pragma("unroll") for (int n = 0; n < 2; ++n) _Pragma("unroll") for (int k = 0; k < 2; ++k) dst[n][k] = *(const PG8_LAS bf16x8*)(lds + PG8_SB(b, h) + boff + n * 2048 + k * 1024); } while (0)
; #define PG8_MMA(ai, bj, At, Bt) do { __builtin_amdgcn_s_setprio(1); _Pragma("unroll") for (int m = 0; m < 4; ++m) _Pragma("unroll") for (int n = 0; n < 2; ++n) _Pragma("unroll") for (int k = 0; k < 2; ++k) \
;         acc[ai][bj][m][n] = __builtin_amdgcn_mfma_f32_16x16x32_bf16(Bt[n][k], At[m][k], acc[ai][bj][m][n], 0, 0, 0); __builtin_amdgcn_s_setprio(0); } while (0)
; #define PG8_WAIT_V(n) asm volatile("s_waitcnt vmcnt(" #n ")" ::: "memory")
; #define PG8_WAIT_L(n) asm volatile("s_waitcnt lgkmcnt(" #n ")" ::: "memory")
; #define PG8_BAR __builtin_amdgcn_s_barrier()
; #define PG8_SCHED __builtin_amdgcn_sched_barrier(0)
; template <class Epi, class Sched, bool ALIGN_EPI = false, bool SP2 = false>
; __device__ __forceinline__ void gemm_phase(PG8_LAS unsigned char* lds, const Gemm g, const Sched& S, const Epi& E) {
;     ...
;             if constexpr (SP2) {
;             PG8_LDB(B0, 0, 0); PG8_LDB(B1, 0, 1); PG8_SCHED; PG8_LDA(At, 0, 0); PG8_STAGE(PG8_SA(1, 1), a1 + hstep, voffA);
;             PG8_WAIT_V(8); PG8_WAIT_L(0); PG8_BAR; PG8_MMA(0, 0, At, B0); PG8_MMA(0, 1, At, B1); PG8_BAR; PG8_SCHED;
;             PG8_LDA(At, 0, 1); PG8_STAGE(PG8_SB(0, 0), b2, voffB); PG8_STAGE(PG8_SB(0, 1), b2 + hstep, voffB); PG8_STAGE(PG8_SA(0, 0), a2, voffA);
;             PG8_WAIT_V(8); PG8_WAIT_L(0); PG8_BAR; PG8_MMA(1, 0, At, B0); PG8_MMA(1, 1, At, B1); PG8_BAR; PG8_SCHED;
.LBB0_244:
	ds_read_b128 v[128:131], v169
	ds_read_b128 v[156:159], v169 offset:1024
	ds_read_b128 v[160:163], v169 offset:2048
	ds_read_b128 v[164:167], v169 offset:3072
	ds_read_b128 v[176:179], v170
	ds_read_b128 v[180:183], v170 offset:1024
	ds_read_b128 v[188:191], v170 offset:2048
	ds_read_b128 v[192:195], v170 offset:3072
	s_add_u32 s0, s4, 0xfff80080
	s_addc_u32 s1, s5, -1
	s_cmp_eq_u32 vcc_hi, 28
	s_cselect_b32 s9, s41, s1
	s_cselect_b32 s8, s51, s0
	s_cselect_b32 s7, s43, vcc_lo
	s_cselect_b32 s6, s56, s57
	s_add_i32 m0, s49, 0xc000
	ds_read_b128 v[196:199], v171
	ds_read_b128 v[200:203], v171 offset:1024
	ds_read_b128 v[204:207], v171 offset:2048
	ds_read_b128 v[208:211], v171 offset:3072
	ds_read_b128 v[212:215], v171 offset:4096
	ds_read_b128 v[216:219], v171 offset:5120
	ds_read_b128 v[220:223], v171 offset:6144
	ds_read_b128 v[224:227], v171 offset:7168
	global_load_lds_dwordx4 v144, s[4:5]
	s_add_i32 m0, s49, 0xe000
	s_nop 0
	global_load_lds_dwordx4 v146, s[4:5]
	s_waitcnt vmcnt(8)
	s_waitcnt lgkmcnt(0)
	s_barrier
	s_setprio 1
	s_waitcnt lgkmcnt(0)
	v_mfma_f32_16x16x32_bf16 v[124:127], v[128:131], v[196:199], v[124:127]
	v_mfma_f32_16x16x32_bf16 v[120:123], v[160:163], v[196:199], v[120:123]
	v_mfma_f32_16x16x32_bf16 v[108:111], v[128:131], v[204:207], v[108:111]
	v_mfma_f32_16x16x32_bf16 v[104:107], v[160:163], v[204:207], v[104:107]
	v_mfma_f32_16x16x32_bf16 v[92:95], v[128:131], v[212:215], v[92:95]
	v_mfma_f32_16x16x32_bf16 v[88:91], v[160:163], v[212:215], v[88:91]
	v_mfma_f32_16x16x32_bf16 v[76:79], v[128:131], v[220:223], v[76:79]
	v_mfma_f32_16x16x32_bf16 v[72:75], v[160:163], v[220:223], v[72:75]
	v_mfma_f32_16x16x32_bf16 v[124:127], v[156:159], v[200:203], v[124:127]
	v_mfma_f32_16x16x32_bf16 v[120:123], v[164:167], v[200:203], v[120:123]
	v_mfma_f32_16x16x32_bf16 v[108:111], v[156:159], v[208:211], v[108:111]
	v_mfma_f32_16x16x32_bf16 v[104:107], v[164:167], v[208:211], v[104:107]
	v_mfma_f32_16x16x32_bf16 v[92:95], v[156:159], v[216:219], v[92:95]
	v_mfma_f32_16x16x32_bf16 v[88:91], v[164:167], v[216:219], v[88:91]
	v_mfma_f32_16x16x32_bf16 v[76:79], v[156:159], v[224:227], v[76:79]
	v_mfma_f32_16x16x32_bf16 v[72:75], v[164:167], v[224:227], v[72:75]
	s_setprio 0
	s_setprio 1
	v_mfma_f32_16x16x32_bf16 v[116:119], v[176:179], v[196:199], v[116:119]
	v_mfma_f32_16x16x32_bf16 v[112:115], v[188:191], v[196:199], v[112:115]
	v_mfma_f32_16x16x32_bf16 v[100:103], v[176:179], v[204:207], v[100:103]
	v_mfma_f32_16x16x32_bf16 v[96:99], v[188:191], v[204:207], v[96:99]
	v_mfma_f32_16x16x32_bf16 v[84:87], v[176:179], v[212:215], v[84:87]
	v_mfma_f32_16x16x32_bf16 v[80:83], v[188:191], v[212:215], v[80:83]
	v_mfma_f32_16x16x32_bf16 v[68:71], v[176:179], v[220:223], v[68:71]
	v_mfma_f32_16x16x32_bf16 v[64:67], v[188:191], v[220:223], v[64:67]
	v_mfma_f32_16x16x32_bf16 v[116:119], v[180:183], v[200:203], v[116:119]
	v_mfma_f32_16x16x32_bf16 v[112:115], v[192:195], v[200:203], v[112:115]
	v_mfma_f32_16x16x32_bf16 v[100:103], v[180:183], v[208:211], v[100:103]
	v_mfma_f32_16x16x32_bf16 v[96:99], v[192:195], v[208:211], v[96:99]
	v_mfma_f32_16x16x32_bf16 v[84:87], v[180:183], v[216:219], v[84:87]
	v_mfma_f32_16x16x32_bf16 v[80:83], v[192:195], v[216:219], v[80:83]
	v_mfma_f32_16x16x32_bf16 v[68:71], v[180:183], v[224:227], v[68:71]
	v_mfma_f32_16x16x32_bf16 v[64:67], v[192:195], v[224:227], v[64:67]
	s_setprio 0
	s_barrier
	s_add_u32 s98, s6, s26
	s_addc_u32 s99, s7, s27
	s_add_u32 s100, s8, s26
	s_addc_u32 s101, s9, s27
	s_add_i32 s0, s70, s58
	s_mov_b32 m0, s0
	ds_read_b128 v[196:199], v171 offset:16384
	ds_read_b128 v[200:203], v171 offset:17408
	ds_read_b128 v[204:207], v171 offset:18432
	ds_read_b128 v[208:211], v171 offset:19456
	ds_read_b128 v[212:215], v171 offset:20480
	ds_read_b128 v[216:219], v171 offset:21504
	ds_read_b128 v[220:223], v171 offset:22528
	ds_read_b128 v[224:227], v171 offset:23552
	global_load_lds_dwordx4 v136, s[6:7]
	s_add_i32 m0, s0, 0x2000
	s_add_u32 s0, s6, 0x80000
	s_addc_u32 s1, s7, 0
	s_add_i32 s83, s72, s58
	global_load_lds_dwordx4 v140, s[6:7]
	s_mov_b32 m0, s83
	s_nop 0
	global_load_lds_dwordx4 v136, s[0:1]
	s_add_i32 m0, s83, 0x2000
	s_nop 0
	global_load_lds_dwordx4 v140, s[0:1]
	s_mov_b32 m0, s49
	s_nop 0
	global_load_lds_dwordx4 v134, s[8:9]
	s_mov_b32 m0, s59
	s_nop 0
	global_load_lds_dwordx4 v138, s[8:9]
	s_waitcnt vmcnt(8)
	s_waitcnt lgkmcnt(0)
	s_barrier
	s_setprio 1
	s_waitcnt lgkmcnt(0)
	v_mfma_f32_16x16x32_bf16 v[60:63], v[128:131], v[196:199], v[60:63]
	v_mfma_f32_16x16x32_bf16 v[56:59], v[160:163], v[196:199], v[56:59]
	v_mfma_f32_16x16x32_bf16 v[44:47], v[128:131], v[204:207], v[44:47]
	v_mfma_f32_16x16x32_bf16 v[40:43], v[160:163], v[204:207], v[40:43]
	v_mfma_f32_16x16x32_bf16 v[28:31], v[128:131], v[212:215], v[28:31]
	v_mfma_f32_16x16x32_bf16 v[24:27], v[160:163], v[212:215], v[24:27]
	v_mfma_f32_16x16x32_bf16 v[12:15], v[128:131], v[220:223], v[12:15]
	v_mfma_f32_16x16x32_bf16 v[8:11], v[160:163], v[220:223], v[8:11]
	v_mfma_f32_16x16x32_bf16 v[60:63], v[156:159], v[200:203], v[60:63]
	v_mfma_f32_16x16x32_bf16 v[56:59], v[164:167], v[200:203], v[56:59]
	v_mfma_f32_16x16x32_bf16 v[44:47], v[156:159], v[208:211], v[44:47]
	v_mfma_f32_16x16x32_bf16 v[40:43], v[164:167], v[208:211], v[40:43]
	v_mfma_f32_16x16x32_bf16 v[28:31], v[156:159], v[216:219], v[28:31]
	v_mfma_f32_16x16x32_bf16 v[24:27], v[164:167], v[216:219], v[24:27]
	v_mfma_f32_16x16x32_bf16 v[12:15], v[156:159], v[224:227], v[12:15]
	v_mfma_f32_16x16x32_bf16 v[8:11], v[164:167], v[224:227], v[8:11]
	s_setprio 0
	s_setprio 1
	v_mfma_f32_16x16x32_bf16 v[52:55], v[176:179], v[196:199], v[52:55]
	v_mfma_f32_16x16x32_bf16 v[48:51], v[188:191], v[196:199], v[48:51]
	v_mfma_f32_16x16x32_bf16 v[36:39], v[176:179], v[204:207], v[36:39]
	v_mfma_f32_16x16x32_bf16 v[32:35], v[188:191], v[204:207], v[32:35]
	v_mfma_f32_16x16x32_bf16 v[20:23], v[176:179], v[212:215], v[20:23]
	v_mfma_f32_16x16x32_bf16 v[16:19], v[188:191], v[212:215], v[16:19]
	v_mfma_f32_16x16x32_bf16 v[4:7], v[176:179], v[220:223], v[4:7]
	v_mfma_f32_16x16x32_bf16 v[0:3], v[188:191], v[220:223], v[0:3]
	v_mfma_f32_16x16x32_bf16 v[52:55], v[180:183], v[200:203], v[52:55]
	v_mfma_f32_16x16x32_bf16 v[48:51], v[192:195], v[200:203], v[48:51]
	v_mfma_f32_16x16x32_bf16 v[36:39], v[180:183], v[208:211], v[36:39]
	v_mfma_f32_16x16x32_bf16 v[32:35], v[192:195], v[208:211], v[32:35]
	v_mfma_f32_16x16x32_bf16 v[20:23], v[180:183], v[216:219], v[20:23]
	v_mfma_f32_16x16x32_bf16 v[16:19], v[192:195], v[216:219], v[16:19]
	v_mfma_f32_16x16x32_bf16 v[4:7], v[180:183], v[224:227], v[4:7]
	v_mfma_f32_16x16x32_bf16 v[0:3], v[192:195], v[224:227], v[0:3]
	s_setprio 0
	s_barrier
; #define PG8_STAGE(bufoff, gbase, voff) do { _Pragma("unroll") for (int _i = 0; _i < 2; ++_i) \
;         __builtin_amdgcn_global_load_lds((const unsigned*)((const char*)(gbase) + (voff)[_i]), (PG8_LAS unsigned*)(lds + (bufoff) + ldsw + _i * 8192), 16, 0, 0); } while (0)
; #define PG8_LDA(dst, b, h) do { _Pragma("unroll") for (int m = 0; m < 4; ++m) _Pragma("unroll") for (int k = 0; k < 2; ++k) dst[m][k] = *(const PG8_LAS bf16x8*)(lds + PG8_SA(b, h) + aoff + m * 2048 + k * 1024); } while (0)
; #define PG8_LDB(dst, b, h) do { _Pragma("unroll") for (int n = 0; n < 2; ++n) _Pragma("unroll") for (int k = 0; k < 2; ++k) dst[n][k] = *(const PG8_LAS bf16x8*)(lds + PG8_SB(b, h) + boff + n * 2048 + k * 1024); } while (0)
; #define PG8_MMA(ai, bj, At, Bt) do { __builtin_amdgcn_s_setprio(1); _Pragma("unroll") for (int m = 0; m < 4; ++m) _Pragma("unroll") for (int n = 0; n < 2; ++n) _Pragma("unroll") for (int k = 0; k < 2; ++k) \
;         acc[ai][bj][m][n] = __builtin_amdgcn_mfma_f32_16x16x32_bf16(Bt[n][k], At[m][k], acc[ai][bj][m][n], 0, 0, 0); __builtin_amdgcn_s_setprio(0); } while (0)
; #define PG8_WAIT_V(n) asm volatile("s_waitcnt vmcnt(" #n ")" ::: "memory")
; #define PG8_WAIT_L(n) asm volatile("s_waitcnt lgkmcnt(" #n ")" ::: "memory")
; #define PG8_BAR __builtin_amdgcn_s_barrier()
; #define PG8_SCHED __builtin_amdgcn_sched_barrier(0)
; template <class Epi, class Sched, bool ALIGN_EPI = false, bool SP2 = false>
; __device__ __forceinline__ void gemm_phase(PG8_LAS unsigned char* lds, const Gemm g, const Sched& S, const Epi& E) {
;     ...
;             PG8_LDB(B0, 1, 0); PG8_LDB(B1, 1, 1); PG8_SCHED; PG8_LDA(At, 1, 0); PG8_STAGE(PG8_SA(0, 1), a2 + hstep, voffA);
;             PG8_WAIT_V(8); PG8_WAIT_L(0); PG8_BAR; PG8_MMA(0, 0, At, B0); PG8_MMA(0, 1, At, B1); PG8_BAR; PG8_SCHED;
;             PG8_LDA(At, 1, 1); PG8_STAGE(PG8_SB(1, 0), b3, voffB); PG8_STAGE(PG8_SB(1, 1), b3 + hstep, voffB); PG8_STAGE(PG8_SA(1, 0), a3, voffA);
;             PG8_WAIT_V(8); PG8_WAIT_L(0); PG8_BAR; PG8_MMA(1, 0, At, B0); PG8_MMA(1, 1, At, B1); PG8_BAR; PG8_SCHED;
;     ...
;         if constexpr (ALIGN_EPI) { if (wr == 0) PG8_BAR; }
	s_add_i32 s83, 0, 0x18000
	v_add_u32_e32 v142, s83, v168
	s_add_i32 s88, 0, 0x1c000
	ds_read_b128 v[128:131], v142
	ds_read_b128 v[156:159], v142 offset:1024
	ds_read_b128 v[160:163], v142 offset:2048
	ds_read_b128 v[164:167], v142 offset:3072
	v_add_u32_e32 v142, s88, v168
	ds_read_b128 v[176:179], v142
	ds_read_b128 v[180:183], v142 offset:1024
	ds_read_b128 v[188:191], v142 offset:2048
	ds_read_b128 v[192:195], v142 offset:3072
	s_add_u32 s0, s8, 0x80000
	s_addc_u32 s1, s9, 0
	s_mov_b32 m0, s73
	ds_read_b128 v[196:199], v171 offset:32768
	ds_read_b128 v[200:203], v171 offset:33792
	ds_read_b128 v[204:207], v171 offset:34816
	ds_read_b128 v[208:211], v171 offset:35840
	ds_read_b128 v[212:215], v171 offset:36864
	ds_read_b128 v[216:219], v171 offset:37888
	ds_read_b128 v[220:223], v171 offset:38912
	ds_read_b128 v[224:227], v171 offset:39936
	global_load_lds_dwordx4 v134, s[0:1]
	s_mov_b32 m0, s74
	s_nop 0
	global_load_lds_dwordx4 v138, s[0:1]
	s_waitcnt vmcnt(8)
	s_waitcnt lgkmcnt(0)
	s_barrier
	s_setprio 1
	s_waitcnt lgkmcnt(0)
	v_mfma_f32_16x16x32_bf16 v[124:127], v[128:131], v[196:199], v[124:127]
	v_mfma_f32_16x16x32_bf16 v[120:123], v[160:163], v[196:199], v[120:123]
	v_mfma_f32_16x16x32_bf16 v[108:111], v[128:131], v[204:207], v[108:111]
	v_mfma_f32_16x16x32_bf16 v[104:107], v[160:163], v[204:207], v[104:107]
	v_mfma_f32_16x16x32_bf16 v[92:95], v[128:131], v[212:215], v[92:95]
	v_mfma_f32_16x16x32_bf16 v[88:91], v[160:163], v[212:215], v[88:91]
	v_mfma_f32_16x16x32_bf16 v[76:79], v[128:131], v[220:223], v[76:79]
	v_mfma_f32_16x16x32_bf16 v[72:75], v[160:163], v[220:223], v[72:75]
	v_mfma_f32_16x16x32_bf16 v[124:127], v[156:159], v[200:203], v[124:127]
	v_mfma_f32_16x16x32_bf16 v[120:123], v[164:167], v[200:203], v[120:123]
	v_mfma_f32_16x16x32_bf16 v[108:111], v[156:159], v[208:211], v[108:111]
	v_mfma_f32_16x16x32_bf16 v[104:107], v[164:167], v[208:211], v[104:107]
	v_mfma_f32_16x16x32_bf16 v[92:95], v[156:159], v[216:219], v[92:95]
	v_mfma_f32_16x16x32_bf16 v[88:91], v[164:167], v[216:219], v[88:91]
	v_mfma_f32_16x16x32_bf16 v[76:79], v[156:159], v[224:227], v[76:79]
	v_mfma_f32_16x16x32_bf16 v[72:75], v[164:167], v[224:227], v[72:75]
	s_setprio 0
	s_setprio 1
	v_mfma_f32_16x16x32_bf16 v[116:119], v[176:179], v[196:199], v[116:119]
	v_mfma_f32_16x16x32_bf16 v[112:115], v[188:191], v[196:199], v[112:115]
	v_mfma_f32_16x16x32_bf16 v[100:103], v[176:179], v[204:207], v[100:103]
	v_mfma_f32_16x16x32_bf16 v[96:99], v[188:191], v[204:207], v[96:99]
	v_mfma_f32_16x16x32_bf16 v[84:87], v[176:179], v[212:215], v[84:87]
	v_mfma_f32_16x16x32_bf16 v[80:83], v[188:191], v[212:215], v[80:83]
	v_mfma_f32_16x16x32_bf16 v[68:71], v[176:179], v[220:223], v[68:71]
	v_mfma_f32_16x16x32_bf16 v[64:67], v[188:191], v[220:223], v[64:67]
	v_mfma_f32_16x16x32_bf16 v[116:119], v[180:183], v[200:203], v[116:119]
	v_mfma_f32_16x16x32_bf16 v[112:115], v[192:195], v[200:203], v[112:115]
	v_mfma_f32_16x16x32_bf16 v[100:103], v[180:183], v[208:211], v[100:103]
	v_mfma_f32_16x16x32_bf16 v[96:99], v[192:195], v[208:211], v[96:99]
	v_mfma_f32_16x16x32_bf16 v[84:87], v[180:183], v[216:219], v[84:87]
	v_mfma_f32_16x16x32_bf16 v[80:83], v[192:195], v[216:219], v[80:83]
	v_mfma_f32_16x16x32_bf16 v[68:71], v[180:183], v[224:227], v[68:71]
	v_mfma_f32_16x16x32_bf16 v[64:67], v[192:195], v[224:227], v[64:67]
	s_setprio 0
	s_barrier
	s_add_i32 s0, s83, s58
	s_mov_b32 m0, s0
	ds_read_b128 v[196:199], v171 offset:49152
	ds_read_b128 v[200:203], v171 offset:50176
	ds_read_b128 v[204:207], v171 offset:51200
	ds_read_b128 v[208:211], v171 offset:52224
	ds_read_b128 v[212:215], v171 offset:53248
	ds_read_b128 v[216:219], v171 offset:54272
	ds_read_b128 v[220:223], v171 offset:55296
	ds_read_b128 v[224:227], v171 offset:56320
	global_load_lds_dwordx4 v136, s[98:99]
	s_add_i32 m0, s0, 0x2000
	s_add_u32 s0, s6, 0x80080
	s_addc_u32 s1, s7, 0
	s_add_i32 s6, s88, s58
	global_load_lds_dwordx4 v140, s[98:99]
	s_mov_b32 m0, s6
	s_nop 0
	global_load_lds_dwordx4 v136, s[0:1]
	s_add_i32 m0, s6, 0x2000
	s_nop 0
	global_load_lds_dwordx4 v140, s[0:1]
	s_mov_b32 m0, s78
	s_nop 0
	global_load_lds_dwordx4 v134, s[100:101]
	s_mov_b32 m0, s79
	s_nop 0
	global_load_lds_dwordx4 v138, s[100:101]
	s_waitcnt vmcnt(8)
	s_waitcnt lgkmcnt(0)
	s_barrier
	s_setprio 1
	s_waitcnt lgkmcnt(0)
	v_mfma_f32_16x16x32_bf16 v[60:63], v[128:131], v[196:199], v[60:63]
	v_mfma_f32_16x16x32_bf16 v[56:59], v[160:163], v[196:199], v[56:59]
	v_mfma_f32_16x16x32_bf16 v[44:47], v[128:131], v[204:207], v[44:47]
	v_mfma_f32_16x16x32_bf16 v[40:43], v[160:163], v[204:207], v[40:43]
	v_mfma_f32_16x16x32_bf16 v[28:31], v[128:131], v[212:215], v[28:31]
	v_mfma_f32_16x16x32_bf16 v[24:27], v[160:163], v[212:215], v[24:27]
	v_mfma_f32_16x16x32_bf16 v[12:15], v[128:131], v[220:223], v[12:15]
	v_mfma_f32_16x16x32_bf16 v[8:11], v[160:163], v[220:223], v[8:11]
	v_mfma_f32_16x16x32_bf16 v[60:63], v[156:159], v[200:203], v[60:63]
	v_mfma_f32_16x16x32_bf16 v[56:59], v[164:167], v[200:203], v[56:59]
	v_mfma_f32_16x16x32_bf16 v[44:47], v[156:159], v[208:211], v[44:47]
	v_mfma_f32_16x16x32_bf16 v[40:43], v[164:167], v[208:211], v[40:43]
	v_mfma_f32_16x16x32_bf16 v[28:31], v[156:159], v[216:219], v[28:31]
	v_mfma_f32_16x16x32_bf16 v[24:27], v[164:167], v[216:219], v[24:27]
	v_mfma_f32_16x16x32_bf16 v[12:15], v[156:159], v[224:227], v[12:15]
	v_mfma_f32_16x16x32_bf16 v[8:11], v[164:167], v[224:227], v[8:11]
	s_setprio 0
	s_setprio 1
	v_mfma_f32_16x16x32_bf16 v[52:55], v[176:179], v[196:199], v[52:55]
	v_mfma_f32_16x16x32_bf16 v[48:51], v[188:191], v[196:199], v[48:51]
	v_mfma_f32_16x16x32_bf16 v[36:39], v[176:179], v[204:207], v[36:39]
	v_mfma_f32_16x16x32_bf16 v[32:35], v[188:191], v[204:207], v[32:35]
	v_mfma_f32_16x16x32_bf16 v[20:23], v[176:179], v[212:215], v[20:23]
	v_mfma_f32_16x16x32_bf16 v[16:19], v[188:191], v[212:215], v[16:19]
	v_mfma_f32_16x16x32_bf16 v[4:7], v[176:179], v[220:223], v[4:7]
	v_mfma_f32_16x16x32_bf16 v[0:3], v[188:191], v[220:223], v[0:3]
	v_mfma_f32_16x16x32_bf16 v[52:55], v[180:183], v[200:203], v[52:55]
	v_mfma_f32_16x16x32_bf16 v[48:51], v[192:195], v[200:203], v[48:51]
	v_mfma_f32_16x16x32_bf16 v[36:39], v[180:183], v[208:211], v[36:39]
	v_mfma_f32_16x16x32_bf16 v[32:35], v[192:195], v[208:211], v[32:35]
	v_mfma_f32_16x16x32_bf16 v[20:23], v[180:183], v[216:219], v[20:23]
	v_mfma_f32_16x16x32_bf16 v[16:19], v[192:195], v[216:219], v[16:19]
	v_mfma_f32_16x16x32_bf16 v[4:7], v[180:183], v[224:227], v[4:7]
	v_mfma_f32_16x16x32_bf16 v[0:3], v[192:195], v[224:227], v[0:3]
	s_setprio 0
	s_barrier
	s_add_i32 vcc_hi, vcc_hi, 2
	s_add_u32 s4, s4, 0x100
	s_addc_u32 s5, s5, 0
	s_add_u32 s57, s57, 0x100
	s_addc_u32 vcc_lo, vcc_lo, 0
	s_cmp_gt_u32 vcc_hi, 29
	s_cbranch_scc0 .LBB0_244
	s_and_b64 vcc, exec, s[28:29]
	s_cbranch_vccz .LBB0_247
	s_barrier

; #define PG8_STAGE(bufoff, gbase, voff) do { _Pragma("unroll") for (int _i = 0; _i < 2; ++_i) \
;         __builtin_amdgcn_global_load_lds((const unsigned*)((const char*)(gbase) + (voff)[_i]), (PG8_LAS unsigned*)(lds + (bufoff) + ldsw + _i * 8192), 16, 0, 0); } while (0)
; #define PG8_WAIT_V(n) asm volatile("s_waitcnt vmcnt(" #n ")" ::: "memory")
; #define PG8_BAR __builtin_amdgcn_s_barrier()
; template <class Epi, class Sched, bool ALIGN_EPI = false, bool SP2 = false>
; __device__ __forceinline__ void gemm_phase(PG8_LAS unsigned char* lds, const Gemm g, const Sched& S, const Epi& E) {
;     const int tid = threadIdx.x, wid = __builtin_amdgcn_readfirstlane(tid >> 6), lane = tid & 63, wr = wid >> 2, wc = wid & 3, fr = lane & 15, fq = lane >> 4;
;     const int K = g.K, nt = K / BK;
;     unsigned voffA[2], voffB[2];
; #pragma unroll
;     for (int i = 0; i < 2; ++i) { int R, C; stage_rc(tid * 16 + i * 8192, R, C); const int Rb = Epi::PERM ? ((R & ~31) + perm32(R & 31)) : R;
;         voffA[i] = (unsigned)(R * K + C) * 2u; voffB[i] = (unsigned)(Rb * K + C) * 2u; }
;     const size_t kstep = (size_t)(BK * 2);
;     const size_t hstep = (size_t)HALF * K * 2;
;     const size_t tstep = 2 * hstep;
;     const unsigned ldsw = (unsigned)wid * 1024u;
;     const int aoff = lds_byte(wr * 64 + fr, fq * 8), boff = lds_byte(wc * 32 + fr, fq * 8);
;     ...
;     if constexpr (SP2) {
;         PG8_STAGE(PG8_SB(0, 0), cB, voffB); PG8_STAGE(PG8_SB(0, 1), cB + hstep, voffB); PG8_STAGE(PG8_SA(0, 0), cA, voffA); PG8_STAGE(PG8_SA(0, 1), cA + hstep, voffA);
;         if (wr == 1) PG8_BAR;
;         PG8_WAIT_V(2); PG8_BAR;
;         PG8_STAGE(PG8_SB(1, 0), cB + kstep, voffB); PG8_STAGE(PG8_SA(1, 0), cA + kstep, voffA); PG8_STAGE(PG8_SB(1, 1), cB + hstep + kstep, voffB);
;         PG8_WAIT_V(6); PG8_BAR;
.LBB0_627:
	s_lshl_b32 s39, s4, 6
	s_lshl_b32 s7, s4, 13
	s_lshl_b32 s4, s5, 5
	s_mov_b64 s[14:15], 0x80
	s_and_b32 s40, s4, 0x60
	s_add_i32 m0, s1, 0x18000
	v_lshl_add_u64 v[6:7], v[6:7], 0, s[14:15]
	s_lshl_b32 s17, s40, 7
	s_waitcnt vmcnt(2)
	s_barrier
	global_load_lds_dwordx4 v[6:7], off
	v_lshl_add_u64 v[4:5], v[4:5], 0, s[14:15]
	s_add_i32 m0, s1, 0x1a000
	s_add_i32 s41, s1, 0x8000
	s_add_i32 s42, s1, 0xa000
	global_load_lds_dwordx4 v[4:5], off
	v_lshl_add_u64 v[0:1], v[0:1], 0, s[14:15]
	s_mov_b32 m0, s41
	s_add_u32 s4, s30, 0x80080
	global_load_lds_dwordx4 v[0:1], off
	v_lshl_add_u64 v[0:1], v[2:3], 0, s[14:15]
	s_mov_b32 m0, s42
	s_addc_u32 s5, s31, 0
	global_load_lds_dwordx4 v[0:1], off
	s_add_i32 m0, s1, 0x1c000
	s_nop 0
	global_load_lds_dwordx4 v130, s[4:5]
	v_lshl_add_u64 v[0:1], s[4:5], 0, v[134:135]
	s_add_i32 m0, s1, 0x1e000
	v_bfe_u32 v151, v186, 4, 2
	global_load_lds_dwordx4 v[0:1], off
	v_and_b32_e32 v150, 15, v186
	v_lshlrev_b32_e32 v0, 4, v151
	v_lshlrev_b32_e32 v2, 2, v186
	v_lshlrev_b32_e32 v3, 6, v186
	s_movk_i32 s4, 0x3c0
	v_lshl_or_b32 v1, v150, 6, v0
	v_and_b32_e32 v2, 32, v2
	v_and_or_b32 v0, v3, s4, v0
	v_bitop3_b32 v152, s17, v0, v2 bitop3:0xf6
	v_lshlrev_b32_e32 v0, 9, v186
	v_bitop3_b32 v1, v1, s7, v2 bitop3:0xde
	v_and_b32_e32 v0, 0x70000, v0
	v_lshlrev_b32_e32 v2, 12, v10
	v_or3_b32 v0, v8, v0, v2
	v_add_u32_e32 v136, v0, v9
	v_lshlrev_b32_e32 v0, 5, v11
	v_and_b32_e32 v0, 0xf0000, v0
	s_waitcnt vmcnt(6)
	s_cmpk_lt_u32 s16, 0x100
	v_or3_b32 v0, v8, v0, v2
	s_cselect_b64 s[16:17], -1, 0
	v_add_u32_e32 v138, v0, v9
	s_add_i32 s45, 0, 0x10000
	s_add_i32 s46, 0, 0x14000
	v_mbcnt_lo_u32_b32 v0, -1, 0
	s_ashr_i32 s43, s3, 31
	s_ashr_i32 s44, s2, 31
	v_mov_b32_e32 v137, v131
	v_mov_b32_e32 v139, v131
	v_mov_b64_e32 v[140:141], 0x100
	v_mov_b64_e32 v[142:143], 0xff
	v_add_u32_e32 v153, s45, v152
	v_add_u32_e32 v154, s46, v152
	v_add_u32_e32 v155, 0, v1
	v_mbcnt_hi_u32_b32 v156, -1, v0
	s_barrier
	s_branch .LBB0_630

; #define PG8_STAGE(bufoff, gbase, voff) do { _Pragma("unroll") for (int _i = 0; _i < 2; ++_i) \
;         __builtin_amdgcn_global_load_lds((const unsigned*)((const char*)(gbase) + (voff)[_i]), (PG8_LAS unsigned*)(lds + (bufoff) + ldsw + _i * 8192), 16, 0, 0); } while (0)
; #define PG8_LDA(dst, b, h) do { _Pragma("unroll") for (int m = 0; m < 4; ++m) _Pragma("unroll") for (int k = 0; k < 2; ++k) dst[m][k] = *(const PG8_LAS bf16x8*)(lds + PG8_SA(b, h) + aoff + m * 2048 + k * 1024); } while (0)
; #define PG8_LDB(dst, b, h) do { _Pragma("unroll") for (int n = 0; n < 2; ++n) _Pragma("unroll") for (int k = 0; k < 2; ++k) dst[n][k] = *(const PG8_LAS bf16x8*)(lds + PG8_SB(b, h) + boff + n * 2048 + k * 1024); } while (0)
; #define PG8_MMA(ai, bj, At, Bt) do { __builtin_amdgcn_s_setprio(1); _Pragma("unroll") for (int m = 0; m < 4; ++m) _Pragma("unroll") for (int n = 0; n < 2; ++n) _Pragma("unroll") for (int k = 0; k < 2; ++k) \
;         acc[ai][bj][m][n] = __builtin_amdgcn_mfma_f32_16x16x32_bf16(Bt[n][k], At[m][k], acc[ai][bj][m][n], 0, 0, 0); __builtin_amdgcn_s_setprio(0); } while (0)
; #define PG8_WAIT_V(n) asm volatile("s_waitcnt vmcnt(" #n ")" ::: "memory")
; #define PG8_WAIT_L(n) asm volatile("s_waitcnt lgkmcnt(" #n ")" ::: "memory")
; #define PG8_BAR __builtin_amdgcn_s_barrier()
; #define PG8_SCHED __builtin_amdgcn_sched_barrier(0)
; template <class Epi, class Sched, bool ALIGN_EPI = false, bool SP2 = false>
; __device__ __forceinline__ void gemm_phase(PG8_LAS unsigned char* lds, const Gemm g, const Sched& S, const Epi& E) {
;     ...
;             if constexpr (SP2) {
;             PG8_LDB(B0, 0, 0); PG8_LDB(B1, 0, 1); PG8_SCHED; PG8_LDA(At, 0, 0); PG8_STAGE(PG8_SA(1, 1), a1 + hstep, voffA);
;             PG8_WAIT_V(8); PG8_WAIT_L(0); PG8_BAR; PG8_MMA(0, 0, At, B0); PG8_MMA(0, 1, At, B1); PG8_BAR; PG8_SCHED;
;             PG8_LDA(At, 0, 1); PG8_STAGE(PG8_SB(0, 0), b2, voffB); PG8_STAGE(PG8_SB(0, 1), b2 + hstep, voffB); PG8_STAGE(PG8_SA(0, 0), a2, voffA);
;             PG8_WAIT_V(8); PG8_WAIT_L(0); PG8_BAR; PG8_MMA(1, 0, At, B0); PG8_MMA(1, 1, At, B1); PG8_BAR; PG8_SCHED;
.LBB0_637:
	ds_read_b128 v[144:147], v153
	ds_read_b128 v[158:161], v153 offset:1024
	ds_read_b128 v[162:165], v153 offset:2048
	ds_read_b128 v[166:169], v153 offset:3072
	ds_read_b128 v[170:173], v154
	ds_read_b128 v[174:177], v154 offset:1024
	ds_read_b128 v[178:181], v154 offset:2048
	ds_read_b128 v[182:185], v154 offset:3072
	s_add_u32 s30, s28, 0xfff80080
	s_addc_u32 s31, s29, -1
	s_cmp_eq_u32 s50, 28
	s_cselect_b32 s35, s7, s31
	s_cselect_b32 s34, s21, s30
	s_cselect_b32 s31, s19, s49
	s_cselect_b32 s30, s47, s48
	s_add_i32 m0, s1, 0xc000
	ds_read_b128 v[188:191], v155
	ds_read_b128 v[192:195], v155 offset:1024
	ds_read_b128 v[196:199], v155 offset:2048
	ds_read_b128 v[200:203], v155 offset:3072
	ds_read_b128 v[204:207], v155 offset:4096
	ds_read_b128 v[208:211], v155 offset:5120
	ds_read_b128 v[212:215], v155 offset:6144
	ds_read_b128 v[216:219], v155 offset:7168
	global_load_lds_dwordx4 v136, s[28:29]
	s_add_i32 m0, s1, 0xe000
	s_nop 0
	global_load_lds_dwordx4 v138, s[28:29]
	s_waitcnt vmcnt(8)
	s_waitcnt lgkmcnt(0)
	s_barrier
	s_setprio 1
	s_waitcnt lgkmcnt(0)
	v_mfma_f32_16x16x32_bf16 v[124:127], v[144:147], v[188:191], v[124:127]
	v_mfma_f32_16x16x32_bf16 v[120:123], v[162:165], v[188:191], v[120:123]
	v_mfma_f32_16x16x32_bf16 v[108:111], v[144:147], v[196:199], v[108:111]
	v_mfma_f32_16x16x32_bf16 v[104:107], v[162:165], v[196:199], v[104:107]
	v_mfma_f32_16x16x32_bf16 v[92:95], v[144:147], v[204:207], v[92:95]
	v_mfma_f32_16x16x32_bf16 v[88:91], v[162:165], v[204:207], v[88:91]
	v_mfma_f32_16x16x32_bf16 v[76:79], v[144:147], v[212:215], v[76:79]
	v_mfma_f32_16x16x32_bf16 v[72:75], v[162:165], v[212:215], v[72:75]
	v_mfma_f32_16x16x32_bf16 v[124:127], v[158:161], v[192:195], v[124:127]
	v_mfma_f32_16x16x32_bf16 v[120:123], v[166:169], v[192:195], v[120:123]
	v_mfma_f32_16x16x32_bf16 v[108:111], v[158:161], v[200:203], v[108:111]
	v_mfma_f32_16x16x32_bf16 v[104:107], v[166:169], v[200:203], v[104:107]
	v_mfma_f32_16x16x32_bf16 v[92:95], v[158:161], v[208:211], v[92:95]
	v_mfma_f32_16x16x32_bf16 v[88:91], v[166:169], v[208:211], v[88:91]
	v_mfma_f32_16x16x32_bf16 v[76:79], v[158:161], v[216:219], v[76:79]
	v_mfma_f32_16x16x32_bf16 v[72:75], v[166:169], v[216:219], v[72:75]
	s_setprio 0
	s_setprio 1
	v_mfma_f32_16x16x32_bf16 v[116:119], v[170:173], v[188:191], v[116:119]
	v_mfma_f32_16x16x32_bf16 v[112:115], v[178:181], v[188:191], v[112:115]
	v_mfma_f32_16x16x32_bf16 v[100:103], v[170:173], v[196:199], v[100:103]
	v_mfma_f32_16x16x32_bf16 v[96:99], v[178:181], v[196:199], v[96:99]
	v_mfma_f32_16x16x32_bf16 v[84:87], v[170:173], v[204:207], v[84:87]
	v_mfma_f32_16x16x32_bf16 v[80:83], v[178:181], v[204:207], v[80:83]
	v_mfma_f32_16x16x32_bf16 v[68:71], v[170:173], v[212:215], v[68:71]
	v_mfma_f32_16x16x32_bf16 v[64:67], v[178:181], v[212:215], v[64:67]
	v_mfma_f32_16x16x32_bf16 v[116:119], v[174:177], v[192:195], v[116:119]
	v_mfma_f32_16x16x32_bf16 v[112:115], v[182:185], v[192:195], v[112:115]
	v_mfma_f32_16x16x32_bf16 v[100:103], v[174:177], v[200:203], v[100:103]
	v_mfma_f32_16x16x32_bf16 v[96:99], v[182:185], v[200:203], v[96:99]
	v_mfma_f32_16x16x32_bf16 v[84:87], v[174:177], v[208:211], v[84:87]
	v_mfma_f32_16x16x32_bf16 v[80:83], v[182:185], v[208:211], v[80:83]
	v_mfma_f32_16x16x32_bf16 v[68:71], v[174:177], v[216:219], v[68:71]
	v_mfma_f32_16x16x32_bf16 v[64:67], v[182:185], v[216:219], v[64:67]
	s_setprio 0
	s_barrier
	s_add_u32 s98, s30, s14
	s_addc_u32 s99, s31, s15
	s_add_u32 s100, s34, s14
	s_addc_u32 s101, s35, s15
	s_add_i32 s51, s45, s0
	s_mov_b32 m0, s51
	ds_read_b128 v[188:191], v155 offset:16384
	ds_read_b128 v[192:195], v155 offset:17408
	ds_read_b128 v[196:199], v155 offset:18432
	ds_read_b128 v[200:203], v155 offset:19456
	ds_read_b128 v[204:207], v155 offset:20480
	ds_read_b128 v[208:211], v155 offset:21504
	ds_read_b128 v[212:215], v155 offset:22528
	ds_read_b128 v[216:219], v155 offset:23552
	global_load_lds_dwordx4 v130, s[30:31]
	s_add_i32 m0, s51, 0x2000
	s_add_u32 s54, s30, 0x80000
	s_addc_u32 s55, s31, 0
	s_add_i32 s51, s46, s0
	global_load_lds_dwordx4 v134, s[30:31]
	s_mov_b32 m0, s51
	v_lshl_add_u64 v[224:225], s[34:35], 0, v[132:133]
	global_load_lds_dwordx4 v130, s[54:55]
	s_add_i32 m0, s51, 0x2000
	s_nop 0
	global_load_lds_dwordx4 v134, s[54:55]
	s_mov_b32 m0, s1
	s_nop 0
	global_load_lds_dwordx4 v128, s[34:35]
	s_mov_b32 m0, s27
	s_nop 0
	global_load_lds_dwordx4 v132, s[34:35]
	s_waitcnt vmcnt(8)
	s_waitcnt lgkmcnt(0)
	s_barrier
	s_setprio 1
	s_waitcnt lgkmcnt(0)
	v_mfma_f32_16x16x32_bf16 v[60:63], v[144:147], v[188:191], v[60:63]
	v_mfma_f32_16x16x32_bf16 v[56:59], v[162:165], v[188:191], v[56:59]
	v_mfma_f32_16x16x32_bf16 v[44:47], v[144:147], v[196:199], v[44:47]
	v_mfma_f32_16x16x32_bf16 v[40:43], v[162:165], v[196:199], v[40:43]
	v_mfma_f32_16x16x32_bf16 v[28:31], v[144:147], v[204:207], v[28:31]
	v_mfma_f32_16x16x32_bf16 v[24:27], v[162:165], v[204:207], v[24:27]
	v_mfma_f32_16x16x32_bf16 v[12:15], v[144:147], v[212:215], v[12:15]
	v_mfma_f32_16x16x32_bf16 v[8:11], v[162:165], v[212:215], v[8:11]
	v_mfma_f32_16x16x32_bf16 v[60:63], v[158:161], v[192:195], v[60:63]
	v_mfma_f32_16x16x32_bf16 v[56:59], v[166:169], v[192:195], v[56:59]
	v_mfma_f32_16x16x32_bf16 v[44:47], v[158:161], v[200:203], v[44:47]
	v_mfma_f32_16x16x32_bf16 v[40:43], v[166:169], v[200:203], v[40:43]
	v_mfma_f32_16x16x32_bf16 v[28:31], v[158:161], v[208:211], v[28:31]
	v_mfma_f32_16x16x32_bf16 v[24:27], v[166:169], v[208:211], v[24:27]
	v_mfma_f32_16x16x32_bf16 v[12:15], v[158:161], v[216:219], v[12:15]
	v_mfma_f32_16x16x32_bf16 v[8:11], v[166:169], v[216:219], v[8:11]
	s_setprio 0
	s_setprio 1
	v_mfma_f32_16x16x32_bf16 v[52:55], v[170:173], v[188:191], v[52:55]
	v_mfma_f32_16x16x32_bf16 v[48:51], v[178:181], v[188:191], v[48:51]
	v_mfma_f32_16x16x32_bf16 v[36:39], v[170:173], v[196:199], v[36:39]
	v_mfma_f32_16x16x32_bf16 v[32:35], v[178:181], v[196:199], v[32:35]
	v_mfma_f32_16x16x32_bf16 v[20:23], v[170:173], v[204:207], v[20:23]
	v_mfma_f32_16x16x32_bf16 v[16:19], v[178:181], v[204:207], v[16:19]
	v_mfma_f32_16x16x32_bf16 v[4:7], v[170:173], v[212:215], v[4:7]
	v_mfma_f32_16x16x32_bf16 v[0:3], v[178:181], v[212:215], v[0:3]
	v_mfma_f32_16x16x32_bf16 v[52:55], v[174:177], v[192:195], v[52:55]
	v_mfma_f32_16x16x32_bf16 v[48:51], v[182:185], v[192:195], v[48:51]
	v_mfma_f32_16x16x32_bf16 v[36:39], v[174:177], v[200:203], v[36:39]
	v_mfma_f32_16x16x32_bf16 v[32:35], v[182:185], v[200:203], v[32:35]
	v_mfma_f32_16x16x32_bf16 v[20:23], v[174:177], v[208:211], v[20:23]
	v_mfma_f32_16x16x32_bf16 v[16:19], v[182:185], v[208:211], v[16:19]
	v_mfma_f32_16x16x32_bf16 v[4:7], v[174:177], v[216:219], v[4:7]
	v_mfma_f32_16x16x32_bf16 v[0:3], v[182:185], v[216:219], v[0:3]
	s_setprio 0
	s_barrier
; #define PG8_STAGE(bufoff, gbase, voff) do { _Pragma("unroll") for (int _i = 0; _i < 2; ++_i) \
;         __builtin_amdgcn_global_load_lds((const unsigned*)((const char*)(gbase) + (voff)[_i]), (PG8_LAS unsigned*)(lds + (bufoff) + ldsw + _i * 8192), 16, 0, 0); } while (0)
; #define PG8_LDA(dst, b, h) do { _Pragma("unroll") for (int m = 0; m < 4; ++m) _Pragma("unroll") for (int k = 0; k < 2; ++k) dst[m][k] = *(const PG8_LAS bf16x8*)(lds + PG8_SA(b, h) + aoff + m * 2048 + k * 1024); } while (0)
; #define PG8_LDB(dst, b, h) do { _Pragma("unroll") for (int n = 0; n < 2; ++n) _Pragma("unroll") for (int k = 0; k < 2; ++k) dst[n][k] = *(const PG8_LAS bf16x8*)(lds + PG8_SB(b, h) + boff + n * 2048 + k * 1024); } while (0)
; #define PG8_MMA(ai, bj, At, Bt) do { __builtin_amdgcn_s_setprio(1); _Pragma("unroll") for (int m = 0; m < 4; ++m) _Pragma("unroll") for (int n = 0; n < 2; ++n) _Pragma("unroll") for (int k = 0; k < 2; ++k) \
;         acc[ai][bj][m][n] = __builtin_amdgcn_mfma_f32_16x16x32_bf16(Bt[n][k], At[m][k], acc[ai][bj][m][n], 0, 0, 0); __builtin_amdgcn_s_setprio(0); } while (0)
; #define PG8_WAIT_V(n) asm volatile("s_waitcnt vmcnt(" #n ")" ::: "memory")
; #define PG8_WAIT_L(n) asm volatile("s_waitcnt lgkmcnt(" #n ")" ::: "memory")
; #define PG8_BAR __builtin_amdgcn_s_barrier()
; #define PG8_SCHED __builtin_amdgcn_sched_barrier(0)
; template <class Epi, class Sched, bool ALIGN_EPI = false, bool SP2 = false>
; __device__ __forceinline__ void gemm_phase(PG8_LAS unsigned char* lds, const Gemm g, const Sched& S, const Epi& E) {
;     ...
;             PG8_LDB(B0, 1, 0); PG8_LDB(B1, 1, 1); PG8_SCHED; PG8_LDA(At, 1, 0); PG8_STAGE(PG8_SA(0, 1), a2 + hstep, voffA);
;             PG8_WAIT_V(8); PG8_WAIT_L(0); PG8_BAR; PG8_MMA(0, 0, At, B0); PG8_MMA(0, 1, At, B1); PG8_BAR; PG8_SCHED;
;             PG8_LDA(At, 1, 1); PG8_STAGE(PG8_SB(1, 0), b3, voffB); PG8_STAGE(PG8_SB(1, 1), b3 + hstep, voffB); PG8_STAGE(PG8_SA(1, 0), a3, voffA);
;             PG8_WAIT_V(8); PG8_WAIT_L(0); PG8_BAR; PG8_MMA(1, 0, At, B0); PG8_MMA(1, 1, At, B1); PG8_BAR; PG8_SCHED;
;     ...
;         if constexpr (ALIGN_EPI) { if (wr == 0) PG8_BAR; }
	s_add_i32 s51, 0, 0x18000
	v_add_u32_e32 v157, s51, v152
	s_add_i32 s54, 0, 0x1c000
	ds_read_b128 v[144:147], v157
	ds_read_b128 v[158:161], v157 offset:1024
	ds_read_b128 v[162:165], v157 offset:2048
	ds_read_b128 v[166:169], v157 offset:3072
	v_add_u32_e32 v157, s54, v152
	ds_read_b128 v[170:173], v157
	ds_read_b128 v[174:177], v157 offset:1024
	ds_read_b128 v[178:181], v157 offset:2048
	ds_read_b128 v[182:185], v157 offset:3072
	s_add_u32 s34, s34, 0x80000
	s_addc_u32 s35, s35, 0
	s_mov_b32 m0, s36
	ds_read_b128 v[188:191], v155 offset:32768
	ds_read_b128 v[192:195], v155 offset:33792
	ds_read_b128 v[196:199], v155 offset:34816
	ds_read_b128 v[200:203], v155 offset:35840
	ds_read_b128 v[204:207], v155 offset:36864
	ds_read_b128 v[208:211], v155 offset:37888
	ds_read_b128 v[212:215], v155 offset:38912
	ds_read_b128 v[216:219], v155 offset:39936
	global_load_lds_dwordx4 v128, s[34:35]
	s_mov_b32 m0, s37
	s_nop 0
	global_load_lds_dwordx4 v132, s[34:35]
	s_waitcnt vmcnt(8)
	s_waitcnt lgkmcnt(0)
	s_barrier
	s_setprio 1
	s_waitcnt lgkmcnt(0)
	v_mfma_f32_16x16x32_bf16 v[124:127], v[144:147], v[188:191], v[124:127]
	v_mfma_f32_16x16x32_bf16 v[120:123], v[162:165], v[188:191], v[120:123]
	v_mfma_f32_16x16x32_bf16 v[108:111], v[144:147], v[196:199], v[108:111]
	v_mfma_f32_16x16x32_bf16 v[104:107], v[162:165], v[196:199], v[104:107]
	v_mfma_f32_16x16x32_bf16 v[92:95], v[144:147], v[204:207], v[92:95]
	v_mfma_f32_16x16x32_bf16 v[88:91], v[162:165], v[204:207], v[88:91]
	v_mfma_f32_16x16x32_bf16 v[76:79], v[144:147], v[212:215], v[76:79]
	v_mfma_f32_16x16x32_bf16 v[72:75], v[162:165], v[212:215], v[72:75]
	v_mfma_f32_16x16x32_bf16 v[124:127], v[158:161], v[192:195], v[124:127]
	v_mfma_f32_16x16x32_bf16 v[120:123], v[166:169], v[192:195], v[120:123]
	v_mfma_f32_16x16x32_bf16 v[108:111], v[158:161], v[200:203], v[108:111]
	v_mfma_f32_16x16x32_bf16 v[104:107], v[166:169], v[200:203], v[104:107]
	v_mfma_f32_16x16x32_bf16 v[92:95], v[158:161], v[208:211], v[92:95]
	v_mfma_f32_16x16x32_bf16 v[88:91], v[166:169], v[208:211], v[88:91]
	v_mfma_f32_16x16x32_bf16 v[76:79], v[158:161], v[216:219], v[76:79]
	v_mfma_f32_16x16x32_bf16 v[72:75], v[166:169], v[216:219], v[72:75]
	s_setprio 0
	s_setprio 1
	v_mfma_f32_16x16x32_bf16 v[116:119], v[170:173], v[188:191], v[116:119]
	v_mfma_f32_16x16x32_bf16 v[112:115], v[178:181], v[188:191], v[112:115]
	v_mfma_f32_16x16x32_bf16 v[100:103], v[170:173], v[196:199], v[100:103]
	v_mfma_f32_16x16x32_bf16 v[96:99], v[178:181], v[196:199], v[96:99]
	v_mfma_f32_16x16x32_bf16 v[84:87], v[170:173], v[204:207], v[84:87]
	v_mfma_f32_16x16x32_bf16 v[80:83], v[178:181], v[204:207], v[80:83]
	v_mfma_f32_16x16x32_bf16 v[68:71], v[170:173], v[212:215], v[68:71]
	v_mfma_f32_16x16x32_bf16 v[64:67], v[178:181], v[212:215], v[64:67]
	v_mfma_f32_16x16x32_bf16 v[116:119], v[174:177], v[192:195], v[116:119]
	v_mfma_f32_16x16x32_bf16 v[112:115], v[182:185], v[192:195], v[112:115]
	v_mfma_f32_16x16x32_bf16 v[100:103], v[174:177], v[200:203], v[100:103]
	v_mfma_f32_16x16x32_bf16 v[96:99], v[182:185], v[200:203], v[96:99]
	v_mfma_f32_16x16x32_bf16 v[84:87], v[174:177], v[208:211], v[84:87]
	v_mfma_f32_16x16x32_bf16 v[80:83], v[182:185], v[208:211], v[80:83]
	v_mfma_f32_16x16x32_bf16 v[68:71], v[174:177], v[216:219], v[68:71]
	v_mfma_f32_16x16x32_bf16 v[64:67], v[182:185], v[216:219], v[64:67]
	s_setprio 0
	s_barrier
	s_add_i32 s34, s51, s0
	s_mov_b32 m0, s34
	ds_read_b128 v[188:191], v155 offset:49152
	ds_read_b128 v[192:195], v155 offset:50176
	ds_read_b128 v[196:199], v155 offset:51200
	ds_read_b128 v[200:203], v155 offset:52224
	ds_read_b128 v[204:207], v155 offset:53248
	ds_read_b128 v[208:211], v155 offset:54272
	ds_read_b128 v[212:215], v155 offset:55296
	ds_read_b128 v[216:219], v155 offset:56320
	global_load_lds_dwordx4 v130, s[98:99]
	s_add_i32 m0, s34, 0x2000
	s_add_u32 s30, s30, 0x80080
	s_addc_u32 s31, s31, 0
	s_add_i32 s34, s54, s0
	global_load_lds_dwordx4 v134, s[98:99]
	s_mov_b32 m0, s34
	s_nop 0
	global_load_lds_dwordx4 v130, s[30:31]
	s_add_i32 m0, s34, 0x2000
	s_nop 0
	global_load_lds_dwordx4 v134, s[30:31]
	s_mov_b32 m0, s41
	s_nop 0
	global_load_lds_dwordx4 v128, s[100:101]
	v_lshl_add_u64 v[148:149], v[224:225], 0, s[14:15]
	s_mov_b32 m0, s42
	s_nop 0
	global_load_lds_dwordx4 v132, s[100:101]
	s_waitcnt vmcnt(8)
	s_waitcnt lgkmcnt(0)
	s_barrier
	s_setprio 1
	s_waitcnt lgkmcnt(0)
	v_mfma_f32_16x16x32_bf16 v[60:63], v[144:147], v[188:191], v[60:63]
	v_mfma_f32_16x16x32_bf16 v[56:59], v[162:165], v[188:191], v[56:59]
	v_mfma_f32_16x16x32_bf16 v[44:47], v[144:147], v[196:199], v[44:47]
	v_mfma_f32_16x16x32_bf16 v[40:43], v[162:165], v[196:199], v[40:43]
	v_mfma_f32_16x16x32_bf16 v[28:31], v[144:147], v[204:207], v[28:31]
	v_mfma_f32_16x16x32_bf16 v[24:27], v[162:165], v[204:207], v[24:27]
	v_mfma_f32_16x16x32_bf16 v[12:15], v[144:147], v[212:215], v[12:15]
	v_mfma_f32_16x16x32_bf16 v[8:11], v[162:165], v[212:215], v[8:11]
	v_mfma_f32_16x16x32_bf16 v[60:63], v[158:161], v[192:195], v[60:63]
	v_mfma_f32_16x16x32_bf16 v[56:59], v[166:169], v[192:195], v[56:59]
	v_mfma_f32_16x16x32_bf16 v[44:47], v[158:161], v[200:203], v[44:47]
	v_mfma_f32_16x16x32_bf16 v[40:43], v[166:169], v[200:203], v[40:43]
	v_mfma_f32_16x16x32_bf16 v[28:31], v[158:161], v[208:211], v[28:31]
	v_mfma_f32_16x16x32_bf16 v[24:27], v[166:169], v[208:211], v[24:27]
	v_mfma_f32_16x16x32_bf16 v[12:15], v[158:161], v[216:219], v[12:15]
	v_mfma_f32_16x16x32_bf16 v[8:11], v[166:169], v[216:219], v[8:11]
	s_setprio 0
	s_setprio 1
	v_mfma_f32_16x16x32_bf16 v[52:55], v[170:173], v[188:191], v[52:55]
	v_mfma_f32_16x16x32_bf16 v[48:51], v[178:181], v[188:191], v[48:51]
	v_mfma_f32_16x16x32_bf16 v[36:39], v[170:173], v[196:199], v[36:39]
	v_mfma_f32_16x16x32_bf16 v[32:35], v[178:181], v[196:199], v[32:35]
	v_mfma_f32_16x16x32_bf16 v[20:23], v[170:173], v[204:207], v[20:23]
	v_mfma_f32_16x16x32_bf16 v[16:19], v[178:181], v[204:207], v[16:19]
	v_mfma_f32_16x16x32_bf16 v[4:7], v[170:173], v[212:215], v[4:7]
	v_mfma_f32_16x16x32_bf16 v[0:3], v[178:181], v[212:215], v[0:3]
	v_mfma_f32_16x16x32_bf16 v[52:55], v[174:177], v[192:195], v[52:55]
	v_mfma_f32_16x16x32_bf16 v[48:51], v[182:185], v[192:195], v[48:51]
	v_mfma_f32_16x16x32_bf16 v[36:39], v[174:177], v[200:203], v[36:39]
	v_mfma_f32_16x16x32_bf16 v[32:35], v[182:185], v[200:203], v[32:35]
	v_mfma_f32_16x16x32_bf16 v[20:23], v[174:177], v[208:211], v[20:23]
	v_mfma_f32_16x16x32_bf16 v[16:19], v[182:185], v[208:211], v[16:19]
	v_mfma_f32_16x16x32_bf16 v[4:7], v[174:177], v[216:219], v[4:7]
	v_mfma_f32_16x16x32_bf16 v[0:3], v[182:185], v[216:219], v[0:3]
	s_setprio 0
	s_barrier
	s_add_i32 s50, s50, 2
	s_add_u32 s28, s28, 0x100
	s_addc_u32 s29, s29, 0
	s_add_u32 s48, s48, 0x100
	s_addc_u32 s49, s49, 0
	s_cmp_gt_u32 s50, 29
	s_cbranch_scc0 .LBB0_637
	s_and_b64 vcc, exec, s[16:17]
	s_cbranch_vccz .LBB0_640
	s_barrier
; __device__ __forceinline__ u32x4 pack8(const f32x4 a, const f32x4 b) { u32x4 w; w.x = cvt_pk_bf16(a[0], a[1]); w.y = cvt_pk_bf16(a[2], a[3]); w.z = cvt_pk_bf16(b[0], b[1]); w.w = cvt_pk_bf16(b[2], b[3]); return w; }
; __device__ __forceinline__ float dot4(const f32x4 a) { return (a[0] * a[0] + a[1] * a[1]) + (a[2] * a[2] + a[3] * a[3]); }
;     __device__ __forceinline__ void operator()(const f32x4 (&acc)[2][2][4][2], const Unit& u, int wr, int wc, int fr, int fq) const {
;         asm volatile("" : "+v"(fr), "+v"(fq));
; #pragma unroll
;         for (int ai = 0; ai < 2; ++ai)
; #pragma unroll
;             for (int m = 0; m < 4; ++m) {
;                 const int row = u.pm * BM + ai * HALF + wr * 64 + m * 16 + fr; float ss = 0.f;
; #pragma unroll
;                 for (int bj = 0; bj < 2; ++bj) {
;                     const int col = u.pn * BM + bj * HALF + wc * 32 + 8 * fq; const size_t off = (size_t)row * 2048 + col;
;                     const f32x4 h0 = *(const f32x4*)(x + off) + acc[ai][bj][m][0], h1 = *(const f32x4*)(x + off + 4) + acc[ai][bj][m][1];
;                     *(u32x4*)(HR + off) = pack8(h0, h1);
;                     ss += dot4(h0) + dot4(h1);
;                 }
;                 ss += __shfl_xor(ss, 16); ss += __shfl_xor(ss, 32);
;                 if (fq == 0) atomicAdd(ssq + row, ss);
;             }
.LBB0_640:
	v_mov_b32_e32 v157, v151
	v_mov_b32_e32 v144, v150
	s_lshl_b32 s7, s26, 8
	s_add_i32 s7, s7, s39
	s_lshl_b32 s6, s6, 8
	v_add_u32_e32 v144, s7, v144
	s_or_b32 s6, s6, s40
	v_ashrrev_i32_e32 v145, 31, v144
	v_lshl_add_u32 v146, v157, 3, s6
	v_cmp_eq_u32_e32 vcc, 0, v157
	v_lshlrev_b32_e32 v183, 2, v146
	v_lshl_add_u32 v147, v144, 13, v183
	v_lshlrev_b32_e32 v183, 1, v146
	v_lshl_add_u32 v148, v144, 12, v183
	v_lshlrev_b32_e32 v149, 2, v144
	v_add_u32_e32 v184, 0x0, v147
	global_load_dwordx4 v[158:161], v184, s[52:53] offset:0
	global_load_dwordx4 v[162:165], v184, s[52:53] offset:16
	v_add_u32_e32 v184, 0x0, v147
	global_load_dwordx4 v[166:169], v184, s[52:53] offset:512
	global_load_dwordx4 v[170:173], v184, s[52:53] offset:528
	v_add_u32_e32 v184, 0x20000, v147
	global_load_dwordx4 v[174:177], v184, s[52:53] offset:0
	global_load_dwordx4 v[178:181], v184, s[52:53] offset:16
	v_add_u32_e32 v184, 0x20000, v147
	global_load_dwordx4 v[188:191], v184, s[52:53] offset:512
	global_load_dwordx4 v[192:195], v184, s[52:53] offset:528
	v_add_u32_e32 v184, 0x40000, v147
	global_load_dwordx4 v[196:199], v184, s[52:53] offset:0
	global_load_dwordx4 v[200:203], v184, s[52:53] offset:16
	v_add_u32_e32 v184, 0x40000, v147
	global_load_dwordx4 v[204:207], v184, s[52:53] offset:512
	global_load_dwordx4 v[208:211], v184, s[52:53] offset:528
	v_add_u32_e32 v184, 0x60000, v147
	global_load_dwordx4 v[212:215], v184, s[52:53] offset:0
	global_load_dwordx4 v[216:219], v184, s[52:53] offset:16
	v_xor_b32_e32 v144, 16, v156
	v_lshlrev_b32_e32 v144, 2, v144
	v_xor_b32_e32 v145, 32, v156
	v_lshlrev_b32_e32 v145, 2, v145
	s_waitcnt vmcnt(12)
	v_pk_add_f32 v[124:125], v[124:125], v[158:159]
	v_pk_add_f32 v[126:127], v[126:127], v[160:161]
	v_pk_add_f32 v[120:121], v[120:121], v[162:163]
	v_pk_add_f32 v[122:123], v[122:123], v[164:165]
	v_mul_f32_e32 v162, v125, v125
	v_mul_f32_e32 v163, v127, v127
	v_mul_f32_e32 v164, v121, v121
	v_mul_f32_e32 v165, v123, v123
	v_cvt_pk_bf16_f32 v158, v124, v125
	v_cvt_pk_bf16_f32 v159, v126, v127
	v_cvt_pk_bf16_f32 v160, v120, v121
	v_cvt_pk_bf16_f32 v161, v122, v123
	v_fmac_f32_e32 v162, v124, v124
	v_fmac_f32_e32 v163, v126, v126
	v_fmac_f32_e32 v164, v120, v120
	v_fmac_f32_e32 v165, v122, v122
	v_add_u32_e32 v185, 0x0, v148
	global_store_dwordx4 v185, v[158:161], s[8:9] offset:0
	v_add_f32_e32 v162, v162, v163
	v_add_f32_e32 v164, v164, v165
	v_add_f32_e32 v182, v162, v164
	v_add_u32_e32 v184, 0x60000, v147
	global_load_dwordx4 v[158:161], v184, s[52:53] offset:512
	global_load_dwordx4 v[162:165], v184, s[52:53] offset:528
	s_waitcnt vmcnt(13)
	v_pk_add_f32 v[116:117], v[116:117], v[166:167]
	v_pk_add_f32 v[118:119], v[118:119], v[168:169]
	v_pk_add_f32 v[112:113], v[112:113], v[170:171]
	v_pk_add_f32 v[114:115], v[114:115], v[172:173]
	v_mul_f32_e32 v170, v117, v117
	v_mul_f32_e32 v171, v119, v119
	v_mul_f32_e32 v172, v113, v113
	v_mul_f32_e32 v173, v115, v115
	v_cvt_pk_bf16_f32 v166, v116, v117
	v_cvt_pk_bf16_f32 v167, v118, v119
	v_cvt_pk_bf16_f32 v168, v112, v113
	v_cvt_pk_bf16_f32 v169, v114, v115
	v_fmac_f32_e32 v170, v116, v116
	v_fmac_f32_e32 v171, v118, v118
	v_fmac_f32_e32 v172, v112, v112
	v_fmac_f32_e32 v173, v114, v114
	v_add_u32_e32 v185, 0x0, v148
	global_store_dwordx4 v185, v[166:169], s[8:9] offset:256
	v_add_f32_e32 v170, v170, v171
	v_add_f32_e32 v172, v172, v173
	v_add_f32_e32 v170, v170, v172
	v_add_f32_e32 v182, v182, v170
	ds_bpermute_b32 v183, v144, v182
	v_add_u32_e32 v146, 0x0, v149
	s_waitcnt lgkmcnt(0)
	v_add_f32_e32 v182, v182, v183
	ds_bpermute_b32 v183, v145, v182
	s_waitcnt lgkmcnt(0)
	v_add_f32_e32 v182, v182, v183
	s_and_saveexec_b64 s[6:7], vcc
	global_atomic_add_f32 v146, v182, s[94:95]
	s_or_b64 exec, exec, s[6:7]
	v_add_u32_e32 v184, 0x100000, v147
	global_load_dwordx4 v[166:169], v184, s[52:53] offset:0
	global_load_dwordx4 v[170:173], v184, s[52:53] offset:16
	s_waitcnt vmcnt(15)
	v_pk_add_f32 v[108:109], v[108:109], v[174:175]
	v_pk_add_f32 v[110:111], v[110:111], v[176:177]
	v_pk_add_f32 v[104:105], v[104:105], v[178:179]
	v_pk_add_f32 v[106:107], v[106:107], v[180:181]
	v_mul_f32_e32 v178, v109, v109
	v_mul_f32_e32 v179, v111, v111
	v_mul_f32_e32 v180, v105, v105
	v_mul_f32_e32 v181, v107, v107
	v_cvt_pk_bf16_f32 v174, v108, v109
	v_cvt_pk_bf16_f32 v175, v110, v111
	v_cvt_pk_bf16_f32 v176, v104, v105
	v_cvt_pk_bf16_f32 v177, v106, v107
	v_fmac_f32_e32 v178, v108, v108
	v_fmac_f32_e32 v179, v110, v110
	v_fmac_f32_e32 v180, v104, v104
	v_fmac_f32_e32 v181, v106, v106
	v_add_u32_e32 v185, 0x10000, v148
	global_store_dwordx4 v185, v[174:177], s[8:9] offset:0
	v_add_f32_e32 v178, v178, v179
	v_add_f32_e32 v180, v180, v181
	v_add_f32_e32 v182, v178, v180
	v_add_u32_e32 v184, 0x100000, v147
	global_load_dwordx4 v[174:177], v184, s[52:53] offset:512
	global_load_dwordx4 v[178:181], v184, s[52:53] offset:528
	s_waitcnt vmcnt(16)
	v_pk_add_f32 v[100:101], v[100:101], v[188:189]
	v_pk_add_f32 v[102:103], v[102:103], v[190:191]
	v_pk_add_f32 v[96:97], v[96:97], v[192:193]
	v_pk_add_f32 v[98:99], v[98:99], v[194:195]
	v_mul_f32_e32 v192, v101, v101
	v_mul_f32_e32 v193, v103, v103
	v_mul_f32_e32 v194, v97, v97
	v_mul_f32_e32 v195, v99, v99
	v_cvt_pk_bf16_f32 v188, v100, v101
	v_cvt_pk_bf16_f32 v189, v102, v103
	v_cvt_pk_bf16_f32 v190, v96, v97
	v_cvt_pk_bf16_f32 v191, v98, v99
	v_fmac_f32_e32 v192, v100, v100
	v_fmac_f32_e32 v193, v102, v102
	v_fmac_f32_e32 v194, v96, v96
	v_fmac_f32_e32 v195, v98, v98
	v_add_u32_e32 v185, 0x10000, v148
	global_store_dwordx4 v185, v[188:191], s[8:9] offset:256
	v_add_f32_e32 v192, v192, v193
	v_add_f32_e32 v194, v194, v195
	v_add_f32_e32 v192, v192, v194
	v_add_f32_e32 v182, v182, v192
	ds_bpermute_b32 v183, v144, v182
	v_add_u32_e32 v146, 0x40, v149
	s_waitcnt lgkmcnt(0)
; __device__ __forceinline__ u32x4 pack8(const f32x4 a, const f32x4 b) { u32x4 w; w.x = cvt_pk_bf16(a[0], a[1]); w.y = cvt_pk_bf16(a[2], a[3]); w.z = cvt_pk_bf16(b[0], b[1]); w.w = cvt_pk_bf16(b[2], b[3]); return w; }
; __device__ __forceinline__ float dot4(const f32x4 a) { return (a[0] * a[0] + a[1] * a[1]) + (a[2] * a[2] + a[3] * a[3]); }
;     __device__ __forceinline__ void operator()(const f32x4 (&acc)[2][2][4][2], const Unit& u, int wr, int wc, int fr, int fq) const {
;     ...
; #pragma unroll
;         for (int ai = 0; ai < 2; ++ai)
; #pragma unroll
;             for (int m = 0; m < 4; ++m) {
;                 const int row = u.pm * BM + ai * HALF + wr * 64 + m * 16 + fr; float ss = 0.f;
; #pragma unroll
;                 for (int bj = 0; bj < 2; ++bj) {
;                     const int col = u.pn * BM + bj * HALF + wc * 32 + 8 * fq; const size_t off = (size_t)row * 2048 + col;
;                     const f32x4 h0 = *(const f32x4*)(x + off) + acc[ai][bj][m][0], h1 = *(const f32x4*)(x + off + 4) + acc[ai][bj][m][1];
;                     *(u32x4*)(HR + off) = pack8(h0, h1);
;                     ss += dot4(h0) + dot4(h1);
;                 }
;                 ss += __shfl_xor(ss, 16); ss += __shfl_xor(ss, 32);
;                 if (fq == 0) atomicAdd(ssq + row, ss);
;             }
	v_add_f32_e32 v182, v182, v183
	ds_bpermute_b32 v183, v145, v182
	s_waitcnt lgkmcnt(0)
	v_add_f32_e32 v182, v182, v183
	s_and_saveexec_b64 s[6:7], vcc
	global_atomic_add_f32 v146, v182, s[94:95]
	s_or_b64 exec, exec, s[6:7]
	v_add_u32_e32 v184, 0x120000, v147
	global_load_dwordx4 v[188:191], v184, s[52:53] offset:0
	global_load_dwordx4 v[192:195], v184, s[52:53] offset:16
	s_waitcnt vmcnt(18)
	v_pk_add_f32 v[92:93], v[92:93], v[196:197]
	v_pk_add_f32 v[94:95], v[94:95], v[198:199]
	v_pk_add_f32 v[88:89], v[88:89], v[200:201]
	v_pk_add_f32 v[90:91], v[90:91], v[202:203]
	v_mul_f32_e32 v200, v93, v93
	v_mul_f32_e32 v201, v95, v95
	v_mul_f32_e32 v202, v89, v89
	v_mul_f32_e32 v203, v91, v91
	v_cvt_pk_bf16_f32 v196, v92, v93
	v_cvt_pk_bf16_f32 v197, v94, v95
	v_cvt_pk_bf16_f32 v198, v88, v89
	v_cvt_pk_bf16_f32 v199, v90, v91
	v_fmac_f32_e32 v200, v92, v92
	v_fmac_f32_e32 v201, v94, v94
	v_fmac_f32_e32 v202, v88, v88
	v_fmac_f32_e32 v203, v90, v90
	v_add_u32_e32 v185, 0x20000, v148
	global_store_dwordx4 v185, v[196:199], s[8:9] offset:0
	v_add_f32_e32 v200, v200, v201
	v_add_f32_e32 v202, v202, v203
	v_add_f32_e32 v182, v200, v202
	v_add_u32_e32 v184, 0x120000, v147
	global_load_dwordx4 v[196:199], v184, s[52:53] offset:512
	global_load_dwordx4 v[200:203], v184, s[52:53] offset:528
	s_waitcnt vmcnt(19)
	v_pk_add_f32 v[84:85], v[84:85], v[204:205]
	v_pk_add_f32 v[86:87], v[86:87], v[206:207]
	v_pk_add_f32 v[80:81], v[80:81], v[208:209]
	v_pk_add_f32 v[82:83], v[82:83], v[210:211]
	v_mul_f32_e32 v208, v85, v85
	v_mul_f32_e32 v209, v87, v87
	v_mul_f32_e32 v210, v81, v81
	v_mul_f32_e32 v211, v83, v83
	v_cvt_pk_bf16_f32 v204, v84, v85
	v_cvt_pk_bf16_f32 v205, v86, v87
	v_cvt_pk_bf16_f32 v206, v80, v81
	v_cvt_pk_bf16_f32 v207, v82, v83
	v_fmac_f32_e32 v208, v84, v84
	v_fmac_f32_e32 v209, v86, v86
	v_fmac_f32_e32 v210, v80, v80
	v_fmac_f32_e32 v211, v82, v82
	v_add_u32_e32 v185, 0x20000, v148
	global_store_dwordx4 v185, v[204:207], s[8:9] offset:256
	v_add_f32_e32 v208, v208, v209
	v_add_f32_e32 v210, v210, v211
	v_add_f32_e32 v208, v208, v210
	v_add_f32_e32 v182, v182, v208
	ds_bpermute_b32 v183, v144, v182
	v_add_u32_e32 v146, 0x80, v149
	s_waitcnt lgkmcnt(0)
	v_add_f32_e32 v182, v182, v183
	ds_bpermute_b32 v183, v145, v182
	s_waitcnt lgkmcnt(0)
	v_add_f32_e32 v182, v182, v183
	s_and_saveexec_b64 s[6:7], vcc
	global_atomic_add_f32 v146, v182, s[94:95]
	s_or_b64 exec, exec, s[6:7]
	v_add_u32_e32 v184, 0x140000, v147
	global_load_dwordx4 v[204:207], v184, s[52:53] offset:0
	global_load_dwordx4 v[208:211], v184, s[52:53] offset:16
	s_waitcnt vmcnt(21)
	v_pk_add_f32 v[76:77], v[76:77], v[212:213]
	v_pk_add_f32 v[78:79], v[78:79], v[214:215]
	v_pk_add_f32 v[72:73], v[72:73], v[216:217]
	v_pk_add_f32 v[74:75], v[74:75], v[218:219]
	v_mul_f32_e32 v216, v77, v77
	v_mul_f32_e32 v217, v79, v79
	v_mul_f32_e32 v218, v73, v73
	v_mul_f32_e32 v219, v75, v75
	v_cvt_pk_bf16_f32 v212, v76, v77
	v_cvt_pk_bf16_f32 v213, v78, v79
	v_cvt_pk_bf16_f32 v214, v72, v73
	v_cvt_pk_bf16_f32 v215, v74, v75
	v_fmac_f32_e32 v216, v76, v76
	v_fmac_f32_e32 v217, v78, v78
	v_fmac_f32_e32 v218, v72, v72
	v_fmac_f32_e32 v219, v74, v74
	v_add_u32_e32 v185, 0x30000, v148
	global_store_dwordx4 v185, v[212:215], s[8:9] offset:0
	v_add_f32_e32 v216, v216, v217
	v_add_f32_e32 v218, v218, v219
	v_add_f32_e32 v182, v216, v218
	v_add_u32_e32 v184, 0x140000, v147
	global_load_dwordx4 v[212:215], v184, s[52:53] offset:512
	global_load_dwordx4 v[216:219], v184, s[52:53] offset:528
	s_waitcnt vmcnt(21)
	v_pk_add_f32 v[68:69], v[68:69], v[158:159]
	v_pk_add_f32 v[70:71], v[70:71], v[160:161]
	v_pk_add_f32 v[64:65], v[64:65], v[162:163]
	v_pk_add_f32 v[66:67], v[66:67], v[164:165]
	v_mul_f32_e32 v162, v69, v69
	v_mul_f32_e32 v163, v71, v71
	v_mul_f32_e32 v164, v65, v65
	v_mul_f32_e32 v165, v67, v67
	v_cvt_pk_bf16_f32 v158, v68, v69
	v_cvt_pk_bf16_f32 v159, v70, v71
	v_cvt_pk_bf16_f32 v160, v64, v65
	v_cvt_pk_bf16_f32 v161, v66, v67
	v_fmac_f32_e32 v162, v68, v68
	v_fmac_f32_e32 v163, v70, v70
	v_fmac_f32_e32 v164, v64, v64
	v_fmac_f32_e32 v165, v66, v66
	v_add_u32_e32 v185, 0x30000, v148
	global_store_dwordx4 v185, v[158:161], s[8:9] offset:256
	v_add_f32_e32 v162, v162, v163
	v_add_f32_e32 v164, v164, v165
	v_add_f32_e32 v162, v162, v164
	v_add_f32_e32 v182, v182, v162
	ds_bpermute_b32 v183, v144, v182
	v_add_u32_e32 v146, 0xc0, v149
	s_waitcnt lgkmcnt(0)
	v_add_f32_e32 v182, v182, v183
	ds_bpermute_b32 v183, v145, v182
	s_waitcnt lgkmcnt(0)
	v_add_f32_e32 v182, v182, v183
	s_and_saveexec_b64 s[6:7], vcc
	global_atomic_add_f32 v146, v182, s[94:95]
	s_or_b64 exec, exec, s[6:7]
	v_add_u32_e32 v184, 0x160000, v147
	global_load_dwordx4 v[158:161], v184, s[52:53] offset:0
	global_load_dwordx4 v[162:165], v184, s[52:53] offset:16
	s_waitcnt vmcnt(21)
	v_pk_add_f32 v[60:61], v[60:61], v[166:167]
	v_pk_add_f32 v[62:63], v[62:63], v[168:169]
	v_pk_add_f32 v[56:57], v[56:57], v[170:171]
	v_pk_add_f32 v[58:59], v[58:59], v[172:173]
	v_mul_f32_e32 v170, v61, v61
	v_mul_f32_e32 v171, v63, v63
	v_mul_f32_e32 v172, v57, v57
	v_mul_f32_e32 v173, v59, v59
	v_cvt_pk_bf16_f32 v166, v60, v61
	v_cvt_pk_bf16_f32 v167, v62, v63
	v_cvt_pk_bf16_f32 v168, v56, v57
	v_cvt_pk_bf16_f32 v169, v58, v59
	v_fmac_f32_e32 v170, v60, v60
	v_fmac_f32_e32 v171, v62, v62
	v_fmac_f32_e32 v172, v56, v56
	v_fmac_f32_e32 v173, v58, v58
	v_add_u32_e32 v185, 0x80000, v148
	global_store_dwordx4 v185, v[166:169], s[8:9] offset:0
	v_add_f32_e32 v170, v170, v171
	v_add_f32_e32 v172, v172, v173
	v_add_f32_e32 v182, v170, v172
	v_add_u32_e32 v184, 0x160000, v147
	global_load_dwordx4 v[166:169], v184, s[52:53] offset:512
	global_load_dwordx4 v[170:173], v184, s[52:53] offset:528
	s_waitcnt vmcnt(21)
; __device__ __forceinline__ u32x4 pack8(const f32x4 a, const f32x4 b) { u32x4 w; w.x = cvt_pk_bf16(a[0], a[1]); w.y = cvt_pk_bf16(a[2], a[3]); w.z = cvt_pk_bf16(b[0], b[1]); w.w = cvt_pk_bf16(b[2], b[3]); return w; }
; __device__ __forceinline__ float dot4(const f32x4 a) { return (a[0] * a[0] + a[1] * a[1]) + (a[2] * a[2] + a[3] * a[3]); }
;     __device__ __forceinline__ void operator()(const f32x4 (&acc)[2][2][4][2], const Unit& u, int wr, int wc, int fr, int fq) const {
;     ...
; #pragma unroll
;         for (int ai = 0; ai < 2; ++ai)
; #pragma unroll
;             for (int m = 0; m < 4; ++m) {
;                 const int row = u.pm * BM + ai * HALF + wr * 64 + m * 16 + fr; float ss = 0.f;
; #pragma unroll
;                 for (int bj = 0; bj < 2; ++bj) {
;                     const int col = u.pn * BM + bj * HALF + wc * 32 + 8 * fq; const size_t off = (size_t)row * 2048 + col;
;                     const f32x4 h0 = *(const f32x4*)(x + off) + acc[ai][bj][m][0], h1 = *(const f32x4*)(x + off + 4) + acc[ai][bj][m][1];
;                     *(u32x4*)(HR + off) = pack8(h0, h1);
;                     ss += dot4(h0) + dot4(h1);
;                 }
;                 ss += __shfl_xor(ss, 16); ss += __shfl_xor(ss, 32);
;                 if (fq == 0) atomicAdd(ssq + row, ss);
;             }
	v_pk_add_f32 v[52:53], v[52:53], v[174:175]
	v_pk_add_f32 v[54:55], v[54:55], v[176:177]
	v_pk_add_f32 v[48:49], v[48:49], v[178:179]
	v_pk_add_f32 v[50:51], v[50:51], v[180:181]
	v_mul_f32_e32 v178, v53, v53
	v_mul_f32_e32 v179, v55, v55
	v_mul_f32_e32 v180, v49, v49
	v_mul_f32_e32 v181, v51, v51
	v_cvt_pk_bf16_f32 v174, v52, v53
	v_cvt_pk_bf16_f32 v175, v54, v55
	v_cvt_pk_bf16_f32 v176, v48, v49
	v_cvt_pk_bf16_f32 v177, v50, v51
	v_fmac_f32_e32 v178, v52, v52
	v_fmac_f32_e32 v179, v54, v54
	v_fmac_f32_e32 v180, v48, v48
	v_fmac_f32_e32 v181, v50, v50
	v_add_u32_e32 v185, 0x80000, v148
	global_store_dwordx4 v185, v[174:177], s[8:9] offset:256
	v_add_f32_e32 v178, v178, v179
	v_add_f32_e32 v180, v180, v181
	v_add_f32_e32 v178, v178, v180
	v_add_f32_e32 v182, v182, v178
	ds_bpermute_b32 v183, v144, v182
	v_add_u32_e32 v146, 0x200, v149
	s_waitcnt lgkmcnt(0)
	v_add_f32_e32 v182, v182, v183
	ds_bpermute_b32 v183, v145, v182
	s_waitcnt lgkmcnt(0)
	v_add_f32_e32 v182, v182, v183
	s_and_saveexec_b64 s[6:7], vcc
	global_atomic_add_f32 v146, v182, s[94:95]
	s_or_b64 exec, exec, s[6:7]
	s_waitcnt vmcnt(19)
	v_pk_add_f32 v[44:45], v[44:45], v[188:189]
	v_pk_add_f32 v[46:47], v[46:47], v[190:191]
	v_pk_add_f32 v[40:41], v[40:41], v[192:193]
	v_pk_add_f32 v[42:43], v[42:43], v[194:195]
	v_mul_f32_e32 v192, v45, v45
	v_mul_f32_e32 v193, v47, v47
	v_mul_f32_e32 v194, v41, v41
	v_mul_f32_e32 v195, v43, v43
	v_cvt_pk_bf16_f32 v188, v44, v45
	v_cvt_pk_bf16_f32 v189, v46, v47
	v_cvt_pk_bf16_f32 v190, v40, v41
	v_cvt_pk_bf16_f32 v191, v42, v43
	v_fmac_f32_e32 v192, v44, v44
	v_fmac_f32_e32 v193, v46, v46
	v_fmac_f32_e32 v194, v40, v40
	v_fmac_f32_e32 v195, v42, v42
	v_add_u32_e32 v185, 0x90000, v148
	global_store_dwordx4 v185, v[188:191], s[8:9] offset:0
	v_add_f32_e32 v192, v192, v193
	v_add_f32_e32 v194, v194, v195
	v_add_f32_e32 v182, v192, v194
	s_waitcnt vmcnt(17)
	v_pk_add_f32 v[36:37], v[36:37], v[196:197]
	v_pk_add_f32 v[38:39], v[38:39], v[198:199]
	v_pk_add_f32 v[32:33], v[32:33], v[200:201]
	v_pk_add_f32 v[34:35], v[34:35], v[202:203]
	v_mul_f32_e32 v200, v37, v37
	v_mul_f32_e32 v201, v39, v39
	v_mul_f32_e32 v202, v33, v33
	v_mul_f32_e32 v203, v35, v35
	v_cvt_pk_bf16_f32 v196, v36, v37
	v_cvt_pk_bf16_f32 v197, v38, v39
	v_cvt_pk_bf16_f32 v198, v32, v33
	v_cvt_pk_bf16_f32 v199, v34, v35
	v_fmac_f32_e32 v200, v36, v36
	v_fmac_f32_e32 v201, v38, v38
	v_fmac_f32_e32 v202, v32, v32
	v_fmac_f32_e32 v203, v34, v34
	v_add_u32_e32 v185, 0x90000, v148
	global_store_dwordx4 v185, v[196:199], s[8:9] offset:256
	v_add_f32_e32 v200, v200, v201
	v_add_f32_e32 v202, v202, v203
	v_add_f32_e32 v200, v200, v202
	v_add_f32_e32 v182, v182, v200
	ds_bpermute_b32 v183, v144, v182
	v_add_u32_e32 v146, 0x240, v149
	s_waitcnt lgkmcnt(0)
	v_add_f32_e32 v182, v182, v183
	ds_bpermute_b32 v183, v145, v182
	s_waitcnt lgkmcnt(0)
	v_add_f32_e32 v182, v182, v183
	s_and_saveexec_b64 s[6:7], vcc
	global_atomic_add_f32 v146, v182, s[94:95]
	s_or_b64 exec, exec, s[6:7]
	s_waitcnt vmcnt(15)
	v_pk_add_f32 v[28:29], v[28:29], v[204:205]
	v_pk_add_f32 v[30:31], v[30:31], v[206:207]
	v_pk_add_f32 v[24:25], v[24:25], v[208:209]
	v_pk_add_f32 v[26:27], v[26:27], v[210:211]
	v_mul_f32_e32 v208, v29, v29
	v_mul_f32_e32 v209, v31, v31
	v_mul_f32_e32 v210, v25, v25
	v_mul_f32_e32 v211, v27, v27
	v_cvt_pk_bf16_f32 v204, v28, v29
	v_cvt_pk_bf16_f32 v205, v30, v31
	v_cvt_pk_bf16_f32 v206, v24, v25
	v_cvt_pk_bf16_f32 v207, v26, v27
	v_fmac_f32_e32 v208, v28, v28
	v_fmac_f32_e32 v209, v30, v30
	v_fmac_f32_e32 v210, v24, v24
	v_fmac_f32_e32 v211, v26, v26
	v_add_u32_e32 v185, 0xa0000, v148
	global_store_dwordx4 v185, v[204:207], s[8:9] offset:0
	v_add_f32_e32 v208, v208, v209
	v_add_f32_e32 v210, v210, v211
	v_add_f32_e32 v182, v208, v210
	s_waitcnt vmcnt(13)
	v_pk_add_f32 v[20:21], v[20:21], v[212:213]
	v_pk_add_f32 v[22:23], v[22:23], v[214:215]
	v_pk_add_f32 v[16:17], v[16:17], v[216:217]
	v_pk_add_f32 v[18:19], v[18:19], v[218:219]
	v_mul_f32_e32 v216, v21, v21
	v_mul_f32_e32 v217, v23, v23
	v_mul_f32_e32 v218, v17, v17
	v_mul_f32_e32 v219, v19, v19
	v_cvt_pk_bf16_f32 v212, v20, v21
	v_cvt_pk_bf16_f32 v213, v22, v23
	v_cvt_pk_bf16_f32 v214, v16, v17
	v_cvt_pk_bf16_f32 v215, v18, v19
	v_fmac_f32_e32 v216, v20, v20
	v_fmac_f32_e32 v217, v22, v22
	v_fmac_f32_e32 v218, v16, v16
	v_fmac_f32_e32 v219, v18, v18
	v_add_u32_e32 v185, 0xa0000, v148
	global_store_dwordx4 v185, v[212:215], s[8:9] offset:256
	v_add_f32_e32 v216, v216, v217
	v_add_f32_e32 v218, v218, v219
	v_add_f32_e32 v216, v216, v218
	v_add_f32_e32 v182, v182, v216
	ds_bpermute_b32 v183, v144, v182
	v_add_u32_e32 v146, 0x280, v149
	s_waitcnt lgkmcnt(0)
	v_add_f32_e32 v182, v182, v183
	ds_bpermute_b32 v183, v145, v182
	s_waitcnt lgkmcnt(0)
	v_add_f32_e32 v182, v182, v183
	s_and_saveexec_b64 s[6:7], vcc
	global_atomic_add_f32 v146, v182, s[94:95]
	s_or_b64 exec, exec, s[6:7]
	s_waitcnt vmcnt(11)
	v_pk_add_f32 v[12:13], v[12:13], v[158:159]
	v_pk_add_f32 v[14:15], v[14:15], v[160:161]
	v_pk_add_f32 v[8:9], v[8:9], v[162:163]
	v_pk_add_f32 v[10:11], v[10:11], v[164:165]
	v_mul_f32_e32 v162, v13, v13
	v_mul_f32_e32 v163, v15, v15
	v_mul_f32_e32 v164, v9, v9
	v_mul_f32_e32 v165, v11, v11
	v_cvt_pk_bf16_f32 v158, v12, v13
	v_cvt_pk_bf16_f32 v159, v14, v15
	v_cvt_pk_bf16_f32 v160, v8, v9
	v_cvt_pk_bf16_f32 v161, v10, v11
	v_fmac_f32_e32 v162, v12, v12
	v_fmac_f32_e32 v163, v14, v14
	v_fmac_f32_e32 v164, v8, v8
	v_fmac_f32_e32 v165, v10, v10
	v_add_u32_e32 v185, 0xb0000, v148
	global_store_dwordx4 v185, v[158:161], s[8:9] offset:0
	v_add_f32_e32 v162, v162, v163
	v_add_f32_e32 v164, v164, v165
	v_add_f32_e32 v182, v162, v164
	s_waitcnt vmcnt(9)
	v_pk_add_f32 v[4:5], v[4:5], v[166:167]
	v_pk_add_f32 v[6:7], v[6:7], v[168:169]
	v_pk_add_f32 v[0:1], v[0:1], v[170:171]
	v_pk_add_f32 v[2:3], v[2:3], v[172:173]
	v_mul_f32_e32 v170, v5, v5
	v_mul_f32_e32 v171, v7, v7
	v_mul_f32_e32 v172, v1, v1
	v_mul_f32_e32 v173, v3, v3
	v_cvt_pk_bf16_f32 v166, v4, v5
	v_cvt_pk_bf16_f32 v167, v6, v7
	v_cvt_pk_bf16_f32 v168, v0, v1
	v_cvt_pk_bf16_f32 v169, v2, v3
	v_fmac_f32_e32 v170, v4, v4
	v_fmac_f32_e32 v171, v6, v6
	v_fmac_f32_e32 v172, v0, v0
	v_fmac_f32_e32 v173, v2, v2
	v_add_u32_e32 v185, 0xb0000, v148
	global_store_dwordx4 v185, v[166:169], s[8:9] offset:256
	v_add_f32_e32 v170, v170, v171
	v_add_f32_e32 v172, v172, v173
	v_add_f32_e32 v170, v170, v172
	v_add_f32_e32 v182, v182, v170
	ds_bpermute_b32 v183, v144, v182
	v_add_u32_e32 v146, 0x2c0, v149
	s_waitcnt lgkmcnt(0)
	v_add_f32_e32 v182, v182, v183
	ds_bpermute_b32 v183, v145, v182
	s_waitcnt lgkmcnt(0)
	v_add_f32_e32 v182, v182, v183
	s_and_saveexec_b64 s[6:7], vcc
	global_atomic_add_f32 v146, v182, s[94:95]
	s_or_b64 exec, exec, s[6:7]

; #define PG8_STAGE(bufoff, gbase, voff) do { _Pragma("unroll") for (int _i = 0; _i < 2; ++_i) \
;         __builtin_amdgcn_global_load_lds((const unsigned*)((const char*)(gbase) + (voff)[_i]), (PG8_LAS unsigned*)(lds + (bufoff) + ldsw + _i * 8192), 16, 0, 0); } while (0)
; #define PG8_WAIT_V(n) asm volatile("s_waitcnt vmcnt(" #n ")" ::: "memory")
; #define PG8_BAR __builtin_amdgcn_s_barrier()
; template <class Epi, class Sched, bool ALIGN_EPI = false, bool SP2 = false>
; __device__ __forceinline__ void gemm_phase(PG8_LAS unsigned char* lds, const Gemm g, const Sched& S, const Epi& E) {
;     const int tid = threadIdx.x, wid = __builtin_amdgcn_readfirstlane(tid >> 6), lane = tid & 63, wr = wid >> 2, wc = wid & 3, fr = lane & 15, fq = lane >> 4;
;     const int K = g.K, nt = K / BK;
;     unsigned voffA[2], voffB[2];
; #pragma unroll
;     for (int i = 0; i < 2; ++i) { int R, C; stage_rc(tid * 16 + i * 8192, R, C); const int Rb = Epi::PERM ? ((R & ~31) + perm32(R & 31)) : R;
;         voffA[i] = (unsigned)(R * K + C) * 2u; voffB[i] = (unsigned)(Rb * K + C) * 2u; }
;     const size_t kstep = (size_t)(BK * 2);
;     const size_t hstep = (size_t)HALF * K * 2;
;     const size_t tstep = 2 * hstep;
;     const unsigned ldsw = (unsigned)wid * 1024u;
;     const int aoff = lds_byte(wr * 64 + fr, fq * 8), boff = lds_byte(wc * 32 + fr, fq * 8);
;     ...
;     if constexpr (SP2) {
;         PG8_STAGE(PG8_SB(0, 0), cB, voffB); PG8_STAGE(PG8_SB(0, 1), cB + hstep, voffB); PG8_STAGE(PG8_SA(0, 0), cA, voffA); PG8_STAGE(PG8_SA(0, 1), cA + hstep, voffA);
;         if (wr == 1) PG8_BAR;
;         PG8_WAIT_V(2); PG8_BAR;
;         PG8_STAGE(PG8_SB(1, 0), cB + kstep, voffB); PG8_STAGE(PG8_SA(1, 0), cA + kstep, voffA); PG8_STAGE(PG8_SB(1, 1), cB + hstep + kstep, voffB);
;         PG8_WAIT_V(6); PG8_BAR;
.LBB0_718:
	s_lshl_b32 s12, s12, 5
	s_and_b32 s39, s12, 0x60
	s_mov_b64 s[12:13], 0x80
	s_add_i32 m0, s25, 0x18000
	v_lshl_add_u64 v[6:7], v[6:7], 0, s[12:13]
	s_lshl_b32 s38, s5, 6
	s_lshl_b32 s5, s5, 13
	s_lshl_b32 s15, s39, 7
	s_waitcnt vmcnt(2)
	s_barrier
	global_load_lds_dwordx4 v[6:7], off
	v_lshl_add_u64 v[4:5], v[4:5], 0, s[12:13]
	s_add_i32 m0, s25, 0x1a000
	s_add_i32 s40, s25, 0x8000
	s_add_i32 s41, s25, 0xa000
	global_load_lds_dwordx4 v[4:5], off
	v_lshl_add_u64 v[0:1], v[0:1], 0, s[12:13]
	s_mov_b32 m0, s40
	s_add_u32 s16, s28, 0x80080
	global_load_lds_dwordx4 v[0:1], off
	v_lshl_add_u64 v[0:1], v[2:3], 0, s[12:13]
	s_mov_b32 m0, s41
	s_addc_u32 s17, s29, 0
	global_load_lds_dwordx4 v[0:1], off
	s_add_i32 m0, s25, 0x1c000
	s_nop 0
	global_load_lds_dwordx4 v130, s[16:17]
	v_lshl_add_u64 v[0:1], s[16:17], 0, v[134:135]
	s_add_i32 m0, s25, 0x1e000
	v_bfe_u32 v149, v186, 4, 2
	global_load_lds_dwordx4 v[0:1], off
	s_sext_i32_i8 s46, s4
	v_and_b32_e32 v148, 15, v186
	v_lshlrev_b32_e32 v0, 4, v149
	v_lshlrev_b32_e32 v2, 2, v186
	v_lshlrev_b32_e32 v3, 6, v186
	s_movk_i32 s4, 0x3c0
	v_lshl_or_b32 v1, v148, 6, v0
	v_and_b32_e32 v2, 32, v2
	v_and_or_b32 v0, v3, s4, v0
	v_bitop3_b32 v150, s15, v0, v2 bitop3:0xf6
	v_lshlrev_b32_e32 v0, 9, v186
	v_bitop3_b32 v1, v1, s5, v2 bitop3:0xde
	v_and_b32_e32 v0, 0x70000, v0
	v_lshlrev_b32_e32 v2, 12, v10
	v_or3_b32 v0, v8, v0, v2
	v_add_u32_e32 v136, v0, v9
	v_lshlrev_b32_e32 v0, 5, v11
	s_waitcnt vmcnt(6)
	s_cmpk_lt_u32 s14, 0x100
	v_and_b32_e32 v0, 0xf0000, v0
	s_cselect_b64 s[14:15], -1, 0
	v_or3_b32 v0, v8, v0, v2
	s_add_i32 s43, 0, 0x10000
	s_add_i32 s44, 0, 0x14000
	s_ashr_i32 s42, s3, 31
	v_mov_b32_e32 v137, v131
	v_add_u32_e32 v138, v0, v9
	v_mov_b32_e32 v139, v131
	v_mov_b64_e32 v[140:141], 0x400
	v_mov_b64_e32 v[142:143], 0x3ff
	v_add_u32_e32 v151, s43, v150
	v_add_u32_e32 v152, s44, v150
	v_add_u32_e32 v153, 0, v1
	v_mov_b32_e32 v154, 0x358637bd
	s_mov_b32 s45, 0x800000
	s_barrier
	s_branch .LBB0_721

; #define PG8_STAGE(bufoff, gbase, voff) do { _Pragma("unroll") for (int _i = 0; _i < 2; ++_i) \
;         __builtin_amdgcn_global_load_lds((const unsigned*)((const char*)(gbase) + (voff)[_i]), (PG8_LAS unsigned*)(lds + (bufoff) + ldsw + _i * 8192), 16, 0, 0); } while (0)
; #define PG8_LDA(dst, b, h) do { _Pragma("unroll") for (int m = 0; m < 4; ++m) _Pragma("unroll") for (int k = 0; k < 2; ++k) dst[m][k] = *(const PG8_LAS bf16x8*)(lds + PG8_SA(b, h) + aoff + m * 2048 + k * 1024); } while (0)
; #define PG8_LDB(dst, b, h) do { _Pragma("unroll") for (int n = 0; n < 2; ++n) _Pragma("unroll") for (int k = 0; k < 2; ++k) dst[n][k] = *(const PG8_LAS bf16x8*)(lds + PG8_SB(b, h) + boff + n * 2048 + k * 1024); } while (0)
; #define PG8_MMA(ai, bj, At, Bt) do { __builtin_amdgcn_s_setprio(1); _Pragma("unroll") for (int m = 0; m < 4; ++m) _Pragma("unroll") for (int n = 0; n < 2; ++n) _Pragma("unroll") for (int k = 0; k < 2; ++k) \
;         acc[ai][bj][m][n] = __builtin_amdgcn_mfma_f32_16x16x32_bf16(Bt[n][k], At[m][k], acc[ai][bj][m][n], 0, 0, 0); __builtin_amdgcn_s_setprio(0); } while (0)
; #define PG8_WAIT_V(n) asm volatile("s_waitcnt vmcnt(" #n ")" ::: "memory")
; #define PG8_WAIT_L(n) asm volatile("s_waitcnt lgkmcnt(" #n ")" ::: "memory")
; template <class Epi, class Sched, bool ALIGN_EPI = false, bool SP2 = false>
; __device__ __forceinline__ void gemm_phase(PG8_LAS unsigned char* lds, const Gemm g, const Sched& S, const Epi& E) {
;     ...
;             const bool last = (t == nt - 2);
;             const char* a1 = cA + (size_t)(t + 1) * kstep;
;             const char* a2 = last ? nA : cA + (size_t)(t + 2) * kstep; const char* b2 = last ? nB : cB + (size_t)(t + 2) * kstep;
;             const char* a3 = a2 + kstep; const char* b3 = b2 + kstep;
;             if (last && has_next) S.a_ready(nxt);
;             if constexpr (SP2) {
;             PG8_LDB(B0, 0, 0); PG8_LDB(B1, 0, 1); PG8_SCHED; PG8_LDA(At, 0, 0); PG8_STAGE(PG8_SA(1, 1), a1 + hstep, voffA);
;             PG8_WAIT_V(8); PG8_WAIT_L(0); PG8_BAR; PG8_MMA(0, 0, At, B0); PG8_MMA(0, 1, At, B1); PG8_BAR; PG8_SCHED;
;             PG8_LDA(At, 0, 1); PG8_STAGE(PG8_SB(0, 0), b2, voffB); PG8_STAGE(PG8_SB(0, 1), b2 + hstep, voffB); PG8_STAGE(PG8_SA(0, 0), a2, voffA);
;             PG8_WAIT_V(8); PG8_WAIT_L(0); PG8_BAR; PG8_MMA(1, 0, At, B0); PG8_MMA(1, 1, At, B1); PG8_BAR; PG8_SCHED;
.LBB0_728:
	ds_read_b128 v[144:147], v151
	ds_read_b128 v[156:159], v151 offset:1024
	ds_read_b128 v[160:163], v151 offset:2048
	ds_read_b128 v[164:167], v151 offset:3072
	ds_read_b128 v[168:171], v152
	ds_read_b128 v[172:175], v152 offset:1024
	ds_read_b128 v[176:179], v152 offset:2048
	ds_read_b128 v[180:183], v152 offset:3072
	s_add_u32 s28, s26, 0xfff80080
	s_addc_u32 s29, s27, -1
	s_cmp_eq_u32 s51, 28
	s_cselect_b32 s31, s19, s29
	s_cselect_b32 s30, s47, s28
	s_cselect_b32 s29, s17, s50
	s_cselect_b32 s28, s48, s49
	s_add_i32 m0, s25, 0xc000
	ds_read_b128 v[188:191], v153
	ds_read_b128 v[192:195], v153 offset:1024
	ds_read_b128 v[196:199], v153 offset:2048
	ds_read_b128 v[200:203], v153 offset:3072
	ds_read_b128 v[204:207], v153 offset:4096
	ds_read_b128 v[208:211], v153 offset:5120
	ds_read_b128 v[212:215], v153 offset:6144
	ds_read_b128 v[216:219], v153 offset:7168
	global_load_lds_dwordx4 v136, s[26:27]
	s_add_i32 m0, s25, 0xe000
	s_nop 0
	global_load_lds_dwordx4 v138, s[26:27]
	s_waitcnt vmcnt(8)
	s_waitcnt lgkmcnt(0)
	s_barrier
	s_setprio 1
	s_waitcnt lgkmcnt(0)
	v_mfma_f32_16x16x32_bf16 v[124:127], v[144:147], v[188:191], v[124:127]
	v_mfma_f32_16x16x32_bf16 v[120:123], v[160:163], v[188:191], v[120:123]
	v_mfma_f32_16x16x32_bf16 v[108:111], v[144:147], v[196:199], v[108:111]
	v_mfma_f32_16x16x32_bf16 v[104:107], v[160:163], v[196:199], v[104:107]
	v_mfma_f32_16x16x32_bf16 v[92:95], v[144:147], v[204:207], v[92:95]
	v_mfma_f32_16x16x32_bf16 v[88:91], v[160:163], v[204:207], v[88:91]
	v_mfma_f32_16x16x32_bf16 v[76:79], v[144:147], v[212:215], v[76:79]
	v_mfma_f32_16x16x32_bf16 v[72:75], v[160:163], v[212:215], v[72:75]
	v_mfma_f32_16x16x32_bf16 v[124:127], v[156:159], v[192:195], v[124:127]
	v_mfma_f32_16x16x32_bf16 v[120:123], v[164:167], v[192:195], v[120:123]
	v_mfma_f32_16x16x32_bf16 v[108:111], v[156:159], v[200:203], v[108:111]
	v_mfma_f32_16x16x32_bf16 v[104:107], v[164:167], v[200:203], v[104:107]
	v_mfma_f32_16x16x32_bf16 v[92:95], v[156:159], v[208:211], v[92:95]
	v_mfma_f32_16x16x32_bf16 v[88:91], v[164:167], v[208:211], v[88:91]
	v_mfma_f32_16x16x32_bf16 v[76:79], v[156:159], v[216:219], v[76:79]
	v_mfma_f32_16x16x32_bf16 v[72:75], v[164:167], v[216:219], v[72:75]
	s_setprio 0
	s_setprio 1
	v_mfma_f32_16x16x32_bf16 v[116:119], v[168:171], v[188:191], v[116:119]
	v_mfma_f32_16x16x32_bf16 v[112:115], v[176:179], v[188:191], v[112:115]
	v_mfma_f32_16x16x32_bf16 v[100:103], v[168:171], v[196:199], v[100:103]
	v_mfma_f32_16x16x32_bf16 v[96:99], v[176:179], v[196:199], v[96:99]
	v_mfma_f32_16x16x32_bf16 v[84:87], v[168:171], v[204:207], v[84:87]
	v_mfma_f32_16x16x32_bf16 v[80:83], v[176:179], v[204:207], v[80:83]
	v_mfma_f32_16x16x32_bf16 v[68:71], v[168:171], v[212:215], v[68:71]
	v_mfma_f32_16x16x32_bf16 v[64:67], v[176:179], v[212:215], v[64:67]
	v_mfma_f32_16x16x32_bf16 v[116:119], v[172:175], v[192:195], v[116:119]
	v_mfma_f32_16x16x32_bf16 v[112:115], v[180:183], v[192:195], v[112:115]
	v_mfma_f32_16x16x32_bf16 v[100:103], v[172:175], v[200:203], v[100:103]
	v_mfma_f32_16x16x32_bf16 v[96:99], v[180:183], v[200:203], v[96:99]
	v_mfma_f32_16x16x32_bf16 v[84:87], v[172:175], v[208:211], v[84:87]
	v_mfma_f32_16x16x32_bf16 v[80:83], v[180:183], v[208:211], v[80:83]
	v_mfma_f32_16x16x32_bf16 v[68:71], v[172:175], v[216:219], v[68:71]
	v_mfma_f32_16x16x32_bf16 v[64:67], v[180:183], v[216:219], v[64:67]
	s_setprio 0
	s_barrier
	s_add_u32 s98, s28, s12
	s_addc_u32 s99, s29, s13
	s_add_u32 s100, s30, s12
	s_addc_u32 s101, s31, s13
	s_add_i32 s54, s43, s1
	s_mov_b32 m0, s54
	ds_read_b128 v[188:191], v153 offset:16384
	ds_read_b128 v[192:195], v153 offset:17408
	ds_read_b128 v[196:199], v153 offset:18432
	ds_read_b128 v[200:203], v153 offset:19456
	ds_read_b128 v[204:207], v153 offset:20480
	ds_read_b128 v[208:211], v153 offset:21504
	ds_read_b128 v[212:215], v153 offset:22528
	ds_read_b128 v[216:219], v153 offset:23552
	global_load_lds_dwordx4 v130, s[28:29]
	s_add_i32 m0, s54, 0x2000
	s_add_u32 s54, s28, 0x80000
	s_addc_u32 s55, s29, 0
	s_add_i32 s56, s44, s1
	global_load_lds_dwordx4 v134, s[28:29]
	s_mov_b32 m0, s56
	s_nop 0
	global_load_lds_dwordx4 v130, s[54:55]
	s_add_i32 m0, s56, 0x2000
	s_nop 0
	global_load_lds_dwordx4 v134, s[54:55]
	s_mov_b32 m0, s25
	s_nop 0
	global_load_lds_dwordx4 v128, s[30:31]
	s_mov_b32 m0, s34
	s_nop 0
	global_load_lds_dwordx4 v132, s[30:31]
	s_waitcnt vmcnt(8)
	s_waitcnt lgkmcnt(0)
	s_barrier
	s_setprio 1
	s_waitcnt lgkmcnt(0)
	v_mfma_f32_16x16x32_bf16 v[60:63], v[144:147], v[188:191], v[60:63]
	v_mfma_f32_16x16x32_bf16 v[56:59], v[160:163], v[188:191], v[56:59]
	v_mfma_f32_16x16x32_bf16 v[44:47], v[144:147], v[196:199], v[44:47]
	v_mfma_f32_16x16x32_bf16 v[40:43], v[160:163], v[196:199], v[40:43]
	v_mfma_f32_16x16x32_bf16 v[28:31], v[144:147], v[204:207], v[28:31]
	v_mfma_f32_16x16x32_bf16 v[24:27], v[160:163], v[204:207], v[24:27]
	v_mfma_f32_16x16x32_bf16 v[12:15], v[144:147], v[212:215], v[12:15]
	v_mfma_f32_16x16x32_bf16 v[8:11], v[160:163], v[212:215], v[8:11]
	v_mfma_f32_16x16x32_bf16 v[60:63], v[156:159], v[192:195], v[60:63]
	v_mfma_f32_16x16x32_bf16 v[56:59], v[164:167], v[192:195], v[56:59]
	v_mfma_f32_16x16x32_bf16 v[44:47], v[156:159], v[200:203], v[44:47]
	v_mfma_f32_16x16x32_bf16 v[40:43], v[164:167], v[200:203], v[40:43]
	v_mfma_f32_16x16x32_bf16 v[28:31], v[156:159], v[208:211], v[28:31]
	v_mfma_f32_16x16x32_bf16 v[24:27], v[164:167], v[208:211], v[24:27]
	v_mfma_f32_16x16x32_bf16 v[12:15], v[156:159], v[216:219], v[12:15]
	v_mfma_f32_16x16x32_bf16 v[8:11], v[164:167], v[216:219], v[8:11]
	s_setprio 0
	s_setprio 1
	v_mfma_f32_16x16x32_bf16 v[52:55], v[168:171], v[188:191], v[52:55]
	v_mfma_f32_16x16x32_bf16 v[48:51], v[176:179], v[188:191], v[48:51]
	v_mfma_f32_16x16x32_bf16 v[36:39], v[168:171], v[196:199], v[36:39]
	v_mfma_f32_16x16x32_bf16 v[32:35], v[176:179], v[196:199], v[32:35]
	v_mfma_f32_16x16x32_bf16 v[20:23], v[168:171], v[204:207], v[20:23]
	v_mfma_f32_16x16x32_bf16 v[16:19], v[176:179], v[204:207], v[16:19]
	v_mfma_f32_16x16x32_bf16 v[4:7], v[168:171], v[212:215], v[4:7]
	v_mfma_f32_16x16x32_bf16 v[0:3], v[176:179], v[212:215], v[0:3]
	v_mfma_f32_16x16x32_bf16 v[52:55], v[172:175], v[192:195], v[52:55]
	v_mfma_f32_16x16x32_bf16 v[48:51], v[180:183], v[192:195], v[48:51]
	v_mfma_f32_16x16x32_bf16 v[36:39], v[172:175], v[200:203], v[36:39]
	v_mfma_f32_16x16x32_bf16 v[32:35], v[180:183], v[200:203], v[32:35]
	v_mfma_f32_16x16x32_bf16 v[20:23], v[172:175], v[208:211], v[20:23]
	v_mfma_f32_16x16x32_bf16 v[16:19], v[180:183], v[208:211], v[16:19]
	v_mfma_f32_16x16x32_bf16 v[4:7], v[172:175], v[216:219], v[4:7]
	v_mfma_f32_16x16x32_bf16 v[0:3], v[180:183], v[216:219], v[0:3]
	s_setprio 0
	s_barrier
; #define PG8_STAGE(bufoff, gbase, voff) do { _Pragma("unroll") for (int _i = 0; _i < 2; ++_i) \
;         __builtin_amdgcn_global_load_lds((const unsigned*)((const char*)(gbase) + (voff)[_i]), (PG8_LAS unsigned*)(lds + (bufoff) + ldsw + _i * 8192), 16, 0, 0); } while (0)
; #define PG8_LDA(dst, b, h) do { _Pragma("unroll") for (int m = 0; m < 4; ++m) _Pragma("unroll") for (int k = 0; k < 2; ++k) dst[m][k] = *(const PG8_LAS bf16x8*)(lds + PG8_SA(b, h) + aoff + m * 2048 + k * 1024); } while (0)
; #define PG8_LDB(dst, b, h) do { _Pragma("unroll") for (int n = 0; n < 2; ++n) _Pragma("unroll") for (int k = 0; k < 2; ++k) dst[n][k] = *(const PG8_LAS bf16x8*)(lds + PG8_SB(b, h) + boff + n * 2048 + k * 1024); } while (0)
; #define PG8_MMA(ai, bj, At, Bt) do { __builtin_amdgcn_s_setprio(1); _Pragma("unroll") for (int m = 0; m < 4; ++m) _Pragma("unroll") for (int n = 0; n < 2; ++n) _Pragma("unroll") for (int k = 0; k < 2; ++k) \
;         acc[ai][bj][m][n] = __builtin_amdgcn_mfma_f32_16x16x32_bf16(Bt[n][k], At[m][k], acc[ai][bj][m][n], 0, 0, 0); __builtin_amdgcn_s_setprio(0); } while (0)
; #define PG8_WAIT_V(n) asm volatile("s_waitcnt vmcnt(" #n ")" ::: "memory")
; #define PG8_WAIT_L(n) asm volatile("s_waitcnt lgkmcnt(" #n ")" ::: "memory")
; #define PG8_BAR __builtin_amdgcn_s_barrier()
; #define PG8_SCHED __builtin_amdgcn_sched_barrier(0)
; template <class Epi, class Sched, bool ALIGN_EPI = false, bool SP2 = false>
; __device__ __forceinline__ void gemm_phase(PG8_LAS unsigned char* lds, const Gemm g, const Sched& S, const Epi& E) {
;     ...
;             PG8_LDB(B0, 1, 0); PG8_LDB(B1, 1, 1); PG8_SCHED; PG8_LDA(At, 1, 0); PG8_STAGE(PG8_SA(0, 1), a2 + hstep, voffA);
;             PG8_WAIT_V(8); PG8_WAIT_L(0); PG8_BAR; PG8_MMA(0, 0, At, B0); PG8_MMA(0, 1, At, B1); PG8_BAR; PG8_SCHED;
;             PG8_LDA(At, 1, 1); PG8_STAGE(PG8_SB(1, 0), b3, voffB); PG8_STAGE(PG8_SB(1, 1), b3 + hstep, voffB); PG8_STAGE(PG8_SA(1, 0), a3, voffA);
;             PG8_WAIT_V(8); PG8_WAIT_L(0); PG8_BAR; PG8_MMA(1, 0, At, B0); PG8_MMA(1, 1, At, B1); PG8_BAR; PG8_SCHED;
	s_add_i32 s54, 0, 0x18000
	v_add_u32_e32 v155, s54, v150
	s_add_i32 s55, 0, 0x1c000
	ds_read_b128 v[144:147], v155
	ds_read_b128 v[156:159], v155 offset:1024
	ds_read_b128 v[160:163], v155 offset:2048
	ds_read_b128 v[164:167], v155 offset:3072
	v_add_u32_e32 v155, s55, v150
	ds_read_b128 v[168:171], v155
	ds_read_b128 v[172:175], v155 offset:1024
	ds_read_b128 v[176:179], v155 offset:2048
	ds_read_b128 v[180:183], v155 offset:3072
	s_add_u32 s30, s30, 0x80000
	s_addc_u32 s31, s31, 0
	s_mov_b32 m0, s35
	ds_read_b128 v[188:191], v153 offset:32768
	ds_read_b128 v[192:195], v153 offset:33792
	ds_read_b128 v[196:199], v153 offset:34816
	ds_read_b128 v[200:203], v153 offset:35840
	ds_read_b128 v[204:207], v153 offset:36864
	ds_read_b128 v[208:211], v153 offset:37888
	ds_read_b128 v[212:215], v153 offset:38912
	ds_read_b128 v[216:219], v153 offset:39936
	global_load_lds_dwordx4 v128, s[30:31]
	s_mov_b32 m0, s36
	s_nop 0
	global_load_lds_dwordx4 v132, s[30:31]
	s_waitcnt vmcnt(8)
	s_waitcnt lgkmcnt(0)
	s_barrier
	s_setprio 1
	s_waitcnt lgkmcnt(0)
	v_mfma_f32_16x16x32_bf16 v[124:127], v[144:147], v[188:191], v[124:127]
	v_mfma_f32_16x16x32_bf16 v[120:123], v[160:163], v[188:191], v[120:123]
	v_mfma_f32_16x16x32_bf16 v[108:111], v[144:147], v[196:199], v[108:111]
	v_mfma_f32_16x16x32_bf16 v[104:107], v[160:163], v[196:199], v[104:107]
	v_mfma_f32_16x16x32_bf16 v[92:95], v[144:147], v[204:207], v[92:95]
	v_mfma_f32_16x16x32_bf16 v[88:91], v[160:163], v[204:207], v[88:91]
	v_mfma_f32_16x16x32_bf16 v[76:79], v[144:147], v[212:215], v[76:79]
	v_mfma_f32_16x16x32_bf16 v[72:75], v[160:163], v[212:215], v[72:75]
	v_mfma_f32_16x16x32_bf16 v[124:127], v[156:159], v[192:195], v[124:127]
	v_mfma_f32_16x16x32_bf16 v[120:123], v[164:167], v[192:195], v[120:123]
	v_mfma_f32_16x16x32_bf16 v[108:111], v[156:159], v[200:203], v[108:111]
	v_mfma_f32_16x16x32_bf16 v[104:107], v[164:167], v[200:203], v[104:107]
	v_mfma_f32_16x16x32_bf16 v[92:95], v[156:159], v[208:211], v[92:95]
	v_mfma_f32_16x16x32_bf16 v[88:91], v[164:167], v[208:211], v[88:91]
	v_mfma_f32_16x16x32_bf16 v[76:79], v[156:159], v[216:219], v[76:79]
	v_mfma_f32_16x16x32_bf16 v[72:75], v[164:167], v[216:219], v[72:75]
	s_setprio 0
	s_setprio 1
	v_mfma_f32_16x16x32_bf16 v[116:119], v[168:171], v[188:191], v[116:119]
	v_mfma_f32_16x16x32_bf16 v[112:115], v[176:179], v[188:191], v[112:115]
	v_mfma_f32_16x16x32_bf16 v[100:103], v[168:171], v[196:199], v[100:103]
	v_mfma_f32_16x16x32_bf16 v[96:99], v[176:179], v[196:199], v[96:99]
	v_mfma_f32_16x16x32_bf16 v[84:87], v[168:171], v[204:207], v[84:87]
	v_mfma_f32_16x16x32_bf16 v[80:83], v[176:179], v[204:207], v[80:83]
	v_mfma_f32_16x16x32_bf16 v[68:71], v[168:171], v[212:215], v[68:71]
	v_mfma_f32_16x16x32_bf16 v[64:67], v[176:179], v[212:215], v[64:67]
	v_mfma_f32_16x16x32_bf16 v[116:119], v[172:175], v[192:195], v[116:119]
	v_mfma_f32_16x16x32_bf16 v[112:115], v[180:183], v[192:195], v[112:115]
	v_mfma_f32_16x16x32_bf16 v[100:103], v[172:175], v[200:203], v[100:103]
	v_mfma_f32_16x16x32_bf16 v[96:99], v[180:183], v[200:203], v[96:99]
	v_mfma_f32_16x16x32_bf16 v[84:87], v[172:175], v[208:211], v[84:87]
	v_mfma_f32_16x16x32_bf16 v[80:83], v[180:183], v[208:211], v[80:83]
	v_mfma_f32_16x16x32_bf16 v[68:71], v[172:175], v[216:219], v[68:71]
	v_mfma_f32_16x16x32_bf16 v[64:67], v[180:183], v[216:219], v[64:67]
	s_setprio 0
	s_barrier
	s_add_i32 s30, s54, s1
	s_mov_b32 m0, s30
	ds_read_b128 v[188:191], v153 offset:49152
	ds_read_b128 v[192:195], v153 offset:50176
	ds_read_b128 v[196:199], v153 offset:51200
	ds_read_b128 v[200:203], v153 offset:52224
	ds_read_b128 v[204:207], v153 offset:53248
	ds_read_b128 v[208:211], v153 offset:54272
	ds_read_b128 v[212:215], v153 offset:55296
	ds_read_b128 v[216:219], v153 offset:56320
	global_load_lds_dwordx4 v130, s[98:99]
	s_add_i32 m0, s30, 0x2000
	s_add_u32 s28, s28, 0x80080
	s_addc_u32 s29, s29, 0
	s_add_i32 s30, s55, s1
	global_load_lds_dwordx4 v134, s[98:99]
	s_mov_b32 m0, s30
	s_nop 0
	global_load_lds_dwordx4 v130, s[28:29]
	s_add_i32 m0, s30, 0x2000
	s_nop 0
	global_load_lds_dwordx4 v134, s[28:29]
	s_mov_b32 m0, s40
	s_nop 0
	global_load_lds_dwordx4 v128, s[100:101]
	s_mov_b32 m0, s41
	s_nop 0
	global_load_lds_dwordx4 v132, s[100:101]
	s_waitcnt vmcnt(8)
	s_waitcnt lgkmcnt(0)
	s_barrier
	s_setprio 1
	s_waitcnt lgkmcnt(0)
	v_mfma_f32_16x16x32_bf16 v[60:63], v[144:147], v[188:191], v[60:63]
	v_mfma_f32_16x16x32_bf16 v[56:59], v[160:163], v[188:191], v[56:59]
	v_mfma_f32_16x16x32_bf16 v[44:47], v[144:147], v[196:199], v[44:47]
	v_mfma_f32_16x16x32_bf16 v[40:43], v[160:163], v[196:199], v[40:43]
	v_mfma_f32_16x16x32_bf16 v[28:31], v[144:147], v[204:207], v[28:31]
	v_mfma_f32_16x16x32_bf16 v[24:27], v[160:163], v[204:207], v[24:27]
	v_mfma_f32_16x16x32_bf16 v[12:15], v[144:147], v[212:215], v[12:15]
	v_mfma_f32_16x16x32_bf16 v[8:11], v[160:163], v[212:215], v[8:11]
	v_mfma_f32_16x16x32_bf16 v[60:63], v[156:159], v[192:195], v[60:63]
	v_mfma_f32_16x16x32_bf16 v[56:59], v[164:167], v[192:195], v[56:59]
	v_mfma_f32_16x16x32_bf16 v[44:47], v[156:159], v[200:203], v[44:47]
	v_mfma_f32_16x16x32_bf16 v[40:43], v[164:167], v[200:203], v[40:43]
	v_mfma_f32_16x16x32_bf16 v[28:31], v[156:159], v[208:211], v[28:31]
	v_mfma_f32_16x16x32_bf16 v[24:27], v[164:167], v[208:211], v[24:27]
	v_mfma_f32_16x16x32_bf16 v[12:15], v[156:159], v[216:219], v[12:15]
	v_mfma_f32_16x16x32_bf16 v[8:11], v[164:167], v[216:219], v[8:11]
	s_setprio 0
	s_setprio 1
	v_mfma_f32_16x16x32_bf16 v[52:55], v[168:171], v[188:191], v[52:55]
	v_mfma_f32_16x16x32_bf16 v[48:51], v[176:179], v[188:191], v[48:51]
	v_mfma_f32_16x16x32_bf16 v[36:39], v[168:171], v[196:199], v[36:39]
	v_mfma_f32_16x16x32_bf16 v[32:35], v[176:179], v[196:199], v[32:35]
	v_mfma_f32_16x16x32_bf16 v[20:23], v[168:171], v[204:207], v[20:23]
	v_mfma_f32_16x16x32_bf16 v[16:19], v[176:179], v[204:207], v[16:19]
	v_mfma_f32_16x16x32_bf16 v[4:7], v[168:171], v[212:215], v[4:7]
	v_mfma_f32_16x16x32_bf16 v[0:3], v[176:179], v[212:215], v[0:3]
	v_mfma_f32_16x16x32_bf16 v[52:55], v[172:175], v[192:195], v[52:55]
	v_mfma_f32_16x16x32_bf16 v[48:51], v[180:183], v[192:195], v[48:51]
	v_mfma_f32_16x16x32_bf16 v[36:39], v[172:175], v[200:203], v[36:39]
	v_mfma_f32_16x16x32_bf16 v[32:35], v[180:183], v[200:203], v[32:35]
	v_mfma_f32_16x16x32_bf16 v[20:23], v[172:175], v[208:211], v[20:23]
	v_mfma_f32_16x16x32_bf16 v[16:19], v[180:183], v[208:211], v[16:19]
	v_mfma_f32_16x16x32_bf16 v[4:7], v[172:175], v[216:219], v[4:7]
	v_mfma_f32_16x16x32_bf16 v[0:3], v[180:183], v[216:219], v[0:3]
	s_setprio 0
	s_barrier
	s_add_i32 s51, s51, 2
	s_add_u32 s26, s26, 0x100
	s_addc_u32 s27, s27, 0
	s_add_u32 s49, s49, 0x100
	s_addc_u32 s50, s50, 0
	s_cmp_gt_u32 s51, 29
	s_cbranch_scc0 .LBB0_728
	s_and_b64 vcc, exec, s[14:15]
	s_cbranch_vccz .LBB0_731
	s_barrier

; #define PG8_STAGE(bufoff, gbase, voff) do { _Pragma("unroll") for (int _i = 0; _i < 2; ++_i) \
;         __builtin_amdgcn_global_load_lds((const unsigned*)((const char*)(gbase) + (voff)[_i]), (PG8_LAS unsigned*)(lds + (bufoff) + ldsw + _i * 8192), 16, 0, 0); } while (0)
; #define PG8_WAIT_V(n) asm volatile("s_waitcnt vmcnt(" #n ")" ::: "memory")
; #define PG8_BAR __builtin_amdgcn_s_barrier()
; template <class Epi, class Sched, bool ALIGN_EPI = false, bool SP2 = false>
; __device__ __forceinline__ void gemm_phase(PG8_LAS unsigned char* lds, const Gemm g, const Sched& S, const Epi& E) {
;     ...
;     for (int i = 0; i < 2; ++i) { int R, C; stage_rc(tid * 16 + i * 8192, R, C); const int Rb = Epi::PERM ? ((R & ~31) + perm32(R & 31)) : R;
;         voffA[i] = (unsigned)(R * K + C) * 2u; voffB[i] = (unsigned)(Rb * K + C) * 2u; }
;     const size_t kstep = (size_t)(BK * 2);
;     const size_t hstep = (size_t)HALF * K * 2;
;     const size_t tstep = 2 * hstep;
;     const unsigned ldsw = (unsigned)wid * 1024u;
;     const int aoff = lds_byte(wr * 64 + fr, fq * 8), boff = lds_byte(wc * 32 + fr, fq * 8);
;     ...
;         PG8_STAGE(PG8_SB(1, 0), cB + kstep, voffB); PG8_STAGE(PG8_SA(1, 0), cA + kstep, voffA); PG8_STAGE(PG8_SB(1, 1), cB + hstep + kstep, voffB);
;         PG8_WAIT_V(6); PG8_BAR;
.LBB0_793:
	s_lshl_b32 s10, s10, 5
	s_mov_b64 s[14:15], 0x80
	s_and_b32 s10, s10, 0x60
	s_add_i32 m0, s27, 0x18000
	v_lshl_add_u64 v[6:7], v[6:7], 0, s[14:15]
	s_lshl_b32 s39, s5, 6
	s_lshl_b32 s5, s5, 13
	s_lshl_b32 s17, s10, 7
	s_waitcnt vmcnt(2)
	s_barrier
	global_load_lds_dwordx4 v[6:7], off
	v_lshl_add_u64 v[4:5], v[4:5], 0, s[14:15]
	s_add_i32 m0, s27, 0x1a000
	s_add_i32 s40, s27, 0x8000
	s_add_i32 s41, s27, 0xa000
	global_load_lds_dwordx4 v[4:5], off
	v_lshl_add_u64 v[0:1], v[0:1], 0, s[14:15]
	s_mov_b32 m0, s40
	s_add_u32 s18, s30, 0x200080
	global_load_lds_dwordx4 v[0:1], off
	v_lshl_add_u64 v[0:1], v[2:3], 0, s[14:15]
	s_mov_b32 m0, s41
	s_addc_u32 s19, s31, 0
	global_load_lds_dwordx4 v[0:1], off
	s_add_i32 m0, s27, 0x1c000
	s_nop 0
	global_load_lds_dwordx4 v130, s[18:19]
	v_lshl_add_u64 v[0:1], s[18:19], 0, v[134:135]
	s_add_i32 m0, s27, 0x1e000
	v_bfe_u32 v149, v186, 4, 2
	global_load_lds_dwordx4 v[0:1], off
	s_sext_i32_i8 s46, s4
	v_and_b32_e32 v148, 15, v186
	v_lshlrev_b32_e32 v0, 4, v149
	v_lshlrev_b32_e32 v2, 2, v186
	v_lshlrev_b32_e32 v3, 6, v186
	s_movk_i32 s4, 0x3c0
	v_lshl_or_b32 v1, v148, 6, v0
	v_and_b32_e32 v2, 32, v2
	v_and_or_b32 v0, v3, s4, v0
	v_bitop3_b32 v150, s17, v0, v2 bitop3:0xf6
	v_lshlrev_b32_e32 v0, 11, v186
	v_bitop3_b32 v1, v1, s5, v2 bitop3:0xde
	v_and_b32_e32 v0, 0x1c0000, v0
	v_lshlrev_b32_e32 v2, 14, v10
	v_or3_b32 v0, v8, v0, v2
	v_add_u32_e32 v136, v0, v9
	v_lshlrev_b32_e32 v0, 7, v11
	s_waitcnt vmcnt(6)
	s_cmpk_lt_u32 s16, 0x100
	v_and_b32_e32 v0, 0x3c0000, v0
	s_cselect_b64 s[16:17], -1, 0
	v_or3_b32 v0, v8, v0, v2
	s_add_i32 s43, 0, 0x10000
	s_add_i32 s44, 0, 0x14000
	s_ashr_i32 s42, s3, 31
	v_mov_b32_e32 v137, v131
	v_add_u32_e32 v138, v0, v9
	v_mov_b32_e32 v139, v131
	v_mov_b64_e32 v[140:141], 0x100
	v_mov_b64_e32 v[142:143], 0xff
	v_add_u32_e32 v151, s43, v150
	v_add_u32_e32 v152, s44, v150
	v_add_u32_e32 v153, 0, v1
	s_mov_b32 s45, s11
	s_barrier
	s_branch .LBB0_796

; #define PG8_STAGE(bufoff, gbase, voff) do { _Pragma("unroll") for (int _i = 0; _i < 2; ++_i) \
;         __builtin_amdgcn_global_load_lds((const unsigned*)((const char*)(gbase) + (voff)[_i]), (PG8_LAS unsigned*)(lds + (bufoff) + ldsw + _i * 8192), 16, 0, 0); } while (0)
; #define PG8_LDA(dst, b, h) do { _Pragma("unroll") for (int m = 0; m < 4; ++m) _Pragma("unroll") for (int k = 0; k < 2; ++k) dst[m][k] = *(const PG8_LAS bf16x8*)(lds + PG8_SA(b, h) + aoff + m * 2048 + k * 1024); } while (0)
; #define PG8_LDB(dst, b, h) do { _Pragma("unroll") for (int n = 0; n < 2; ++n) _Pragma("unroll") for (int k = 0; k < 2; ++k) dst[n][k] = *(const PG8_LAS bf16x8*)(lds + PG8_SB(b, h) + boff + n * 2048 + k * 1024); } while (0)
; #define PG8_MMA(ai, bj, At, Bt) do { __builtin_amdgcn_s_setprio(1); _Pragma("unroll") for (int m = 0; m < 4; ++m) _Pragma("unroll") for (int n = 0; n < 2; ++n) _Pragma("unroll") for (int k = 0; k < 2; ++k) \
;         acc[ai][bj][m][n] = __builtin_amdgcn_mfma_f32_16x16x32_bf16(Bt[n][k], At[m][k], acc[ai][bj][m][n], 0, 0, 0); __builtin_amdgcn_s_setprio(0); } while (0)
; #define PG8_WAIT_V(n) asm volatile("s_waitcnt vmcnt(" #n ")" ::: "memory")
; #define PG8_WAIT_L(n) asm volatile("s_waitcnt lgkmcnt(" #n ")" ::: "memory")
; template <class Epi, class Sched, bool ALIGN_EPI = false, bool SP2 = false>
; __device__ __forceinline__ void gemm_phase(PG8_LAS unsigned char* lds, const Gemm g, const Sched& S, const Epi& E) {
;     ...
;             const bool last = (t == nt - 2);
;             const char* a1 = cA + (size_t)(t + 1) * kstep;
;             const char* a2 = last ? nA : cA + (size_t)(t + 2) * kstep; const char* b2 = last ? nB : cB + (size_t)(t + 2) * kstep;
;             const char* a3 = a2 + kstep; const char* b3 = b2 + kstep;
;             if (last && has_next) S.a_ready(nxt);
;             if constexpr (SP2) {
;             PG8_LDB(B0, 0, 0); PG8_LDB(B1, 0, 1); PG8_SCHED; PG8_LDA(At, 0, 0); PG8_STAGE(PG8_SA(1, 1), a1 + hstep, voffA);
;             PG8_WAIT_V(8); PG8_WAIT_L(0); PG8_BAR; PG8_MMA(0, 0, At, B0); PG8_MMA(0, 1, At, B1); PG8_BAR; PG8_SCHED;
;             PG8_LDA(At, 0, 1); PG8_STAGE(PG8_SB(0, 0), b2, voffB); PG8_STAGE(PG8_SB(0, 1), b2 + hstep, voffB); PG8_STAGE(PG8_SA(0, 0), a2, voffA);
;             PG8_WAIT_V(8); PG8_WAIT_L(0); PG8_BAR; PG8_MMA(1, 0, At, B0); PG8_MMA(1, 1, At, B1); PG8_BAR; PG8_SCHED;
.LBB0_803:
	ds_read_b128 v[144:147], v151
	ds_read_b128 v[154:157], v151 offset:1024
	ds_read_b128 v[158:161], v151 offset:2048
	ds_read_b128 v[162:165], v151 offset:3072
	ds_read_b128 v[166:169], v152
	ds_read_b128 v[170:173], v152 offset:1024
	ds_read_b128 v[174:177], v152 offset:2048
	ds_read_b128 v[178:181], v152 offset:3072
	s_add_u32 s30, s28, 0xffe00080
	s_addc_u32 s31, s29, -1
	s_cmpk_eq_i32 s51, 0x7c
	s_cselect_b32 s35, s21, s31
	s_cselect_b32 s34, s47, s30
	s_cselect_b32 s31, s19, s50
	s_cselect_b32 s30, s48, s49
	s_add_i32 m0, s27, 0xc000
	ds_read_b128 v[182:185], v153
	ds_read_b128 v[188:191], v153 offset:1024
	ds_read_b128 v[192:195], v153 offset:2048
	ds_read_b128 v[196:199], v153 offset:3072
	ds_read_b128 v[200:203], v153 offset:4096
	ds_read_b128 v[204:207], v153 offset:5120
	ds_read_b128 v[208:211], v153 offset:6144
	ds_read_b128 v[212:215], v153 offset:7168
	global_load_lds_dwordx4 v136, s[28:29]
	s_add_i32 m0, s27, 0xe000
	s_nop 0
	global_load_lds_dwordx4 v138, s[28:29]
	s_waitcnt vmcnt(8)
	s_waitcnt lgkmcnt(0)
	s_barrier
	s_setprio 1
	s_waitcnt lgkmcnt(0)
	v_mfma_f32_16x16x32_bf16 v[124:127], v[144:147], v[182:185], v[124:127]
	v_mfma_f32_16x16x32_bf16 v[120:123], v[158:161], v[182:185], v[120:123]
	v_mfma_f32_16x16x32_bf16 v[112:115], v[144:147], v[192:195], v[112:115]
	v_mfma_f32_16x16x32_bf16 v[104:107], v[158:161], v[192:195], v[104:107]
	v_mfma_f32_16x16x32_bf16 v[96:99], v[144:147], v[200:203], v[96:99]
	v_mfma_f32_16x16x32_bf16 v[88:91], v[158:161], v[200:203], v[88:91]
	v_mfma_f32_16x16x32_bf16 v[80:83], v[144:147], v[208:211], v[80:83]
	v_mfma_f32_16x16x32_bf16 v[72:75], v[158:161], v[208:211], v[72:75]
	v_mfma_f32_16x16x32_bf16 v[124:127], v[154:157], v[188:191], v[124:127]
	v_mfma_f32_16x16x32_bf16 v[120:123], v[162:165], v[188:191], v[120:123]
	v_mfma_f32_16x16x32_bf16 v[112:115], v[154:157], v[196:199], v[112:115]
	v_mfma_f32_16x16x32_bf16 v[104:107], v[162:165], v[196:199], v[104:107]
	v_mfma_f32_16x16x32_bf16 v[96:99], v[154:157], v[204:207], v[96:99]
	v_mfma_f32_16x16x32_bf16 v[88:91], v[162:165], v[204:207], v[88:91]
	v_mfma_f32_16x16x32_bf16 v[80:83], v[154:157], v[212:215], v[80:83]
	v_mfma_f32_16x16x32_bf16 v[72:75], v[162:165], v[212:215], v[72:75]
	s_setprio 0
	s_setprio 1
	v_mfma_f32_16x16x32_bf16 v[116:119], v[166:169], v[182:185], v[116:119]
	v_mfma_f32_16x16x32_bf16 v[108:111], v[174:177], v[182:185], v[108:111]
	v_mfma_f32_16x16x32_bf16 v[100:103], v[166:169], v[192:195], v[100:103]
	v_mfma_f32_16x16x32_bf16 v[92:95], v[174:177], v[192:195], v[92:95]
	v_mfma_f32_16x16x32_bf16 v[84:87], v[166:169], v[200:203], v[84:87]
	v_mfma_f32_16x16x32_bf16 v[76:79], v[174:177], v[200:203], v[76:79]
	v_mfma_f32_16x16x32_bf16 v[68:71], v[166:169], v[208:211], v[68:71]
	v_mfma_f32_16x16x32_bf16 v[64:67], v[174:177], v[208:211], v[64:67]
	v_mfma_f32_16x16x32_bf16 v[116:119], v[170:173], v[188:191], v[116:119]
	v_mfma_f32_16x16x32_bf16 v[108:111], v[178:181], v[188:191], v[108:111]
	v_mfma_f32_16x16x32_bf16 v[100:103], v[170:173], v[196:199], v[100:103]
	v_mfma_f32_16x16x32_bf16 v[92:95], v[178:181], v[196:199], v[92:95]
	v_mfma_f32_16x16x32_bf16 v[84:87], v[170:173], v[204:207], v[84:87]
	v_mfma_f32_16x16x32_bf16 v[76:79], v[178:181], v[204:207], v[76:79]
	v_mfma_f32_16x16x32_bf16 v[68:71], v[170:173], v[212:215], v[68:71]
	v_mfma_f32_16x16x32_bf16 v[64:67], v[178:181], v[212:215], v[64:67]
	s_setprio 0
	s_barrier
	s_add_u32 s98, s30, s14
	s_addc_u32 s99, s31, s15
	s_add_u32 s100, s34, s14
	s_addc_u32 s101, s35, s15
	s_add_i32 s54, s43, s1
	s_mov_b32 m0, s54
	ds_read_b128 v[182:185], v153 offset:16384
	ds_read_b128 v[188:191], v153 offset:17408
	ds_read_b128 v[192:195], v153 offset:18432
	ds_read_b128 v[196:199], v153 offset:19456
	ds_read_b128 v[200:203], v153 offset:20480
	ds_read_b128 v[204:207], v153 offset:21504
	ds_read_b128 v[208:211], v153 offset:22528
	ds_read_b128 v[212:215], v153 offset:23552
	global_load_lds_dwordx4 v130, s[30:31]
	s_add_i32 m0, s54, 0x2000
	s_add_u32 s54, s30, 0x200000
	s_addc_u32 s55, s31, 0
	s_add_i32 s56, s44, s1
	global_load_lds_dwordx4 v134, s[30:31]
	s_mov_b32 m0, s56
	s_nop 0
	global_load_lds_dwordx4 v130, s[54:55]
	s_add_i32 m0, s56, 0x2000
	s_nop 0
	global_load_lds_dwordx4 v134, s[54:55]
	s_mov_b32 m0, s27
	s_nop 0
	global_load_lds_dwordx4 v128, s[34:35]
	s_mov_b32 m0, s36
	s_nop 0
	global_load_lds_dwordx4 v132, s[34:35]
	s_waitcnt vmcnt(8)
	s_waitcnt lgkmcnt(0)
	s_barrier
	s_setprio 1
	s_waitcnt lgkmcnt(0)
	v_mfma_f32_16x16x32_bf16 v[60:63], v[144:147], v[182:185], v[60:63]
	v_mfma_f32_16x16x32_bf16 v[56:59], v[158:161], v[182:185], v[56:59]
	v_mfma_f32_16x16x32_bf16 v[48:51], v[144:147], v[192:195], v[48:51]
	v_mfma_f32_16x16x32_bf16 v[40:43], v[158:161], v[192:195], v[40:43]
	v_mfma_f32_16x16x32_bf16 v[32:35], v[144:147], v[200:203], v[32:35]
	v_mfma_f32_16x16x32_bf16 v[24:27], v[158:161], v[200:203], v[24:27]
	v_mfma_f32_16x16x32_bf16 v[16:19], v[144:147], v[208:211], v[16:19]
	v_mfma_f32_16x16x32_bf16 v[8:11], v[158:161], v[208:211], v[8:11]
	v_mfma_f32_16x16x32_bf16 v[60:63], v[154:157], v[188:191], v[60:63]
	v_mfma_f32_16x16x32_bf16 v[56:59], v[162:165], v[188:191], v[56:59]
	v_mfma_f32_16x16x32_bf16 v[48:51], v[154:157], v[196:199], v[48:51]
	v_mfma_f32_16x16x32_bf16 v[40:43], v[162:165], v[196:199], v[40:43]
	v_mfma_f32_16x16x32_bf16 v[32:35], v[154:157], v[204:207], v[32:35]
	v_mfma_f32_16x16x32_bf16 v[24:27], v[162:165], v[204:207], v[24:27]
	v_mfma_f32_16x16x32_bf16 v[16:19], v[154:157], v[212:215], v[16:19]
	v_mfma_f32_16x16x32_bf16 v[8:11], v[162:165], v[212:215], v[8:11]
	s_setprio 0
	s_setprio 1
	v_mfma_f32_16x16x32_bf16 v[52:55], v[166:169], v[182:185], v[52:55]
	v_mfma_f32_16x16x32_bf16 v[44:47], v[174:177], v[182:185], v[44:47]
	v_mfma_f32_16x16x32_bf16 v[36:39], v[166:169], v[192:195], v[36:39]
	v_mfma_f32_16x16x32_bf16 v[28:31], v[174:177], v[192:195], v[28:31]
	v_mfma_f32_16x16x32_bf16 v[20:23], v[166:169], v[200:203], v[20:23]
	v_mfma_f32_16x16x32_bf16 v[12:15], v[174:177], v[200:203], v[12:15]
	v_mfma_f32_16x16x32_bf16 v[4:7], v[166:169], v[208:211], v[4:7]
	v_mfma_f32_16x16x32_bf16 v[0:3], v[174:177], v[208:211], v[0:3]
	v_mfma_f32_16x16x32_bf16 v[52:55], v[170:173], v[188:191], v[52:55]
	v_mfma_f32_16x16x32_bf16 v[44:47], v[178:181], v[188:191], v[44:47]
	v_mfma_f32_16x16x32_bf16 v[36:39], v[170:173], v[196:199], v[36:39]
	v_mfma_f32_16x16x32_bf16 v[28:31], v[178:181], v[196:199], v[28:31]
	v_mfma_f32_16x16x32_bf16 v[20:23], v[170:173], v[204:207], v[20:23]
	v_mfma_f32_16x16x32_bf16 v[12:15], v[178:181], v[204:207], v[12:15]
	v_mfma_f32_16x16x32_bf16 v[4:7], v[170:173], v[212:215], v[4:7]
	v_mfma_f32_16x16x32_bf16 v[0:3], v[178:181], v[212:215], v[0:3]
	s_setprio 0
	s_barrier
; #define PG8_STAGE(bufoff, gbase, voff) do { _Pragma("unroll") for (int _i = 0; _i < 2; ++_i) \
;         __builtin_amdgcn_global_load_lds((const unsigned*)((const char*)(gbase) + (voff)[_i]), (PG8_LAS unsigned*)(lds + (bufoff) + ldsw + _i * 8192), 16, 0, 0); } while (0)
; #define PG8_LDA(dst, b, h) do { _Pragma("unroll") for (int m = 0; m < 4; ++m) _Pragma("unroll") for (int k = 0; k < 2; ++k) dst[m][k] = *(const PG8_LAS bf16x8*)(lds + PG8_SA(b, h) + aoff + m * 2048 + k * 1024); } while (0)
; #define PG8_LDB(dst, b, h) do { _Pragma("unroll") for (int n = 0; n < 2; ++n) _Pragma("unroll") for (int k = 0; k < 2; ++k) dst[n][k] = *(const PG8_LAS bf16x8*)(lds + PG8_SB(b, h) + boff + n * 2048 + k * 1024); } while (0)
; #define PG8_MMA(ai, bj, At, Bt) do { __builtin_amdgcn_s_setprio(1); _Pragma("unroll") for (int m = 0; m < 4; ++m) _Pragma("unroll") for (int n = 0; n < 2; ++n) _Pragma("unroll") for (int k = 0; k < 2; ++k) \
;         acc[ai][bj][m][n] = __builtin_amdgcn_mfma_f32_16x16x32_bf16(Bt[n][k], At[m][k], acc[ai][bj][m][n], 0, 0, 0); __builtin_amdgcn_s_setprio(0); } while (0)
; #define PG8_WAIT_V(n) asm volatile("s_waitcnt vmcnt(" #n ")" ::: "memory")
; #define PG8_WAIT_L(n) asm volatile("s_waitcnt lgkmcnt(" #n ")" ::: "memory")
; #define PG8_BAR __builtin_amdgcn_s_barrier()
; #define PG8_SCHED __builtin_amdgcn_sched_barrier(0)
; template <class Epi, class Sched, bool ALIGN_EPI = false, bool SP2 = false>
; __device__ __forceinline__ void gemm_phase(PG8_LAS unsigned char* lds, const Gemm g, const Sched& S, const Epi& E) {
;     ...
;             PG8_LDB(B0, 1, 0); PG8_LDB(B1, 1, 1); PG8_SCHED; PG8_LDA(At, 1, 0); PG8_STAGE(PG8_SA(0, 1), a2 + hstep, voffA);
;             PG8_WAIT_V(8); PG8_WAIT_L(0); PG8_BAR; PG8_MMA(0, 0, At, B0); PG8_MMA(0, 1, At, B1); PG8_BAR; PG8_SCHED;
;             PG8_LDA(At, 1, 1); PG8_STAGE(PG8_SB(1, 0), b3, voffB); PG8_STAGE(PG8_SB(1, 1), b3 + hstep, voffB); PG8_STAGE(PG8_SA(1, 0), a3, voffA);
;             PG8_WAIT_V(8); PG8_WAIT_L(0); PG8_BAR; PG8_MMA(1, 0, At, B0); PG8_MMA(1, 1, At, B1); PG8_BAR; PG8_SCHED;
	s_add_i32 s54, 0, 0x18000
	s_add_i32 s55, 0, 0x1c000
	v_add_u32_e32 v162, s54, v150
	v_add_u32_e32 v178, s55, v150
	ds_read_b128 v[144:147], v162
	ds_read_b128 v[154:157], v162 offset:1024
	ds_read_b128 v[158:161], v162 offset:2048
	ds_read_b128 v[162:165], v162 offset:3072
	ds_read_b128 v[166:169], v178
	ds_read_b128 v[170:173], v178 offset:1024
	ds_read_b128 v[174:177], v178 offset:2048
	ds_read_b128 v[178:181], v178 offset:3072
	s_add_u32 s34, s34, 0x200000
	s_addc_u32 s35, s35, 0
	s_mov_b32 m0, s37
	ds_read_b128 v[182:185], v153 offset:32768
	ds_read_b128 v[188:191], v153 offset:33792
	ds_read_b128 v[192:195], v153 offset:34816
	ds_read_b128 v[196:199], v153 offset:35840
	ds_read_b128 v[200:203], v153 offset:36864
	ds_read_b128 v[204:207], v153 offset:37888
	ds_read_b128 v[208:211], v153 offset:38912
	ds_read_b128 v[212:215], v153 offset:39936
	global_load_lds_dwordx4 v128, s[34:35]
	s_mov_b32 m0, s38
	s_nop 0
	global_load_lds_dwordx4 v132, s[34:35]
	s_waitcnt vmcnt(8)
	s_waitcnt lgkmcnt(0)
	s_barrier
	s_setprio 1
	s_waitcnt lgkmcnt(0)
	v_mfma_f32_16x16x32_bf16 v[124:127], v[144:147], v[182:185], v[124:127]
	v_mfma_f32_16x16x32_bf16 v[120:123], v[158:161], v[182:185], v[120:123]
	v_mfma_f32_16x16x32_bf16 v[112:115], v[144:147], v[192:195], v[112:115]
	v_mfma_f32_16x16x32_bf16 v[104:107], v[158:161], v[192:195], v[104:107]
	v_mfma_f32_16x16x32_bf16 v[96:99], v[144:147], v[200:203], v[96:99]
	v_mfma_f32_16x16x32_bf16 v[88:91], v[158:161], v[200:203], v[88:91]
	v_mfma_f32_16x16x32_bf16 v[80:83], v[144:147], v[208:211], v[80:83]
	v_mfma_f32_16x16x32_bf16 v[72:75], v[158:161], v[208:211], v[72:75]
	v_mfma_f32_16x16x32_bf16 v[124:127], v[154:157], v[188:191], v[124:127]
	v_mfma_f32_16x16x32_bf16 v[120:123], v[162:165], v[188:191], v[120:123]
	v_mfma_f32_16x16x32_bf16 v[112:115], v[154:157], v[196:199], v[112:115]
	v_mfma_f32_16x16x32_bf16 v[104:107], v[162:165], v[196:199], v[104:107]
	v_mfma_f32_16x16x32_bf16 v[96:99], v[154:157], v[204:207], v[96:99]
	v_mfma_f32_16x16x32_bf16 v[88:91], v[162:165], v[204:207], v[88:91]
	v_mfma_f32_16x16x32_bf16 v[80:83], v[154:157], v[212:215], v[80:83]
	v_mfma_f32_16x16x32_bf16 v[72:75], v[162:165], v[212:215], v[72:75]
	s_setprio 0
	s_setprio 1
	v_mfma_f32_16x16x32_bf16 v[116:119], v[166:169], v[182:185], v[116:119]
	v_mfma_f32_16x16x32_bf16 v[108:111], v[174:177], v[182:185], v[108:111]
	v_mfma_f32_16x16x32_bf16 v[100:103], v[166:169], v[192:195], v[100:103]
	v_mfma_f32_16x16x32_bf16 v[92:95], v[174:177], v[192:195], v[92:95]
	v_mfma_f32_16x16x32_bf16 v[84:87], v[166:169], v[200:203], v[84:87]
	v_mfma_f32_16x16x32_bf16 v[76:79], v[174:177], v[200:203], v[76:79]
	v_mfma_f32_16x16x32_bf16 v[68:71], v[166:169], v[208:211], v[68:71]
	v_mfma_f32_16x16x32_bf16 v[64:67], v[174:177], v[208:211], v[64:67]
	v_mfma_f32_16x16x32_bf16 v[116:119], v[170:173], v[188:191], v[116:119]
	v_mfma_f32_16x16x32_bf16 v[108:111], v[178:181], v[188:191], v[108:111]
	v_mfma_f32_16x16x32_bf16 v[100:103], v[170:173], v[196:199], v[100:103]
	v_mfma_f32_16x16x32_bf16 v[92:95], v[178:181], v[196:199], v[92:95]
	v_mfma_f32_16x16x32_bf16 v[84:87], v[170:173], v[204:207], v[84:87]
	v_mfma_f32_16x16x32_bf16 v[76:79], v[178:181], v[204:207], v[76:79]
	v_mfma_f32_16x16x32_bf16 v[68:71], v[170:173], v[212:215], v[68:71]
	v_mfma_f32_16x16x32_bf16 v[64:67], v[178:181], v[212:215], v[64:67]
	s_setprio 0
	s_barrier
	s_add_i32 s34, s54, s1
	s_mov_b32 m0, s34
	ds_read_b128 v[182:185], v153 offset:49152
	ds_read_b128 v[188:191], v153 offset:50176
	ds_read_b128 v[192:195], v153 offset:51200
	ds_read_b128 v[196:199], v153 offset:52224
	ds_read_b128 v[200:203], v153 offset:53248
	ds_read_b128 v[204:207], v153 offset:54272
	ds_read_b128 v[208:211], v153 offset:55296
	ds_read_b128 v[212:215], v153 offset:56320
	global_load_lds_dwordx4 v130, s[98:99]
	s_add_i32 m0, s34, 0x2000
	s_add_u32 s30, s30, 0x200080
	s_addc_u32 s31, s31, 0
	s_add_i32 s34, s55, s1
	global_load_lds_dwordx4 v134, s[98:99]
	s_mov_b32 m0, s34
	s_nop 0
	global_load_lds_dwordx4 v130, s[30:31]
	s_add_i32 m0, s34, 0x2000
	s_nop 0
	global_load_lds_dwordx4 v134, s[30:31]
	s_mov_b32 m0, s40
	s_nop 0
	global_load_lds_dwordx4 v128, s[100:101]
	s_mov_b32 m0, s41
	s_nop 0
	global_load_lds_dwordx4 v132, s[100:101]
	s_waitcnt vmcnt(8)
	s_waitcnt lgkmcnt(0)
	s_barrier
	s_setprio 1
	s_waitcnt lgkmcnt(0)
	v_mfma_f32_16x16x32_bf16 v[60:63], v[144:147], v[182:185], v[60:63]
	v_mfma_f32_16x16x32_bf16 v[56:59], v[158:161], v[182:185], v[56:59]
	v_mfma_f32_16x16x32_bf16 v[48:51], v[144:147], v[192:195], v[48:51]
	v_mfma_f32_16x16x32_bf16 v[40:43], v[158:161], v[192:195], v[40:43]
	v_mfma_f32_16x16x32_bf16 v[32:35], v[144:147], v[200:203], v[32:35]
	v_mfma_f32_16x16x32_bf16 v[24:27], v[158:161], v[200:203], v[24:27]
	v_mfma_f32_16x16x32_bf16 v[16:19], v[144:147], v[208:211], v[16:19]
	v_mfma_f32_16x16x32_bf16 v[8:11], v[158:161], v[208:211], v[8:11]
	v_mfma_f32_16x16x32_bf16 v[60:63], v[154:157], v[188:191], v[60:63]
	v_mfma_f32_16x16x32_bf16 v[56:59], v[162:165], v[188:191], v[56:59]
	v_mfma_f32_16x16x32_bf16 v[48:51], v[154:157], v[196:199], v[48:51]
	v_mfma_f32_16x16x32_bf16 v[40:43], v[162:165], v[196:199], v[40:43]
	v_mfma_f32_16x16x32_bf16 v[32:35], v[154:157], v[204:207], v[32:35]
	v_mfma_f32_16x16x32_bf16 v[24:27], v[162:165], v[204:207], v[24:27]
	v_mfma_f32_16x16x32_bf16 v[16:19], v[154:157], v[212:215], v[16:19]
	v_mfma_f32_16x16x32_bf16 v[8:11], v[162:165], v[212:215], v[8:11]
	s_setprio 0
	s_setprio 1
	v_mfma_f32_16x16x32_bf16 v[52:55], v[166:169], v[182:185], v[52:55]
	v_mfma_f32_16x16x32_bf16 v[44:47], v[174:177], v[182:185], v[44:47]
	v_mfma_f32_16x16x32_bf16 v[36:39], v[166:169], v[192:195], v[36:39]
	v_mfma_f32_16x16x32_bf16 v[28:31], v[174:177], v[192:195], v[28:31]
	v_mfma_f32_16x16x32_bf16 v[20:23], v[166:169], v[200:203], v[20:23]
	v_mfma_f32_16x16x32_bf16 v[12:15], v[174:177], v[200:203], v[12:15]
	v_mfma_f32_16x16x32_bf16 v[4:7], v[166:169], v[208:211], v[4:7]
	v_mfma_f32_16x16x32_bf16 v[0:3], v[174:177], v[208:211], v[0:3]
	v_mfma_f32_16x16x32_bf16 v[52:55], v[170:173], v[188:191], v[52:55]
	v_mfma_f32_16x16x32_bf16 v[44:47], v[178:181], v[188:191], v[44:47]
	v_mfma_f32_16x16x32_bf16 v[36:39], v[170:173], v[196:199], v[36:39]
	v_mfma_f32_16x16x32_bf16 v[28:31], v[178:181], v[196:199], v[28:31]
	v_mfma_f32_16x16x32_bf16 v[20:23], v[170:173], v[204:207], v[20:23]
	v_mfma_f32_16x16x32_bf16 v[12:15], v[178:181], v[204:207], v[12:15]
	v_mfma_f32_16x16x32_bf16 v[4:7], v[170:173], v[212:215], v[4:7]
	v_mfma_f32_16x16x32_bf16 v[0:3], v[178:181], v[212:215], v[0:3]
	s_setprio 0
	s_barrier
	s_add_i32 s51, s51, 2
	s_add_u32 s28, s28, 0x100
	s_addc_u32 s29, s29, 0
	s_add_u32 s49, s49, 0x100
	s_addc_u32 s50, s50, 0
	s_cmpk_gt_u32 s51, 0x7d
	s_cbranch_scc0 .LBB0_803
	s_and_b64 vcc, exec, s[16:17]
	s_cbranch_vccz .LBB0_806
	s_barrier

; __device__ __forceinline__ u32x4 pack8(const f32x4 a, const f32x4 b) { u32x4 w; w.x = cvt_pk_bf16(a[0], a[1]); w.y = cvt_pk_bf16(a[2], a[3]); w.z = cvt_pk_bf16(b[0], b[1]); w.w = cvt_pk_bf16(b[2], b[3]); return w; }
; __device__ __forceinline__ float dot4(const f32x4 a) { return (a[0] * a[0] + a[1] * a[1]) + (a[2] * a[2] + a[3] * a[3]); }
;     __device__ __forceinline__ void operator()(const f32x4 (&acc)[2][2][4][2], const Unit& u, int wr, int wc, int fr, int fq) const {
;         asm volatile("" : "+v"(fr), "+v"(fq));
; #pragma unroll
;         for (int ai = 0; ai < 2; ++ai)
; #pragma unroll
;             for (int m = 0; m < 4; ++m) {
;                 const int row = u.pm * BM + ai * HALF + wr * 64 + m * 16 + fr; float ss = 0.f;
; #pragma unroll
;                 for (int bj = 0; bj < 2; ++bj) {
;                     const int col = u.pn * BM + bj * HALF + wc * 32 + 8 * fq; const size_t off = (size_t)row * 2048 + col;
;                     const f32x4 h0 = *(const f32x4*)(x + off) + acc[ai][bj][m][0], h1 = *(const f32x4*)(x + off + 4) + acc[ai][bj][m][1];
;                     *(u32x4*)(HR + off) = pack8(h0, h1);
;                     ss += dot4(h0) + dot4(h1);
;                 }
;                 ss += __shfl_xor(ss, 16); ss += __shfl_xor(ss, 32);
;                 if (fq == 0) atomicAdd(ssq + row, ss);
;             }
.LBB0_833:
	v_mov_b32_e32 v144, v150
	v_mov_b32_e32 v157, v151
	s_lshl_b32 s7, s26, 8
	s_add_i32 s7, s7, s39
	s_lshl_b32 s6, s6, 8
	v_add_u32_e32 v144, s7, v144
	s_or_b32 s6, s6, s40
	v_ashrrev_i32_e32 v145, 31, v144
	v_lshl_add_u32 v146, v157, 3, s6
	v_cmp_eq_u32_e32 vcc, 0, v157
	v_lshlrev_b32_e32 v183, 2, v146
	v_lshl_add_u32 v147, v144, 13, v183
	v_lshlrev_b32_e32 v183, 1, v146
	v_lshl_add_u32 v148, v144, 12, v183
	v_lshlrev_b32_e32 v149, 2, v144
	v_add_u32_e32 v184, 0x0, v147
	global_load_dwordx4 v[158:161], v184, s[52:53] offset:0
	global_load_dwordx4 v[162:165], v184, s[52:53] offset:16
	v_add_u32_e32 v184, 0x0, v147
	global_load_dwordx4 v[166:169], v184, s[52:53] offset:512
	global_load_dwordx4 v[170:173], v184, s[52:53] offset:528
	v_add_u32_e32 v184, 0x20000, v147
	global_load_dwordx4 v[174:177], v184, s[52:53] offset:0
	global_load_dwordx4 v[178:181], v184, s[52:53] offset:16
	v_add_u32_e32 v184, 0x20000, v147
	global_load_dwordx4 v[188:191], v184, s[52:53] offset:512
	global_load_dwordx4 v[192:195], v184, s[52:53] offset:528
	v_add_u32_e32 v184, 0x40000, v147
	global_load_dwordx4 v[196:199], v184, s[52:53] offset:0
	global_load_dwordx4 v[200:203], v184, s[52:53] offset:16
	v_add_u32_e32 v184, 0x40000, v147
	global_load_dwordx4 v[204:207], v184, s[52:53] offset:512
	global_load_dwordx4 v[208:211], v184, s[52:53] offset:528
	v_add_u32_e32 v184, 0x60000, v147
	global_load_dwordx4 v[212:215], v184, s[52:53] offset:0
	global_load_dwordx4 v[216:219], v184, s[52:53] offset:16
	v_xor_b32_e32 v144, 16, v156
	v_lshlrev_b32_e32 v144, 2, v144
	v_xor_b32_e32 v145, 32, v156
	v_lshlrev_b32_e32 v145, 2, v145
	s_waitcnt vmcnt(12)
	v_pk_add_f32 v[124:125], v[124:125], v[158:159]
	v_pk_add_f32 v[126:127], v[126:127], v[160:161]
	v_pk_add_f32 v[120:121], v[120:121], v[162:163]
	v_pk_add_f32 v[122:123], v[122:123], v[164:165]
	v_mul_f32_e32 v162, v125, v125
	v_mul_f32_e32 v163, v127, v127
	v_mul_f32_e32 v164, v121, v121
	v_mul_f32_e32 v165, v123, v123
	v_cvt_pk_bf16_f32 v158, v124, v125
	v_cvt_pk_bf16_f32 v159, v126, v127
	v_cvt_pk_bf16_f32 v160, v120, v121
	v_cvt_pk_bf16_f32 v161, v122, v123
	v_fmac_f32_e32 v162, v124, v124
	v_fmac_f32_e32 v163, v126, v126
	v_fmac_f32_e32 v164, v120, v120
	v_fmac_f32_e32 v165, v122, v122
	v_add_u32_e32 v185, 0x0, v148
	global_store_dwordx4 v185, v[158:161], s[8:9] offset:0
	v_add_f32_e32 v162, v162, v163
	v_add_f32_e32 v164, v164, v165
	v_add_f32_e32 v182, v162, v164
	v_add_u32_e32 v184, 0x60000, v147
	global_load_dwordx4 v[158:161], v184, s[52:53] offset:512
	global_load_dwordx4 v[162:165], v184, s[52:53] offset:528
	s_waitcnt vmcnt(13)
	v_pk_add_f32 v[116:117], v[116:117], v[166:167]
	v_pk_add_f32 v[118:119], v[118:119], v[168:169]
	v_pk_add_f32 v[112:113], v[112:113], v[170:171]
	v_pk_add_f32 v[114:115], v[114:115], v[172:173]
	v_mul_f32_e32 v170, v117, v117
	v_mul_f32_e32 v171, v119, v119
	v_mul_f32_e32 v172, v113, v113
	v_mul_f32_e32 v173, v115, v115
	v_cvt_pk_bf16_f32 v166, v116, v117
	v_cvt_pk_bf16_f32 v167, v118, v119
	v_cvt_pk_bf16_f32 v168, v112, v113
	v_cvt_pk_bf16_f32 v169, v114, v115
	v_fmac_f32_e32 v170, v116, v116
	v_fmac_f32_e32 v171, v118, v118
	v_fmac_f32_e32 v172, v112, v112
	v_fmac_f32_e32 v173, v114, v114
	v_add_u32_e32 v185, 0x0, v148
	global_store_dwordx4 v185, v[166:169], s[8:9] offset:256
	v_add_f32_e32 v170, v170, v171
	v_add_f32_e32 v172, v172, v173
	v_add_f32_e32 v170, v170, v172
	v_add_f32_e32 v182, v182, v170
	ds_bpermute_b32 v183, v144, v182
	v_add_u32_e32 v146, 0x0, v149
	s_waitcnt lgkmcnt(0)
	v_add_f32_e32 v182, v182, v183
	ds_bpermute_b32 v183, v145, v182
	s_waitcnt lgkmcnt(0)
	v_add_f32_e32 v182, v182, v183
	s_and_saveexec_b64 s[6:7], vcc
	global_atomic_add_f32 v146, v182, s[94:95]
	s_or_b64 exec, exec, s[6:7]
	v_add_u32_e32 v184, 0x100000, v147
	global_load_dwordx4 v[166:169], v184, s[52:53] offset:0
	global_load_dwordx4 v[170:173], v184, s[52:53] offset:16
	s_waitcnt vmcnt(15)
	v_pk_add_f32 v[108:109], v[108:109], v[174:175]
	v_pk_add_f32 v[110:111], v[110:111], v[176:177]
	v_pk_add_f32 v[104:105], v[104:105], v[178:179]
	v_pk_add_f32 v[106:107], v[106:107], v[180:181]
	v_mul_f32_e32 v178, v109, v109
	v_mul_f32_e32 v179, v111, v111
	v_mul_f32_e32 v180, v105, v105
	v_mul_f32_e32 v181, v107, v107
	v_cvt_pk_bf16_f32 v174, v108, v109
	v_cvt_pk_bf16_f32 v175, v110, v111
	v_cvt_pk_bf16_f32 v176, v104, v105
	v_cvt_pk_bf16_f32 v177, v106, v107
	v_fmac_f32_e32 v178, v108, v108
	v_fmac_f32_e32 v179, v110, v110
	v_fmac_f32_e32 v180, v104, v104
	v_fmac_f32_e32 v181, v106, v106
	v_add_u32_e32 v185, 0x10000, v148
	global_store_dwordx4 v185, v[174:177], s[8:9] offset:0
	v_add_f32_e32 v178, v178, v179
	v_add_f32_e32 v180, v180, v181
	v_add_f32_e32 v182, v178, v180
	v_add_u32_e32 v184, 0x100000, v147
	global_load_dwordx4 v[174:177], v184, s[52:53] offset:512
	global_load_dwordx4 v[178:181], v184, s[52:53] offset:528
	s_waitcnt vmcnt(16)
	v_pk_add_f32 v[100:101], v[100:101], v[188:189]
	v_pk_add_f32 v[102:103], v[102:103], v[190:191]
	v_pk_add_f32 v[96:97], v[96:97], v[192:193]
	v_pk_add_f32 v[98:99], v[98:99], v[194:195]
	v_mul_f32_e32 v192, v101, v101
	v_mul_f32_e32 v193, v103, v103
	v_mul_f32_e32 v194, v97, v97
	v_mul_f32_e32 v195, v99, v99
	v_cvt_pk_bf16_f32 v188, v100, v101
	v_cvt_pk_bf16_f32 v189, v102, v103
	v_cvt_pk_bf16_f32 v190, v96, v97
	v_cvt_pk_bf16_f32 v191, v98, v99
	v_fmac_f32_e32 v192, v100, v100
	v_fmac_f32_e32 v193, v102, v102
	v_fmac_f32_e32 v194, v96, v96
	v_fmac_f32_e32 v195, v98, v98
	v_add_u32_e32 v185, 0x10000, v148
	global_store_dwordx4 v185, v[188:191], s[8:9] offset:256
	v_add_f32_e32 v192, v192, v193
	v_add_f32_e32 v194, v194, v195
	v_add_f32_e32 v192, v192, v194
	v_add_f32_e32 v182, v182, v192
	ds_bpermute_b32 v183, v144, v182
	v_add_u32_e32 v146, 0x40, v149
	s_waitcnt lgkmcnt(0)
; __device__ __forceinline__ u32x4 pack8(const f32x4 a, const f32x4 b) { u32x4 w; w.x = cvt_pk_bf16(a[0], a[1]); w.y = cvt_pk_bf16(a[2], a[3]); w.z = cvt_pk_bf16(b[0], b[1]); w.w = cvt_pk_bf16(b[2], b[3]); return w; }
; __device__ __forceinline__ float dot4(const f32x4 a) { return (a[0] * a[0] + a[1] * a[1]) + (a[2] * a[2] + a[3] * a[3]); }
;     __device__ __forceinline__ void operator()(const f32x4 (&acc)[2][2][4][2], const Unit& u, int wr, int wc, int fr, int fq) const {
;         asm volatile("" : "+v"(fr), "+v"(fq));
; #pragma unroll
;         for (int ai = 0; ai < 2; ++ai)
; #pragma unroll
;             for (int m = 0; m < 4; ++m) {
;                 const int row = u.pm * BM + ai * HALF + wr * 64 + m * 16 + fr; float ss = 0.f;
; #pragma unroll
;                 for (int bj = 0; bj < 2; ++bj) {
;                     const int col = u.pn * BM + bj * HALF + wc * 32 + 8 * fq; const size_t off = (size_t)row * 2048 + col;
;                     const f32x4 h0 = *(const f32x4*)(x + off) + acc[ai][bj][m][0], h1 = *(const f32x4*)(x + off + 4) + acc[ai][bj][m][1];
;                     *(u32x4*)(HR + off) = pack8(h0, h1);
;                     ss += dot4(h0) + dot4(h1);
;                 }
;                 ss += __shfl_xor(ss, 16); ss += __shfl_xor(ss, 32);
;                 if (fq == 0) atomicAdd(ssq + row, ss);
;             }
	v_add_f32_e32 v182, v182, v183
	ds_bpermute_b32 v183, v145, v182
	s_waitcnt lgkmcnt(0)
	v_add_f32_e32 v182, v182, v183
	s_and_saveexec_b64 s[6:7], vcc
	global_atomic_add_f32 v146, v182, s[94:95]
	s_or_b64 exec, exec, s[6:7]
	v_add_u32_e32 v184, 0x120000, v147
	global_load_dwordx4 v[188:191], v184, s[52:53] offset:0
	global_load_dwordx4 v[192:195], v184, s[52:53] offset:16
	s_waitcnt vmcnt(18)
	v_pk_add_f32 v[92:93], v[92:93], v[196:197]
	v_pk_add_f32 v[94:95], v[94:95], v[198:199]
	v_pk_add_f32 v[88:89], v[88:89], v[200:201]
	v_pk_add_f32 v[90:91], v[90:91], v[202:203]
	v_mul_f32_e32 v200, v93, v93
	v_mul_f32_e32 v201, v95, v95
	v_mul_f32_e32 v202, v89, v89
	v_mul_f32_e32 v203, v91, v91
	v_cvt_pk_bf16_f32 v196, v92, v93
	v_cvt_pk_bf16_f32 v197, v94, v95
	v_cvt_pk_bf16_f32 v198, v88, v89
	v_cvt_pk_bf16_f32 v199, v90, v91
	v_fmac_f32_e32 v200, v92, v92
	v_fmac_f32_e32 v201, v94, v94
	v_fmac_f32_e32 v202, v88, v88
	v_fmac_f32_e32 v203, v90, v90
	v_add_u32_e32 v185, 0x20000, v148
	global_store_dwordx4 v185, v[196:199], s[8:9] offset:0
	v_add_f32_e32 v200, v200, v201
	v_add_f32_e32 v202, v202, v203
	v_add_f32_e32 v182, v200, v202
	v_add_u32_e32 v184, 0x120000, v147
	global_load_dwordx4 v[196:199], v184, s[52:53] offset:512
	global_load_dwordx4 v[200:203], v184, s[52:53] offset:528
	s_waitcnt vmcnt(19)
	v_pk_add_f32 v[84:85], v[84:85], v[204:205]
	v_pk_add_f32 v[86:87], v[86:87], v[206:207]
	v_pk_add_f32 v[80:81], v[80:81], v[208:209]
	v_pk_add_f32 v[82:83], v[82:83], v[210:211]
	v_mul_f32_e32 v208, v85, v85
	v_mul_f32_e32 v209, v87, v87
	v_mul_f32_e32 v210, v81, v81
	v_mul_f32_e32 v211, v83, v83
	v_cvt_pk_bf16_f32 v204, v84, v85
	v_cvt_pk_bf16_f32 v205, v86, v87
	v_cvt_pk_bf16_f32 v206, v80, v81
	v_cvt_pk_bf16_f32 v207, v82, v83
	v_fmac_f32_e32 v208, v84, v84
	v_fmac_f32_e32 v209, v86, v86
	v_fmac_f32_e32 v210, v80, v80
	v_fmac_f32_e32 v211, v82, v82
	v_add_u32_e32 v185, 0x20000, v148
	global_store_dwordx4 v185, v[204:207], s[8:9] offset:256
	v_add_f32_e32 v208, v208, v209
	v_add_f32_e32 v210, v210, v211
	v_add_f32_e32 v208, v208, v210
	v_add_f32_e32 v182, v182, v208
	ds_bpermute_b32 v183, v144, v182
	v_add_u32_e32 v146, 0x80, v149
	s_waitcnt lgkmcnt(0)
	v_add_f32_e32 v182, v182, v183
	ds_bpermute_b32 v183, v145, v182
	s_waitcnt lgkmcnt(0)
	v_add_f32_e32 v182, v182, v183
	s_and_saveexec_b64 s[6:7], vcc
	global_atomic_add_f32 v146, v182, s[94:95]
	s_or_b64 exec, exec, s[6:7]
	v_add_u32_e32 v184, 0x140000, v147
	global_load_dwordx4 v[204:207], v184, s[52:53] offset:0
	global_load_dwordx4 v[208:211], v184, s[52:53] offset:16
	s_waitcnt vmcnt(21)
	v_pk_add_f32 v[76:77], v[76:77], v[212:213]
	v_pk_add_f32 v[78:79], v[78:79], v[214:215]
	v_pk_add_f32 v[72:73], v[72:73], v[216:217]
	v_pk_add_f32 v[74:75], v[74:75], v[218:219]
	v_mul_f32_e32 v216, v77, v77
	v_mul_f32_e32 v217, v79, v79
	v_mul_f32_e32 v218, v73, v73
	v_mul_f32_e32 v219, v75, v75
	v_cvt_pk_bf16_f32 v212, v76, v77
	v_cvt_pk_bf16_f32 v213, v78, v79
	v_cvt_pk_bf16_f32 v214, v72, v73
	v_cvt_pk_bf16_f32 v215, v74, v75
	v_fmac_f32_e32 v216, v76, v76
	v_fmac_f32_e32 v217, v78, v78
	v_fmac_f32_e32 v218, v72, v72
	v_fmac_f32_e32 v219, v74, v74
	v_add_u32_e32 v185, 0x30000, v148
	global_store_dwordx4 v185, v[212:215], s[8:9] offset:0
	v_add_f32_e32 v216, v216, v217
	v_add_f32_e32 v218, v218, v219
	v_add_f32_e32 v182, v216, v218
	v_add_u32_e32 v184, 0x140000, v147
	global_load_dwordx4 v[212:215], v184, s[52:53] offset:512
	global_load_dwordx4 v[216:219], v184, s[52:53] offset:528
	s_waitcnt vmcnt(21)
	v_pk_add_f32 v[68:69], v[68:69], v[158:159]
	v_pk_add_f32 v[70:71], v[70:71], v[160:161]
	v_pk_add_f32 v[64:65], v[64:65], v[162:163]
	v_pk_add_f32 v[66:67], v[66:67], v[164:165]
	v_mul_f32_e32 v162, v69, v69
	v_mul_f32_e32 v163, v71, v71
	v_mul_f32_e32 v164, v65, v65
	v_mul_f32_e32 v165, v67, v67
	v_cvt_pk_bf16_f32 v158, v68, v69
	v_cvt_pk_bf16_f32 v159, v70, v71
	v_cvt_pk_bf16_f32 v160, v64, v65
	v_cvt_pk_bf16_f32 v161, v66, v67
	v_fmac_f32_e32 v162, v68, v68
	v_fmac_f32_e32 v163, v70, v70
	v_fmac_f32_e32 v164, v64, v64
	v_fmac_f32_e32 v165, v66, v66
	v_add_u32_e32 v185, 0x30000, v148
	global_store_dwordx4 v185, v[158:161], s[8:9] offset:256
	v_add_f32_e32 v162, v162, v163
	v_add_f32_e32 v164, v164, v165
	v_add_f32_e32 v162, v162, v164
	v_add_f32_e32 v182, v182, v162
	ds_bpermute_b32 v183, v144, v182
	v_add_u32_e32 v146, 0xc0, v149
	s_waitcnt lgkmcnt(0)
	v_add_f32_e32 v182, v182, v183
	ds_bpermute_b32 v183, v145, v182
	s_waitcnt lgkmcnt(0)
	v_add_f32_e32 v182, v182, v183
	s_and_saveexec_b64 s[6:7], vcc
	global_atomic_add_f32 v146, v182, s[94:95]
	s_or_b64 exec, exec, s[6:7]
	v_add_u32_e32 v184, 0x160000, v147
	global_load_dwordx4 v[158:161], v184, s[52:53] offset:0
	global_load_dwordx4 v[162:165], v184, s[52:53] offset:16
	s_waitcnt vmcnt(21)
	v_pk_add_f32 v[60:61], v[60:61], v[166:167]
	v_pk_add_f32 v[62:63], v[62:63], v[168:169]
	v_pk_add_f32 v[56:57], v[56:57], v[170:171]
	v_pk_add_f32 v[58:59], v[58:59], v[172:173]
	v_mul_f32_e32 v170, v61, v61
	v_mul_f32_e32 v171, v63, v63
	v_mul_f32_e32 v172, v57, v57
	v_mul_f32_e32 v173, v59, v59
	v_cvt_pk_bf16_f32 v166, v60, v61
	v_cvt_pk_bf16_f32 v167, v62, v63
	v_cvt_pk_bf16_f32 v168, v56, v57
	v_cvt_pk_bf16_f32 v169, v58, v59
	v_fmac_f32_e32 v170, v60, v60
	v_fmac_f32_e32 v171, v62, v62
	v_fmac_f32_e32 v172, v56, v56
	v_fmac_f32_e32 v173, v58, v58
	v_add_u32_e32 v185, 0x80000, v148
	global_store_dwordx4 v185, v[166:169], s[8:9] offset:0
	v_add_f32_e32 v170, v170, v171
	v_add_f32_e32 v172, v172, v173
	v_add_f32_e32 v182, v170, v172
	v_add_u32_e32 v184, 0x160000, v147
	global_load_dwordx4 v[166:169], v184, s[52:53] offset:512
	global_load_dwordx4 v[170:173], v184, s[52:53] offset:528
	s_waitcnt vmcnt(21)
; __device__ __forceinline__ u32x4 pack8(const f32x4 a, const f32x4 b) { u32x4 w; w.x = cvt_pk_bf16(a[0], a[1]); w.y = cvt_pk_bf16(a[2], a[3]); w.z = cvt_pk_bf16(b[0], b[1]); w.w = cvt_pk_bf16(b[2], b[3]); return w; }
; __device__ __forceinline__ float dot4(const f32x4 a) { return (a[0] * a[0] + a[1] * a[1]) + (a[2] * a[2] + a[3] * a[3]); }
;     __device__ __forceinline__ void operator()(const f32x4 (&acc)[2][2][4][2], const Unit& u, int wr, int wc, int fr, int fq) const {
;         asm volatile("" : "+v"(fr), "+v"(fq));
; #pragma unroll
;         for (int ai = 0; ai < 2; ++ai)
; #pragma unroll
;             for (int m = 0; m < 4; ++m) {
;                 const int row = u.pm * BM + ai * HALF + wr * 64 + m * 16 + fr; float ss = 0.f;
; #pragma unroll
;                 for (int bj = 0; bj < 2; ++bj) {
;                     const int col = u.pn * BM + bj * HALF + wc * 32 + 8 * fq; const size_t off = (size_t)row * 2048 + col;
;                     const f32x4 h0 = *(const f32x4*)(x + off) + acc[ai][bj][m][0], h1 = *(const f32x4*)(x + off + 4) + acc[ai][bj][m][1];
;                     *(u32x4*)(HR + off) = pack8(h0, h1);
;                     ss += dot4(h0) + dot4(h1);
;                 }
;                 ss += __shfl_xor(ss, 16); ss += __shfl_xor(ss, 32);
;                 if (fq == 0) atomicAdd(ssq + row, ss);
;             }
	v_pk_add_f32 v[52:53], v[52:53], v[174:175]
	v_pk_add_f32 v[54:55], v[54:55], v[176:177]
	v_pk_add_f32 v[48:49], v[48:49], v[178:179]
	v_pk_add_f32 v[50:51], v[50:51], v[180:181]
	v_mul_f32_e32 v178, v53, v53
	v_mul_f32_e32 v179, v55, v55
	v_mul_f32_e32 v180, v49, v49
	v_mul_f32_e32 v181, v51, v51
	v_cvt_pk_bf16_f32 v174, v52, v53
	v_cvt_pk_bf16_f32 v175, v54, v55
	v_cvt_pk_bf16_f32 v176, v48, v49
	v_cvt_pk_bf16_f32 v177, v50, v51
	v_fmac_f32_e32 v178, v52, v52
	v_fmac_f32_e32 v179, v54, v54
	v_fmac_f32_e32 v180, v48, v48
	v_fmac_f32_e32 v181, v50, v50
	v_add_u32_e32 v185, 0x80000, v148
	global_store_dwordx4 v185, v[174:177], s[8:9] offset:256
	v_add_f32_e32 v178, v178, v179
	v_add_f32_e32 v180, v180, v181
	v_add_f32_e32 v178, v178, v180
	v_add_f32_e32 v182, v182, v178
	ds_bpermute_b32 v183, v144, v182
	v_add_u32_e32 v146, 0x200, v149
	s_waitcnt lgkmcnt(0)
	v_add_f32_e32 v182, v182, v183
	ds_bpermute_b32 v183, v145, v182
	s_waitcnt lgkmcnt(0)
	v_add_f32_e32 v182, v182, v183
	s_and_saveexec_b64 s[6:7], vcc
	global_atomic_add_f32 v146, v182, s[94:95]
	s_or_b64 exec, exec, s[6:7]
	s_waitcnt vmcnt(19)
	v_pk_add_f32 v[44:45], v[44:45], v[188:189]
	v_pk_add_f32 v[46:47], v[46:47], v[190:191]
	v_pk_add_f32 v[40:41], v[40:41], v[192:193]
	v_pk_add_f32 v[42:43], v[42:43], v[194:195]
	v_mul_f32_e32 v192, v45, v45
	v_mul_f32_e32 v193, v47, v47
	v_mul_f32_e32 v194, v41, v41
	v_mul_f32_e32 v195, v43, v43
	v_cvt_pk_bf16_f32 v188, v44, v45
	v_cvt_pk_bf16_f32 v189, v46, v47
	v_cvt_pk_bf16_f32 v190, v40, v41
	v_cvt_pk_bf16_f32 v191, v42, v43
	v_fmac_f32_e32 v192, v44, v44
	v_fmac_f32_e32 v193, v46, v46
	v_fmac_f32_e32 v194, v40, v40
	v_fmac_f32_e32 v195, v42, v42
	v_add_u32_e32 v185, 0x90000, v148
	global_store_dwordx4 v185, v[188:191], s[8:9] offset:0
	v_add_f32_e32 v192, v192, v193
	v_add_f32_e32 v194, v194, v195
	v_add_f32_e32 v182, v192, v194
	s_waitcnt vmcnt(17)
	v_pk_add_f32 v[36:37], v[36:37], v[196:197]
	v_pk_add_f32 v[38:39], v[38:39], v[198:199]
	v_pk_add_f32 v[32:33], v[32:33], v[200:201]
	v_pk_add_f32 v[34:35], v[34:35], v[202:203]
	v_mul_f32_e32 v200, v37, v37
	v_mul_f32_e32 v201, v39, v39
	v_mul_f32_e32 v202, v33, v33
	v_mul_f32_e32 v203, v35, v35
	v_cvt_pk_bf16_f32 v196, v36, v37
	v_cvt_pk_bf16_f32 v197, v38, v39
	v_cvt_pk_bf16_f32 v198, v32, v33
	v_cvt_pk_bf16_f32 v199, v34, v35
	v_fmac_f32_e32 v200, v36, v36
	v_fmac_f32_e32 v201, v38, v38
	v_fmac_f32_e32 v202, v32, v32
	v_fmac_f32_e32 v203, v34, v34
	v_add_u32_e32 v185, 0x90000, v148
	global_store_dwordx4 v185, v[196:199], s[8:9] offset:256
	v_add_f32_e32 v200, v200, v201
	v_add_f32_e32 v202, v202, v203
	v_add_f32_e32 v200, v200, v202
	v_add_f32_e32 v182, v182, v200
	ds_bpermute_b32 v183, v144, v182
	v_add_u32_e32 v146, 0x240, v149
	s_waitcnt lgkmcnt(0)
	v_add_f32_e32 v182, v182, v183
	ds_bpermute_b32 v183, v145, v182
	s_waitcnt lgkmcnt(0)
	v_add_f32_e32 v182, v182, v183
	s_and_saveexec_b64 s[6:7], vcc
	global_atomic_add_f32 v146, v182, s[94:95]
	s_or_b64 exec, exec, s[6:7]
	s_waitcnt vmcnt(15)
	v_pk_add_f32 v[28:29], v[28:29], v[204:205]
	v_pk_add_f32 v[30:31], v[30:31], v[206:207]
	v_pk_add_f32 v[24:25], v[24:25], v[208:209]
	v_pk_add_f32 v[26:27], v[26:27], v[210:211]
	v_mul_f32_e32 v208, v29, v29
	v_mul_f32_e32 v209, v31, v31
	v_mul_f32_e32 v210, v25, v25
	v_mul_f32_e32 v211, v27, v27
	v_cvt_pk_bf16_f32 v204, v28, v29
	v_cvt_pk_bf16_f32 v205, v30, v31
	v_cvt_pk_bf16_f32 v206, v24, v25
	v_cvt_pk_bf16_f32 v207, v26, v27
	v_fmac_f32_e32 v208, v28, v28
	v_fmac_f32_e32 v209, v30, v30
	v_fmac_f32_e32 v210, v24, v24
	v_fmac_f32_e32 v211, v26, v26
	v_add_u32_e32 v185, 0xa0000, v148
	global_store_dwordx4 v185, v[204:207], s[8:9] offset:0
	v_add_f32_e32 v208, v208, v209
	v_add_f32_e32 v210, v210, v211
	v_add_f32_e32 v182, v208, v210
	s_waitcnt vmcnt(13)
	v_pk_add_f32 v[20:21], v[20:21], v[212:213]
	v_pk_add_f32 v[22:23], v[22:23], v[214:215]
	v_pk_add_f32 v[16:17], v[16:17], v[216:217]
	v_pk_add_f32 v[18:19], v[18:19], v[218:219]
	v_mul_f32_e32 v216, v21, v21
	v_mul_f32_e32 v217, v23, v23
	v_mul_f32_e32 v218, v17, v17
	v_mul_f32_e32 v219, v19, v19
	v_cvt_pk_bf16_f32 v212, v20, v21
	v_cvt_pk_bf16_f32 v213, v22, v23
	v_cvt_pk_bf16_f32 v214, v16, v17
	v_cvt_pk_bf16_f32 v215, v18, v19
	v_fmac_f32_e32 v216, v20, v20
	v_fmac_f32_e32 v217, v22, v22
	v_fmac_f32_e32 v218, v16, v16
	v_fmac_f32_e32 v219, v18, v18
	v_add_u32_e32 v185, 0xa0000, v148
	global_store_dwordx4 v185, v[212:215], s[8:9] offset:256
	v_add_f32_e32 v216, v216, v217
	v_add_f32_e32 v218, v218, v219
	v_add_f32_e32 v216, v216, v218
	v_add_f32_e32 v182, v182, v216
	ds_bpermute_b32 v183, v144, v182
	v_add_u32_e32 v146, 0x280, v149
	s_waitcnt lgkmcnt(0)
	v_add_f32_e32 v182, v182, v183
	ds_bpermute_b32 v183, v145, v182
	s_waitcnt lgkmcnt(0)
	v_add_f32_e32 v182, v182, v183
	s_and_saveexec_b64 s[6:7], vcc
	global_atomic_add_f32 v146, v182, s[94:95]
	s_or_b64 exec, exec, s[6:7]
	s_waitcnt vmcnt(11)
	v_pk_add_f32 v[12:13], v[12:13], v[158:159]
	v_pk_add_f32 v[14:15], v[14:15], v[160:161]
	v_pk_add_f32 v[8:9], v[8:9], v[162:163]
	v_pk_add_f32 v[10:11], v[10:11], v[164:165]
	v_mul_f32_e32 v162, v13, v13
	v_mul_f32_e32 v163, v15, v15
	v_mul_f32_e32 v164, v9, v9
	v_mul_f32_e32 v165, v11, v11
	v_cvt_pk_bf16_f32 v158, v12, v13
	v_cvt_pk_bf16_f32 v159, v14, v15
	v_cvt_pk_bf16_f32 v160, v8, v9
	v_cvt_pk_bf16_f32 v161, v10, v11
	v_fmac_f32_e32 v162, v12, v12
	v_fmac_f32_e32 v163, v14, v14
	v_fmac_f32_e32 v164, v8, v8
	v_fmac_f32_e32 v165, v10, v10
	v_add_u32_e32 v185, 0xb0000, v148
	global_store_dwordx4 v185, v[158:161], s[8:9] offset:0
	v_add_f32_e32 v162, v162, v163
	v_add_f32_e32 v164, v164, v165
	v_add_f32_e32 v182, v162, v164
	s_waitcnt vmcnt(9)
	v_pk_add_f32 v[4:5], v[4:5], v[166:167]
	v_pk_add_f32 v[6:7], v[6:7], v[168:169]
	v_pk_add_f32 v[0:1], v[0:1], v[170:171]
	v_pk_add_f32 v[2:3], v[2:3], v[172:173]
	v_mul_f32_e32 v170, v5, v5
	v_mul_f32_e32 v171, v7, v7
	v_mul_f32_e32 v172, v1, v1
	v_mul_f32_e32 v173, v3, v3
	v_cvt_pk_bf16_f32 v166, v4, v5
	v_cvt_pk_bf16_f32 v167, v6, v7
	v_cvt_pk_bf16_f32 v168, v0, v1
	v_cvt_pk_bf16_f32 v169, v2, v3
	v_fmac_f32_e32 v170, v4, v4
	v_fmac_f32_e32 v171, v6, v6
	v_fmac_f32_e32 v172, v0, v0
	v_fmac_f32_e32 v173, v2, v2
	v_add_u32_e32 v185, 0xb0000, v148
	global_store_dwordx4 v185, v[166:169], s[8:9] offset:256
	v_add_f32_e32 v170, v170, v171
	v_add_f32_e32 v172, v172, v173
	v_add_f32_e32 v170, v170, v172
	v_add_f32_e32 v182, v182, v170
	ds_bpermute_b32 v183, v144, v182
	v_add_u32_e32 v146, 0x2c0, v149
	s_waitcnt lgkmcnt(0)
	v_add_f32_e32 v182, v182, v183
	ds_bpermute_b32 v183, v145, v182
	s_waitcnt lgkmcnt(0)
	v_add_f32_e32 v182, v182, v183
	s_and_saveexec_b64 s[6:7], vcc
	global_atomic_add_f32 v146, v182, s[94:95]
	s_or_b64 exec, exec, s[6:7]

; #define PG8_STAGE(bufoff, gbase, voff) do { _Pragma("unroll") for (int _i = 0; _i < 2; ++_i) \
;         __builtin_amdgcn_global_load_lds((const unsigned*)((const char*)(gbase) + (voff)[_i]), (PG8_LAS unsigned*)(lds + (bufoff) + ldsw + _i * 8192), 16, 0, 0); } while (0)
; #define PG8_WAIT_V(n) asm volatile("s_waitcnt vmcnt(" #n ")" ::: "memory")
; #define PG8_BAR __builtin_amdgcn_s_barrier()
; template <class Epi, class Sched, bool ALIGN_EPI = false, bool SP2 = false>
; __device__ __forceinline__ void gemm_phase(PG8_LAS unsigned char* lds, const Gemm g, const Sched& S, const Epi& E) {
;     ...
;     for (int i = 0; i < 2; ++i) { int R, C; stage_rc(tid * 16 + i * 8192, R, C); const int Rb = Epi::PERM ? ((R & ~31) + perm32(R & 31)) : R;
;         voffA[i] = (unsigned)(R * K + C) * 2u; voffB[i] = (unsigned)(Rb * K + C) * 2u; }
;     const size_t kstep = (size_t)(BK * 2);
;     const size_t hstep = (size_t)HALF * K * 2;
;     const size_t tstep = 2 * hstep;
;     const unsigned ldsw = (unsigned)wid * 1024u;
;     const int aoff = lds_byte(wr * 64 + fr, fq * 8), boff = lds_byte(wc * 32 + fr, fq * 8);
;     ...
;         PG8_STAGE(PG8_SB(1, 0), cB + kstep, voffB); PG8_STAGE(PG8_SA(1, 0), cA + kstep, voffA); PG8_STAGE(PG8_SB(1, 1), cB + hstep + kstep, voffB);
;         PG8_WAIT_V(6); PG8_BAR;
.LBB0_911:
	s_add_u32 s12, s86, 0x961000
	s_addc_u32 s13, s87, 0
	s_lshl_b32 s14, s14, 5
	s_and_b32 s41, s14, 0x60
	s_mov_b64 s[14:15], 0x80
	s_add_i32 m0, s27, 0x18000
	v_lshl_add_u64 v[6:7], v[6:7], 0, s[14:15]
	s_lshl_b32 s40, s5, 6
	s_lshl_b32 s5, s5, 13
	s_lshl_b32 s17, s41, 7
	s_waitcnt vmcnt(2)
	s_barrier
	global_load_lds_dwordx4 v[6:7], off
	v_lshl_add_u64 v[4:5], v[4:5], 0, s[14:15]
	s_add_i32 m0, s27, 0x1a000
	s_add_i32 s42, s27, 0x8000
	s_add_i32 s43, s27, 0xa000
	global_load_lds_dwordx4 v[4:5], off
	v_lshl_add_u64 v[0:1], v[0:1], 0, s[14:15]
	s_mov_b32 m0, s42
	s_add_u32 s18, s30, 0x80080
	global_load_lds_dwordx4 v[0:1], off
	v_lshl_add_u64 v[0:1], v[2:3], 0, s[14:15]
	s_mov_b32 m0, s43
	s_addc_u32 s19, s31, 0
	global_load_lds_dwordx4 v[0:1], off
	s_add_i32 m0, s27, 0x1c000
	s_nop 0
	global_load_lds_dwordx4 v130, s[18:19]
	v_lshl_add_u64 v[0:1], s[18:19], 0, v[134:135]
	s_add_i32 m0, s27, 0x1e000
	v_bfe_u32 v149, v186, 4, 2
	global_load_lds_dwordx4 v[0:1], off
	s_sext_i32_i8 s48, s4
	v_and_b32_e32 v148, 15, v186
	v_lshlrev_b32_e32 v0, 4, v149
	v_lshlrev_b32_e32 v2, 2, v186
	v_lshlrev_b32_e32 v3, 6, v186
	s_movk_i32 s4, 0x3c0
	v_lshl_or_b32 v1, v148, 6, v0
	v_and_b32_e32 v2, 32, v2
	v_and_or_b32 v0, v3, s4, v0
	v_bitop3_b32 v150, s17, v0, v2 bitop3:0xf6
	v_lshlrev_b32_e32 v0, 9, v186
	v_bitop3_b32 v1, v1, s5, v2 bitop3:0xde
	v_and_b32_e32 v0, 0x70000, v0
	v_lshlrev_b32_e32 v2, 12, v10
	v_or3_b32 v0, v8, v0, v2
	v_add_u32_e32 v136, v0, v9
	v_lshlrev_b32_e32 v0, 5, v11
	s_waitcnt vmcnt(6)
	s_cmpk_lt_u32 s16, 0x100
	v_and_b32_e32 v0, 0xf0000, v0
	s_cselect_b64 s[16:17], -1, 0
	v_or3_b32 v0, v8, v0, v2
	s_add_i32 s45, 0, 0x10000
	s_add_i32 s46, 0, 0x14000
	s_ashr_i32 s44, s3, 31
	v_mov_b32_e32 v137, v131
	v_add_u32_e32 v138, v0, v9
	v_mov_b32_e32 v139, v131
	v_mov_b64_e32 v[140:141], 0x400
	v_mov_b64_e32 v[142:143], 0x3ff
	v_add_u32_e32 v151, s45, v150
	v_add_u32_e32 v152, s46, v150
	v_add_u32_e32 v153, 0, v1
	v_mov_b32_e32 v154, 0x358637bd
	s_mov_b32 s47, 0x800000
	s_barrier
	s_branch .LBB0_914

; #define PG8_STAGE(bufoff, gbase, voff) do { _Pragma("unroll") for (int _i = 0; _i < 2; ++_i) \
;         __builtin_amdgcn_global_load_lds((const unsigned*)((const char*)(gbase) + (voff)[_i]), (PG8_LAS unsigned*)(lds + (bufoff) + ldsw + _i * 8192), 16, 0, 0); } while (0)
; #define PG8_LDA(dst, b, h) do { _Pragma("unroll") for (int m = 0; m < 4; ++m) _Pragma("unroll") for (int k = 0; k < 2; ++k) dst[m][k] = *(const PG8_LAS bf16x8*)(lds + PG8_SA(b, h) + aoff + m * 2048 + k * 1024); } while (0)
; #define PG8_LDB(dst, b, h) do { _Pragma("unroll") for (int n = 0; n < 2; ++n) _Pragma("unroll") for (int k = 0; k < 2; ++k) dst[n][k] = *(const PG8_LAS bf16x8*)(lds + PG8_SB(b, h) + boff + n * 2048 + k * 1024); } while (0)
; #define PG8_MMA(ai, bj, At, Bt) do { __builtin_amdgcn_s_setprio(1); _Pragma("unroll") for (int m = 0; m < 4; ++m) _Pragma("unroll") for (int n = 0; n < 2; ++n) _Pragma("unroll") for (int k = 0; k < 2; ++k) \
;         acc[ai][bj][m][n] = __builtin_amdgcn_mfma_f32_16x16x32_bf16(Bt[n][k], At[m][k], acc[ai][bj][m][n], 0, 0, 0); __builtin_amdgcn_s_setprio(0); } while (0)
; #define PG8_WAIT_V(n) asm volatile("s_waitcnt vmcnt(" #n ")" ::: "memory")
; #define PG8_WAIT_L(n) asm volatile("s_waitcnt lgkmcnt(" #n ")" ::: "memory")
; template <class Epi, class Sched, bool ALIGN_EPI = false, bool SP2 = false>
; __device__ __forceinline__ void gemm_phase(PG8_LAS unsigned char* lds, const Gemm g, const Sched& S, const Epi& E) {
;     ...
;             const bool last = (t == nt - 2);
;             const char* a1 = cA + (size_t)(t + 1) * kstep;
;             const char* a2 = last ? nA : cA + (size_t)(t + 2) * kstep; const char* b2 = last ? nB : cB + (size_t)(t + 2) * kstep;
;             const char* a3 = a2 + kstep; const char* b3 = b2 + kstep;
;             if (last && has_next) S.a_ready(nxt);
;             if constexpr (SP2) {
;             PG8_LDB(B0, 0, 0); PG8_LDB(B1, 0, 1); PG8_SCHED; PG8_LDA(At, 0, 0); PG8_STAGE(PG8_SA(1, 1), a1 + hstep, voffA);
;             PG8_WAIT_V(8); PG8_WAIT_L(0); PG8_BAR; PG8_MMA(0, 0, At, B0); PG8_MMA(0, 1, At, B1); PG8_BAR; PG8_SCHED;
;             PG8_LDA(At, 0, 1); PG8_STAGE(PG8_SB(0, 0), b2, voffB); PG8_STAGE(PG8_SB(0, 1), b2 + hstep, voffB); PG8_STAGE(PG8_SA(0, 0), a2, voffA);
;             PG8_WAIT_V(8); PG8_WAIT_L(0); PG8_BAR; PG8_MMA(1, 0, At, B0); PG8_MMA(1, 1, At, B1); PG8_BAR; PG8_SCHED;
.LBB0_921:
	ds_read_b128 v[144:147], v151
	ds_read_b128 v[156:159], v151 offset:1024
	ds_read_b128 v[160:163], v151 offset:2048
	ds_read_b128 v[164:167], v151 offset:3072
	ds_read_b128 v[168:171], v152
	ds_read_b128 v[172:175], v152 offset:1024
	ds_read_b128 v[176:179], v152 offset:2048
	ds_read_b128 v[180:183], v152 offset:3072
	s_add_u32 s30, s28, 0xfff80080
	s_addc_u32 s31, s29, -1
	s_cmp_eq_u32 s53, 28
	s_cselect_b32 s35, s21, s31
	s_cselect_b32 s34, s49, s30
	s_cselect_b32 s31, s19, s52
	s_cselect_b32 s30, s50, s51
	s_add_i32 m0, s27, 0xc000
	ds_read_b128 v[188:191], v153
	ds_read_b128 v[192:195], v153 offset:1024
	ds_read_b128 v[196:199], v153 offset:2048
	ds_read_b128 v[200:203], v153 offset:3072
	ds_read_b128 v[204:207], v153 offset:4096
	ds_read_b128 v[208:211], v153 offset:5120
	ds_read_b128 v[212:215], v153 offset:6144
	ds_read_b128 v[216:219], v153 offset:7168
	global_load_lds_dwordx4 v136, s[28:29]
	s_add_i32 m0, s27, 0xe000
	s_nop 0
	global_load_lds_dwordx4 v138, s[28:29]
	s_waitcnt vmcnt(8)
	s_waitcnt lgkmcnt(0)
	s_barrier
	s_setprio 1
	s_waitcnt lgkmcnt(0)
	v_mfma_f32_16x16x32_bf16 v[124:127], v[144:147], v[188:191], v[124:127]
	v_mfma_f32_16x16x32_bf16 v[120:123], v[160:163], v[188:191], v[120:123]
	v_mfma_f32_16x16x32_bf16 v[108:111], v[144:147], v[196:199], v[108:111]
	v_mfma_f32_16x16x32_bf16 v[104:107], v[160:163], v[196:199], v[104:107]
	v_mfma_f32_16x16x32_bf16 v[92:95], v[144:147], v[204:207], v[92:95]
	v_mfma_f32_16x16x32_bf16 v[88:91], v[160:163], v[204:207], v[88:91]
	v_mfma_f32_16x16x32_bf16 v[76:79], v[144:147], v[212:215], v[76:79]
	v_mfma_f32_16x16x32_bf16 v[72:75], v[160:163], v[212:215], v[72:75]
	v_mfma_f32_16x16x32_bf16 v[124:127], v[156:159], v[192:195], v[124:127]
	v_mfma_f32_16x16x32_bf16 v[120:123], v[164:167], v[192:195], v[120:123]
	v_mfma_f32_16x16x32_bf16 v[108:111], v[156:159], v[200:203], v[108:111]
	v_mfma_f32_16x16x32_bf16 v[104:107], v[164:167], v[200:203], v[104:107]
	v_mfma_f32_16x16x32_bf16 v[92:95], v[156:159], v[208:211], v[92:95]
	v_mfma_f32_16x16x32_bf16 v[88:91], v[164:167], v[208:211], v[88:91]
	v_mfma_f32_16x16x32_bf16 v[76:79], v[156:159], v[216:219], v[76:79]
	v_mfma_f32_16x16x32_bf16 v[72:75], v[164:167], v[216:219], v[72:75]
	s_setprio 0
	s_setprio 1
	v_mfma_f32_16x16x32_bf16 v[116:119], v[168:171], v[188:191], v[116:119]
	v_mfma_f32_16x16x32_bf16 v[112:115], v[176:179], v[188:191], v[112:115]
	v_mfma_f32_16x16x32_bf16 v[100:103], v[168:171], v[196:199], v[100:103]
	v_mfma_f32_16x16x32_bf16 v[96:99], v[176:179], v[196:199], v[96:99]
	v_mfma_f32_16x16x32_bf16 v[84:87], v[168:171], v[204:207], v[84:87]
	v_mfma_f32_16x16x32_bf16 v[80:83], v[176:179], v[204:207], v[80:83]
	v_mfma_f32_16x16x32_bf16 v[68:71], v[168:171], v[212:215], v[68:71]
	v_mfma_f32_16x16x32_bf16 v[64:67], v[176:179], v[212:215], v[64:67]
	v_mfma_f32_16x16x32_bf16 v[116:119], v[172:175], v[192:195], v[116:119]
	v_mfma_f32_16x16x32_bf16 v[112:115], v[180:183], v[192:195], v[112:115]
	v_mfma_f32_16x16x32_bf16 v[100:103], v[172:175], v[200:203], v[100:103]
	v_mfma_f32_16x16x32_bf16 v[96:99], v[180:183], v[200:203], v[96:99]
	v_mfma_f32_16x16x32_bf16 v[84:87], v[172:175], v[208:211], v[84:87]
	v_mfma_f32_16x16x32_bf16 v[80:83], v[180:183], v[208:211], v[80:83]
	v_mfma_f32_16x16x32_bf16 v[68:71], v[172:175], v[216:219], v[68:71]
	v_mfma_f32_16x16x32_bf16 v[64:67], v[180:183], v[216:219], v[64:67]
	s_setprio 0
	s_barrier
	s_add_u32 s98, s30, s14
	s_addc_u32 s99, s31, s15
	s_add_u32 s100, s34, s14
	s_addc_u32 s101, s35, s15
	s_add_i32 s54, s45, s1
	s_mov_b32 m0, s54
	ds_read_b128 v[188:191], v153 offset:16384
	ds_read_b128 v[192:195], v153 offset:17408
	ds_read_b128 v[196:199], v153 offset:18432
	ds_read_b128 v[200:203], v153 offset:19456
	ds_read_b128 v[204:207], v153 offset:20480
	ds_read_b128 v[208:211], v153 offset:21504
	ds_read_b128 v[212:215], v153 offset:22528
	ds_read_b128 v[216:219], v153 offset:23552
	global_load_lds_dwordx4 v130, s[30:31]
	s_add_i32 m0, s54, 0x2000
	s_add_u32 s54, s30, 0x80000
	s_addc_u32 s55, s31, 0
	s_add_i32 s56, s46, s1
	global_load_lds_dwordx4 v134, s[30:31]
	s_mov_b32 m0, s56
	s_nop 0
	global_load_lds_dwordx4 v130, s[54:55]
	s_add_i32 m0, s56, 0x2000
	s_nop 0
	global_load_lds_dwordx4 v134, s[54:55]
	s_mov_b32 m0, s27
	s_nop 0
	global_load_lds_dwordx4 v128, s[34:35]
	s_mov_b32 m0, s36
	s_nop 0
	global_load_lds_dwordx4 v132, s[34:35]
	s_waitcnt vmcnt(8)
	s_waitcnt lgkmcnt(0)
	s_barrier
	s_setprio 1
	s_waitcnt lgkmcnt(0)
	v_mfma_f32_16x16x32_bf16 v[60:63], v[144:147], v[188:191], v[60:63]
	v_mfma_f32_16x16x32_bf16 v[56:59], v[160:163], v[188:191], v[56:59]
	v_mfma_f32_16x16x32_bf16 v[44:47], v[144:147], v[196:199], v[44:47]
	v_mfma_f32_16x16x32_bf16 v[40:43], v[160:163], v[196:199], v[40:43]
	v_mfma_f32_16x16x32_bf16 v[28:31], v[144:147], v[204:207], v[28:31]
	v_mfma_f32_16x16x32_bf16 v[24:27], v[160:163], v[204:207], v[24:27]
	v_mfma_f32_16x16x32_bf16 v[12:15], v[144:147], v[212:215], v[12:15]
	v_mfma_f32_16x16x32_bf16 v[8:11], v[160:163], v[212:215], v[8:11]
	v_mfma_f32_16x16x32_bf16 v[60:63], v[156:159], v[192:195], v[60:63]
	v_mfma_f32_16x16x32_bf16 v[56:59], v[164:167], v[192:195], v[56:59]
	v_mfma_f32_16x16x32_bf16 v[44:47], v[156:159], v[200:203], v[44:47]
	v_mfma_f32_16x16x32_bf16 v[40:43], v[164:167], v[200:203], v[40:43]
	v_mfma_f32_16x16x32_bf16 v[28:31], v[156:159], v[208:211], v[28:31]
	v_mfma_f32_16x16x32_bf16 v[24:27], v[164:167], v[208:211], v[24:27]
	v_mfma_f32_16x16x32_bf16 v[12:15], v[156:159], v[216:219], v[12:15]
	v_mfma_f32_16x16x32_bf16 v[8:11], v[164:167], v[216:219], v[8:11]
	s_setprio 0
	s_setprio 1
	v_mfma_f32_16x16x32_bf16 v[52:55], v[168:171], v[188:191], v[52:55]
	v_mfma_f32_16x16x32_bf16 v[48:51], v[176:179], v[188:191], v[48:51]
	v_mfma_f32_16x16x32_bf16 v[36:39], v[168:171], v[196:199], v[36:39]
	v_mfma_f32_16x16x32_bf16 v[32:35], v[176:179], v[196:199], v[32:35]
	v_mfma_f32_16x16x32_bf16 v[20:23], v[168:171], v[204:207], v[20:23]
	v_mfma_f32_16x16x32_bf16 v[16:19], v[176:179], v[204:207], v[16:19]
	v_mfma_f32_16x16x32_bf16 v[4:7], v[168:171], v[212:215], v[4:7]
	v_mfma_f32_16x16x32_bf16 v[0:3], v[176:179], v[212:215], v[0:3]
	v_mfma_f32_16x16x32_bf16 v[52:55], v[172:175], v[192:195], v[52:55]
	v_mfma_f32_16x16x32_bf16 v[48:51], v[180:183], v[192:195], v[48:51]
	v_mfma_f32_16x16x32_bf16 v[36:39], v[172:175], v[200:203], v[36:39]
	v_mfma_f32_16x16x32_bf16 v[32:35], v[180:183], v[200:203], v[32:35]
	v_mfma_f32_16x16x32_bf16 v[20:23], v[172:175], v[208:211], v[20:23]
	v_mfma_f32_16x16x32_bf16 v[16:19], v[180:183], v[208:211], v[16:19]
	v_mfma_f32_16x16x32_bf16 v[4:7], v[172:175], v[216:219], v[4:7]
	v_mfma_f32_16x16x32_bf16 v[0:3], v[180:183], v[216:219], v[0:3]
	s_setprio 0
	s_barrier
; #define PG8_STAGE(bufoff, gbase, voff) do { _Pragma("unroll") for (int _i = 0; _i < 2; ++_i) \
;         __builtin_amdgcn_global_load_lds((const unsigned*)((const char*)(gbase) + (voff)[_i]), (PG8_LAS unsigned*)(lds + (bufoff) + ldsw + _i * 8192), 16, 0, 0); } while (0)
; #define PG8_LDA(dst, b, h) do { _Pragma("unroll") for (int m = 0; m < 4; ++m) _Pragma("unroll") for (int k = 0; k < 2; ++k) dst[m][k] = *(const PG8_LAS bf16x8*)(lds + PG8_SA(b, h) + aoff + m * 2048 + k * 1024); } while (0)
; #define PG8_LDB(dst, b, h) do { _Pragma("unroll") for (int n = 0; n < 2; ++n) _Pragma("unroll") for (int k = 0; k < 2; ++k) dst[n][k] = *(const PG8_LAS bf16x8*)(lds + PG8_SB(b, h) + boff + n * 2048 + k * 1024); } while (0)
; #define PG8_MMA(ai, bj, At, Bt) do { __builtin_amdgcn_s_setprio(1); _Pragma("unroll") for (int m = 0; m < 4; ++m) _Pragma("unroll") for (int n = 0; n < 2; ++n) _Pragma("unroll") for (int k = 0; k < 2; ++k) \
;         acc[ai][bj][m][n] = __builtin_amdgcn_mfma_f32_16x16x32_bf16(Bt[n][k], At[m][k], acc[ai][bj][m][n], 0, 0, 0); __builtin_amdgcn_s_setprio(0); } while (0)
; #define PG8_WAIT_V(n) asm volatile("s_waitcnt vmcnt(" #n ")" ::: "memory")
; #define PG8_WAIT_L(n) asm volatile("s_waitcnt lgkmcnt(" #n ")" ::: "memory")
; #define PG8_BAR __builtin_amdgcn_s_barrier()
; #define PG8_SCHED __builtin_amdgcn_sched_barrier(0)
; template <class Epi, class Sched, bool ALIGN_EPI = false, bool SP2 = false>
; __device__ __forceinline__ void gemm_phase(PG8_LAS unsigned char* lds, const Gemm g, const Sched& S, const Epi& E) {
;     ...
;             PG8_LDB(B0, 1, 0); PG8_LDB(B1, 1, 1); PG8_SCHED; PG8_LDA(At, 1, 0); PG8_STAGE(PG8_SA(0, 1), a2 + hstep, voffA);
;             PG8_WAIT_V(8); PG8_WAIT_L(0); PG8_BAR; PG8_MMA(0, 0, At, B0); PG8_MMA(0, 1, At, B1); PG8_BAR; PG8_SCHED;
;             PG8_LDA(At, 1, 1); PG8_STAGE(PG8_SB(1, 0), b3, voffB); PG8_STAGE(PG8_SB(1, 1), b3 + hstep, voffB); PG8_STAGE(PG8_SA(1, 0), a3, voffA);
;             PG8_WAIT_V(8); PG8_WAIT_L(0); PG8_BAR; PG8_MMA(1, 0, At, B0); PG8_MMA(1, 1, At, B1); PG8_BAR; PG8_SCHED;
	s_add_i32 s54, 0, 0x18000
	v_add_u32_e32 v155, s54, v150
	s_add_i32 s55, 0, 0x1c000
	ds_read_b128 v[144:147], v155
	ds_read_b128 v[156:159], v155 offset:1024
	ds_read_b128 v[160:163], v155 offset:2048
	ds_read_b128 v[164:167], v155 offset:3072
	v_add_u32_e32 v155, s55, v150
	ds_read_b128 v[168:171], v155
	ds_read_b128 v[172:175], v155 offset:1024
	ds_read_b128 v[176:179], v155 offset:2048
	ds_read_b128 v[180:183], v155 offset:3072
	s_add_u32 s34, s34, 0x80000
	s_addc_u32 s35, s35, 0
	s_mov_b32 m0, s37
	ds_read_b128 v[188:191], v153 offset:32768
	ds_read_b128 v[192:195], v153 offset:33792
	ds_read_b128 v[196:199], v153 offset:34816
	ds_read_b128 v[200:203], v153 offset:35840
	ds_read_b128 v[204:207], v153 offset:36864
	ds_read_b128 v[208:211], v153 offset:37888
	ds_read_b128 v[212:215], v153 offset:38912
	ds_read_b128 v[216:219], v153 offset:39936
	global_load_lds_dwordx4 v128, s[34:35]
	s_mov_b32 m0, s38
	s_nop 0
	global_load_lds_dwordx4 v132, s[34:35]
	s_waitcnt vmcnt(8)
	s_waitcnt lgkmcnt(0)
	s_barrier
	s_setprio 1
	s_waitcnt lgkmcnt(0)
	v_mfma_f32_16x16x32_bf16 v[124:127], v[144:147], v[188:191], v[124:127]
	v_mfma_f32_16x16x32_bf16 v[120:123], v[160:163], v[188:191], v[120:123]
	v_mfma_f32_16x16x32_bf16 v[108:111], v[144:147], v[196:199], v[108:111]
	v_mfma_f32_16x16x32_bf16 v[104:107], v[160:163], v[196:199], v[104:107]
	v_mfma_f32_16x16x32_bf16 v[92:95], v[144:147], v[204:207], v[92:95]
	v_mfma_f32_16x16x32_bf16 v[88:91], v[160:163], v[204:207], v[88:91]
	v_mfma_f32_16x16x32_bf16 v[76:79], v[144:147], v[212:215], v[76:79]
	v_mfma_f32_16x16x32_bf16 v[72:75], v[160:163], v[212:215], v[72:75]
	v_mfma_f32_16x16x32_bf16 v[124:127], v[156:159], v[192:195], v[124:127]
	v_mfma_f32_16x16x32_bf16 v[120:123], v[164:167], v[192:195], v[120:123]
	v_mfma_f32_16x16x32_bf16 v[108:111], v[156:159], v[200:203], v[108:111]
	v_mfma_f32_16x16x32_bf16 v[104:107], v[164:167], v[200:203], v[104:107]
	v_mfma_f32_16x16x32_bf16 v[92:95], v[156:159], v[208:211], v[92:95]
	v_mfma_f32_16x16x32_bf16 v[88:91], v[164:167], v[208:211], v[88:91]
	v_mfma_f32_16x16x32_bf16 v[76:79], v[156:159], v[216:219], v[76:79]
	v_mfma_f32_16x16x32_bf16 v[72:75], v[164:167], v[216:219], v[72:75]
	s_setprio 0
	s_setprio 1
	v_mfma_f32_16x16x32_bf16 v[116:119], v[168:171], v[188:191], v[116:119]
	v_mfma_f32_16x16x32_bf16 v[112:115], v[176:179], v[188:191], v[112:115]
	v_mfma_f32_16x16x32_bf16 v[100:103], v[168:171], v[196:199], v[100:103]
	v_mfma_f32_16x16x32_bf16 v[96:99], v[176:179], v[196:199], v[96:99]
	v_mfma_f32_16x16x32_bf16 v[84:87], v[168:171], v[204:207], v[84:87]
	v_mfma_f32_16x16x32_bf16 v[80:83], v[176:179], v[204:207], v[80:83]
	v_mfma_f32_16x16x32_bf16 v[68:71], v[168:171], v[212:215], v[68:71]
	v_mfma_f32_16x16x32_bf16 v[64:67], v[176:179], v[212:215], v[64:67]
	v_mfma_f32_16x16x32_bf16 v[116:119], v[172:175], v[192:195], v[116:119]
	v_mfma_f32_16x16x32_bf16 v[112:115], v[180:183], v[192:195], v[112:115]
	v_mfma_f32_16x16x32_bf16 v[100:103], v[172:175], v[200:203], v[100:103]
	v_mfma_f32_16x16x32_bf16 v[96:99], v[180:183], v[200:203], v[96:99]
	v_mfma_f32_16x16x32_bf16 v[84:87], v[172:175], v[208:211], v[84:87]
	v_mfma_f32_16x16x32_bf16 v[80:83], v[180:183], v[208:211], v[80:83]
	v_mfma_f32_16x16x32_bf16 v[68:71], v[172:175], v[216:219], v[68:71]
	v_mfma_f32_16x16x32_bf16 v[64:67], v[180:183], v[216:219], v[64:67]
	s_setprio 0
	s_barrier
	s_add_i32 s34, s54, s1
	s_mov_b32 m0, s34
	ds_read_b128 v[188:191], v153 offset:49152
	ds_read_b128 v[192:195], v153 offset:50176
	ds_read_b128 v[196:199], v153 offset:51200
	ds_read_b128 v[200:203], v153 offset:52224
	ds_read_b128 v[204:207], v153 offset:53248
	ds_read_b128 v[208:211], v153 offset:54272
	ds_read_b128 v[212:215], v153 offset:55296
	ds_read_b128 v[216:219], v153 offset:56320
	global_load_lds_dwordx4 v130, s[98:99]
	s_add_i32 m0, s34, 0x2000
	s_add_u32 s30, s30, 0x80080
	s_addc_u32 s31, s31, 0
	s_add_i32 s34, s55, s1
	global_load_lds_dwordx4 v134, s[98:99]
	s_mov_b32 m0, s34
	s_nop 0
	global_load_lds_dwordx4 v130, s[30:31]
	s_add_i32 m0, s34, 0x2000
	s_nop 0
	global_load_lds_dwordx4 v134, s[30:31]
	s_mov_b32 m0, s42
	s_nop 0
	global_load_lds_dwordx4 v128, s[100:101]
	s_mov_b32 m0, s43
	s_nop 0
	global_load_lds_dwordx4 v132, s[100:101]
	s_waitcnt vmcnt(8)
	s_waitcnt lgkmcnt(0)
	s_barrier
	s_setprio 1
	s_waitcnt lgkmcnt(0)
	v_mfma_f32_16x16x32_bf16 v[60:63], v[144:147], v[188:191], v[60:63]
	v_mfma_f32_16x16x32_bf16 v[56:59], v[160:163], v[188:191], v[56:59]
	v_mfma_f32_16x16x32_bf16 v[44:47], v[144:147], v[196:199], v[44:47]
	v_mfma_f32_16x16x32_bf16 v[40:43], v[160:163], v[196:199], v[40:43]
	v_mfma_f32_16x16x32_bf16 v[28:31], v[144:147], v[204:207], v[28:31]
	v_mfma_f32_16x16x32_bf16 v[24:27], v[160:163], v[204:207], v[24:27]
	v_mfma_f32_16x16x32_bf16 v[12:15], v[144:147], v[212:215], v[12:15]
	v_mfma_f32_16x16x32_bf16 v[8:11], v[160:163], v[212:215], v[8:11]
	v_mfma_f32_16x16x32_bf16 v[60:63], v[156:159], v[192:195], v[60:63]
	v_mfma_f32_16x16x32_bf16 v[56:59], v[164:167], v[192:195], v[56:59]
	v_mfma_f32_16x16x32_bf16 v[44:47], v[156:159], v[200:203], v[44:47]
	v_mfma_f32_16x16x32_bf16 v[40:43], v[164:167], v[200:203], v[40:43]
	v_mfma_f32_16x16x32_bf16 v[28:31], v[156:159], v[208:211], v[28:31]
	v_mfma_f32_16x16x32_bf16 v[24:27], v[164:167], v[208:211], v[24:27]
	v_mfma_f32_16x16x32_bf16 v[12:15], v[156:159], v[216:219], v[12:15]
	v_mfma_f32_16x16x32_bf16 v[8:11], v[164:167], v[216:219], v[8:11]
	s_setprio 0
	s_setprio 1
	v_mfma_f32_16x16x32_bf16 v[52:55], v[168:171], v[188:191], v[52:55]
	v_mfma_f32_16x16x32_bf16 v[48:51], v[176:179], v[188:191], v[48:51]
	v_mfma_f32_16x16x32_bf16 v[36:39], v[168:171], v[196:199], v[36:39]
	v_mfma_f32_16x16x32_bf16 v[32:35], v[176:179], v[196:199], v[32:35]
	v_mfma_f32_16x16x32_bf16 v[20:23], v[168:171], v[204:207], v[20:23]
	v_mfma_f32_16x16x32_bf16 v[16:19], v[176:179], v[204:207], v[16:19]
	v_mfma_f32_16x16x32_bf16 v[4:7], v[168:171], v[212:215], v[4:7]
	v_mfma_f32_16x16x32_bf16 v[0:3], v[176:179], v[212:215], v[0:3]
	v_mfma_f32_16x16x32_bf16 v[52:55], v[172:175], v[192:195], v[52:55]
	v_mfma_f32_16x16x32_bf16 v[48:51], v[180:183], v[192:195], v[48:51]
	v_mfma_f32_16x16x32_bf16 v[36:39], v[172:175], v[200:203], v[36:39]
	v_mfma_f32_16x16x32_bf16 v[32:35], v[180:183], v[200:203], v[32:35]
	v_mfma_f32_16x16x32_bf16 v[20:23], v[172:175], v[208:211], v[20:23]
	v_mfma_f32_16x16x32_bf16 v[16:19], v[180:183], v[208:211], v[16:19]
	v_mfma_f32_16x16x32_bf16 v[4:7], v[172:175], v[216:219], v[4:7]
	v_mfma_f32_16x16x32_bf16 v[0:3], v[180:183], v[216:219], v[0:3]
	s_setprio 0
	s_barrier
	s_add_i32 s53, s53, 2
	s_add_u32 s28, s28, 0x100
	s_addc_u32 s29, s29, 0
	s_add_u32 s51, s51, 0x100
	s_addc_u32 s52, s52, 0
	s_cmp_gt_u32 s53, 29
	s_cbranch_scc0 .LBB0_921
	s_and_b64 vcc, exec, s[16:17]
	s_cbranch_vccz .LBB0_924
	s_barrier

; #define PG8_STAGE(bufoff, gbase, voff) do { _Pragma("unroll") for (int _i = 0; _i < 2; ++_i) \
;         __builtin_amdgcn_global_load_lds((const unsigned*)((const char*)(gbase) + (voff)[_i]), (PG8_LAS unsigned*)(lds + (bufoff) + ldsw + _i * 8192), 16, 0, 0); } while (0)
; #define PG8_WAIT_V(n) asm volatile("s_waitcnt vmcnt(" #n ")" ::: "memory")
; #define PG8_BAR __builtin_amdgcn_s_barrier()
; template <class Epi, class Sched, bool ALIGN_EPI = false, bool SP2 = false>
; __device__ __forceinline__ void gemm_phase(PG8_LAS unsigned char* lds, const Gemm g, const Sched& S, const Epi& E) {
;     ...
;     for (int i = 0; i < 2; ++i) { int R, C; stage_rc(tid * 16 + i * 8192, R, C); const int Rb = Epi::PERM ? ((R & ~31) + perm32(R & 31)) : R;
;         voffA[i] = (unsigned)(R * K + C) * 2u; voffB[i] = (unsigned)(Rb * K + C) * 2u; }
;     const size_t kstep = (size_t)(BK * 2);
;     const size_t hstep = (size_t)HALF * K * 2;
;     const size_t tstep = 2 * hstep;
;     const unsigned ldsw = (unsigned)wid * 1024u;
;     const int aoff = lds_byte(wr * 64 + fr, fq * 8), boff = lds_byte(wc * 32 + fr, fq * 8);
;     ...
;         PG8_STAGE(PG8_SB(1, 0), cB + kstep, voffB); PG8_STAGE(PG8_SA(1, 0), cA + kstep, voffA); PG8_STAGE(PG8_SB(1, 1), cB + hstep + kstep, voffB);
;         PG8_WAIT_V(6); PG8_BAR;
.LBB0_986:
	s_lshl_b32 s6, s6, 5
	s_mov_b64 s[12:13], 0x80
	s_and_b32 s6, s6, 0x60
	s_add_i32 m0, s25, 0x18000
	v_lshl_add_u64 v[6:7], v[6:7], 0, s[12:13]
	s_lshl_b32 s40, s1, 6
	s_lshl_b32 s1, s1, 13
	s_lshl_b32 s15, s6, 7
	s_waitcnt vmcnt(2)
	s_barrier
	global_load_lds_dwordx4 v[6:7], off
	v_lshl_add_u64 v[4:5], v[4:5], 0, s[12:13]
	s_add_i32 m0, s25, 0x1a000
	s_add_i32 s41, s25, 0x8000
	s_add_i32 s42, s25, 0xa000
	global_load_lds_dwordx4 v[4:5], off
	v_lshl_add_u64 v[0:1], v[0:1], 0, s[12:13]
	s_mov_b32 m0, s41
	s_add_u32 s16, s28, 0x200080
	global_load_lds_dwordx4 v[0:1], off
	v_lshl_add_u64 v[0:1], v[2:3], 0, s[12:13]
	s_mov_b32 m0, s42
	s_addc_u32 s17, s29, 0
	global_load_lds_dwordx4 v[0:1], off
	s_add_i32 m0, s25, 0x1c000
	s_nop 0
	global_load_lds_dwordx4 v130, s[16:17]
	v_lshl_add_u64 v[0:1], s[16:17], 0, v[134:135]
	s_add_i32 m0, s25, 0x1e000
	v_bfe_u32 v149, v186, 4, 2
	global_load_lds_dwordx4 v[0:1], off
	v_and_b32_e32 v148, 15, v186
	v_lshlrev_b32_e32 v0, 4, v149
	v_lshlrev_b32_e32 v2, 2, v186
	v_lshl_or_b32 v1, v148, 6, v0
	v_and_b32_e32 v2, 32, v2
	v_bitop3_b32 v1, v1, s1, v2 bitop3:0xde
	v_lshlrev_b32_e32 v3, 6, v186
	s_movk_i32 s1, 0x3c0
	v_and_or_b32 v0, v3, s1, v0
	v_bitop3_b32 v150, s15, v0, v2 bitop3:0xf6
	v_lshlrev_b32_e32 v0, 11, v186
	v_and_b32_e32 v0, 0x1c0000, v0
	v_lshlrev_b32_e32 v2, 14, v10
	v_or3_b32 v0, v8, v0, v2
	v_add_u32_e32 v136, v0, v9
	v_lshlrev_b32_e32 v0, 7, v11
	s_waitcnt vmcnt(6)
	s_cmpk_lt_u32 s0, 0x100
	v_and_b32_e32 v0, 0x3c0000, v0
	s_sext_i32_i8 s47, s14
	s_cselect_b64 s[14:15], -1, 0
	v_or3_b32 v0, v8, v0, v2
	s_add_i32 s44, 0, 0x10000
	s_add_i32 s45, 0, 0x14000
	s_ashr_i32 s43, s3, 31
	v_mov_b32_e32 v137, v131
	v_add_u32_e32 v138, v0, v9
	v_mov_b32_e32 v139, v131
	v_mov_b64_e32 v[140:141], 0x100
	v_mov_b64_e32 v[142:143], 0xff
	v_add_u32_e32 v151, s44, v150
	v_add_u32_e32 v152, s45, v150
	v_add_u32_e32 v153, 0, v1
	s_mov_b32 s46, s7
	s_barrier
	s_branch .LBB0_989

; #define PG8_STAGE(bufoff, gbase, voff) do { _Pragma("unroll") for (int _i = 0; _i < 2; ++_i) \
;         __builtin_amdgcn_global_load_lds((const unsigned*)((const char*)(gbase) + (voff)[_i]), (PG8_LAS unsigned*)(lds + (bufoff) + ldsw + _i * 8192), 16, 0, 0); } while (0)
; #define PG8_LDA(dst, b, h) do { _Pragma("unroll") for (int m = 0; m < 4; ++m) _Pragma("unroll") for (int k = 0; k < 2; ++k) dst[m][k] = *(const PG8_LAS bf16x8*)(lds + PG8_SA(b, h) + aoff + m * 2048 + k * 1024); } while (0)
; #define PG8_LDB(dst, b, h) do { _Pragma("unroll") for (int n = 0; n < 2; ++n) _Pragma("unroll") for (int k = 0; k < 2; ++k) dst[n][k] = *(const PG8_LAS bf16x8*)(lds + PG8_SB(b, h) + boff + n * 2048 + k * 1024); } while (0)
; #define PG8_MMA(ai, bj, At, Bt) do { __builtin_amdgcn_s_setprio(1); _Pragma("unroll") for (int m = 0; m < 4; ++m) _Pragma("unroll") for (int n = 0; n < 2; ++n) _Pragma("unroll") for (int k = 0; k < 2; ++k) \
;         acc[ai][bj][m][n] = __builtin_amdgcn_mfma_f32_16x16x32_bf16(Bt[n][k], At[m][k], acc[ai][bj][m][n], 0, 0, 0); __builtin_amdgcn_s_setprio(0); } while (0)
; #define PG8_WAIT_V(n) asm volatile("s_waitcnt vmcnt(" #n ")" ::: "memory")
; #define PG8_WAIT_L(n) asm volatile("s_waitcnt lgkmcnt(" #n ")" ::: "memory")
; template <class Epi, class Sched, bool ALIGN_EPI = false, bool SP2 = false>
; __device__ __forceinline__ void gemm_phase(PG8_LAS unsigned char* lds, const Gemm g, const Sched& S, const Epi& E) {
;     ...
;             const bool last = (t == nt - 2);
;             const char* a1 = cA + (size_t)(t + 1) * kstep;
;             const char* a2 = last ? nA : cA + (size_t)(t + 2) * kstep; const char* b2 = last ? nB : cB + (size_t)(t + 2) * kstep;
;             const char* a3 = a2 + kstep; const char* b3 = b2 + kstep;
;             if (last && has_next) S.a_ready(nxt);
;             if constexpr (SP2) {
;             PG8_LDB(B0, 0, 0); PG8_LDB(B1, 0, 1); PG8_SCHED; PG8_LDA(At, 0, 0); PG8_STAGE(PG8_SA(1, 1), a1 + hstep, voffA);
;             PG8_WAIT_V(8); PG8_WAIT_L(0); PG8_BAR; PG8_MMA(0, 0, At, B0); PG8_MMA(0, 1, At, B1); PG8_BAR; PG8_SCHED;
;             PG8_LDA(At, 0, 1); PG8_STAGE(PG8_SB(0, 0), b2, voffB); PG8_STAGE(PG8_SB(0, 1), b2 + hstep, voffB); PG8_STAGE(PG8_SA(0, 0), a2, voffA);
;             PG8_WAIT_V(8); PG8_WAIT_L(0); PG8_BAR; PG8_MMA(1, 0, At, B0); PG8_MMA(1, 1, At, B1); PG8_BAR; PG8_SCHED;
.LBB0_996:
	ds_read_b128 v[144:147], v151
	ds_read_b128 v[154:157], v151 offset:1024
	ds_read_b128 v[158:161], v151 offset:2048
	ds_read_b128 v[162:165], v151 offset:3072
	ds_read_b128 v[166:169], v152
	ds_read_b128 v[170:173], v152 offset:1024
	ds_read_b128 v[174:177], v152 offset:2048
	ds_read_b128 v[178:181], v152 offset:3072
	s_add_u32 s28, s26, 0xffe00080
	s_addc_u32 s29, s27, -1
	s_cmpk_eq_i32 s52, 0x7c
	s_cselect_b32 s31, s19, s29
	s_cselect_b32 s30, s48, s28
	s_cselect_b32 s29, s17, s51
	s_cselect_b32 s28, s49, s50
	s_add_i32 m0, s25, 0xc000
	ds_read_b128 v[182:185], v153
	ds_read_b128 v[186:189], v153 offset:1024
	ds_read_b128 v[190:193], v153 offset:2048
	ds_read_b128 v[194:197], v153 offset:3072
	ds_read_b128 v[198:201], v153 offset:4096
	ds_read_b128 v[202:205], v153 offset:5120
	ds_read_b128 v[206:209], v153 offset:6144
	ds_read_b128 v[210:213], v153 offset:7168
	global_load_lds_dwordx4 v136, s[26:27]
	s_add_i32 m0, s25, 0xe000
	s_nop 0
	global_load_lds_dwordx4 v138, s[26:27]
	s_waitcnt vmcnt(8)
	s_waitcnt lgkmcnt(0)
	s_barrier
	s_setprio 1
	s_waitcnt lgkmcnt(0)
	v_mfma_f32_16x16x32_bf16 v[124:127], v[144:147], v[182:185], v[124:127]
	v_mfma_f32_16x16x32_bf16 v[120:123], v[158:161], v[182:185], v[120:123]
	v_mfma_f32_16x16x32_bf16 v[112:115], v[144:147], v[190:193], v[112:115]
	v_mfma_f32_16x16x32_bf16 v[104:107], v[158:161], v[190:193], v[104:107]
	v_mfma_f32_16x16x32_bf16 v[96:99], v[144:147], v[198:201], v[96:99]
	v_mfma_f32_16x16x32_bf16 v[88:91], v[158:161], v[198:201], v[88:91]
	v_mfma_f32_16x16x32_bf16 v[80:83], v[144:147], v[206:209], v[80:83]
	v_mfma_f32_16x16x32_bf16 v[72:75], v[158:161], v[206:209], v[72:75]
	v_mfma_f32_16x16x32_bf16 v[124:127], v[154:157], v[186:189], v[124:127]
	v_mfma_f32_16x16x32_bf16 v[120:123], v[162:165], v[186:189], v[120:123]
	v_mfma_f32_16x16x32_bf16 v[112:115], v[154:157], v[194:197], v[112:115]
	v_mfma_f32_16x16x32_bf16 v[104:107], v[162:165], v[194:197], v[104:107]
	v_mfma_f32_16x16x32_bf16 v[96:99], v[154:157], v[202:205], v[96:99]
	v_mfma_f32_16x16x32_bf16 v[88:91], v[162:165], v[202:205], v[88:91]
	v_mfma_f32_16x16x32_bf16 v[80:83], v[154:157], v[210:213], v[80:83]
	v_mfma_f32_16x16x32_bf16 v[72:75], v[162:165], v[210:213], v[72:75]
	s_setprio 0
	s_setprio 1
	v_mfma_f32_16x16x32_bf16 v[116:119], v[166:169], v[182:185], v[116:119]
	v_mfma_f32_16x16x32_bf16 v[108:111], v[174:177], v[182:185], v[108:111]
	v_mfma_f32_16x16x32_bf16 v[100:103], v[166:169], v[190:193], v[100:103]
	v_mfma_f32_16x16x32_bf16 v[92:95], v[174:177], v[190:193], v[92:95]
	v_mfma_f32_16x16x32_bf16 v[84:87], v[166:169], v[198:201], v[84:87]
	v_mfma_f32_16x16x32_bf16 v[76:79], v[174:177], v[198:201], v[76:79]
	v_mfma_f32_16x16x32_bf16 v[68:71], v[166:169], v[206:209], v[68:71]
	v_mfma_f32_16x16x32_bf16 v[64:67], v[174:177], v[206:209], v[64:67]
	v_mfma_f32_16x16x32_bf16 v[116:119], v[170:173], v[186:189], v[116:119]
	v_mfma_f32_16x16x32_bf16 v[108:111], v[178:181], v[186:189], v[108:111]
	v_mfma_f32_16x16x32_bf16 v[100:103], v[170:173], v[194:197], v[100:103]
	v_mfma_f32_16x16x32_bf16 v[92:95], v[178:181], v[194:197], v[92:95]
	v_mfma_f32_16x16x32_bf16 v[84:87], v[170:173], v[202:205], v[84:87]
	v_mfma_f32_16x16x32_bf16 v[76:79], v[178:181], v[202:205], v[76:79]
	v_mfma_f32_16x16x32_bf16 v[68:71], v[170:173], v[210:213], v[68:71]
	v_mfma_f32_16x16x32_bf16 v[64:67], v[178:181], v[210:213], v[64:67]
	s_setprio 0
	s_barrier
	s_add_u32 s98, s28, s12
	s_addc_u32 s99, s29, s13
	s_add_u32 s100, s30, s12
	s_addc_u32 s101, s31, s13
	s_add_i32 s53, s44, s36
	s_mov_b32 m0, s53
	ds_read_b128 v[182:185], v153 offset:16384
	ds_read_b128 v[186:189], v153 offset:17408
	ds_read_b128 v[190:193], v153 offset:18432
	ds_read_b128 v[194:197], v153 offset:19456
	ds_read_b128 v[198:201], v153 offset:20480
	ds_read_b128 v[202:205], v153 offset:21504
	ds_read_b128 v[206:209], v153 offset:22528
	ds_read_b128 v[210:213], v153 offset:23552
	global_load_lds_dwordx4 v130, s[28:29]
	s_add_i32 m0, s53, 0x2000
	s_add_u32 s54, s28, 0x200000
	s_addc_u32 s55, s29, 0
	s_add_i32 s53, s45, s36
	global_load_lds_dwordx4 v134, s[28:29]
	s_mov_b32 m0, s53
	s_nop 0
	global_load_lds_dwordx4 v130, s[54:55]
	s_add_i32 m0, s53, 0x2000
	s_nop 0
	global_load_lds_dwordx4 v134, s[54:55]
	s_mov_b32 m0, s25
	s_nop 0
	global_load_lds_dwordx4 v128, s[30:31]
	s_mov_b32 m0, s37
	s_nop 0
	global_load_lds_dwordx4 v132, s[30:31]
	s_waitcnt vmcnt(8)
	s_waitcnt lgkmcnt(0)
	s_barrier
	s_setprio 1
	s_waitcnt lgkmcnt(0)
	v_mfma_f32_16x16x32_bf16 v[60:63], v[144:147], v[182:185], v[60:63]
	v_mfma_f32_16x16x32_bf16 v[56:59], v[158:161], v[182:185], v[56:59]
	v_mfma_f32_16x16x32_bf16 v[48:51], v[144:147], v[190:193], v[48:51]
	v_mfma_f32_16x16x32_bf16 v[40:43], v[158:161], v[190:193], v[40:43]
	v_mfma_f32_16x16x32_bf16 v[32:35], v[144:147], v[198:201], v[32:35]
	v_mfma_f32_16x16x32_bf16 v[24:27], v[158:161], v[198:201], v[24:27]
	v_mfma_f32_16x16x32_bf16 v[16:19], v[144:147], v[206:209], v[16:19]
	v_mfma_f32_16x16x32_bf16 v[8:11], v[158:161], v[206:209], v[8:11]
	v_mfma_f32_16x16x32_bf16 v[60:63], v[154:157], v[186:189], v[60:63]
	v_mfma_f32_16x16x32_bf16 v[56:59], v[162:165], v[186:189], v[56:59]
	v_mfma_f32_16x16x32_bf16 v[48:51], v[154:157], v[194:197], v[48:51]
	v_mfma_f32_16x16x32_bf16 v[40:43], v[162:165], v[194:197], v[40:43]
	v_mfma_f32_16x16x32_bf16 v[32:35], v[154:157], v[202:205], v[32:35]
	v_mfma_f32_16x16x32_bf16 v[24:27], v[162:165], v[202:205], v[24:27]
	v_mfma_f32_16x16x32_bf16 v[16:19], v[154:157], v[210:213], v[16:19]
	v_mfma_f32_16x16x32_bf16 v[8:11], v[162:165], v[210:213], v[8:11]
	s_setprio 0
	s_setprio 1
	v_mfma_f32_16x16x32_bf16 v[52:55], v[166:169], v[182:185], v[52:55]
	v_mfma_f32_16x16x32_bf16 v[44:47], v[174:177], v[182:185], v[44:47]
	v_mfma_f32_16x16x32_bf16 v[36:39], v[166:169], v[190:193], v[36:39]
	v_mfma_f32_16x16x32_bf16 v[28:31], v[174:177], v[190:193], v[28:31]
	v_mfma_f32_16x16x32_bf16 v[20:23], v[166:169], v[198:201], v[20:23]
	v_mfma_f32_16x16x32_bf16 v[12:15], v[174:177], v[198:201], v[12:15]
	v_mfma_f32_16x16x32_bf16 v[4:7], v[166:169], v[206:209], v[4:7]
	v_mfma_f32_16x16x32_bf16 v[0:3], v[174:177], v[206:209], v[0:3]
	v_mfma_f32_16x16x32_bf16 v[52:55], v[170:173], v[186:189], v[52:55]
	v_mfma_f32_16x16x32_bf16 v[44:47], v[178:181], v[186:189], v[44:47]
	v_mfma_f32_16x16x32_bf16 v[36:39], v[170:173], v[194:197], v[36:39]
	v_mfma_f32_16x16x32_bf16 v[28:31], v[178:181], v[194:197], v[28:31]
	v_mfma_f32_16x16x32_bf16 v[20:23], v[170:173], v[202:205], v[20:23]
	v_mfma_f32_16x16x32_bf16 v[12:15], v[178:181], v[202:205], v[12:15]
	v_mfma_f32_16x16x32_bf16 v[4:7], v[170:173], v[210:213], v[4:7]
	v_mfma_f32_16x16x32_bf16 v[0:3], v[178:181], v[210:213], v[0:3]
	s_setprio 0
	s_barrier
; #define PG8_STAGE(bufoff, gbase, voff) do { _Pragma("unroll") for (int _i = 0; _i < 2; ++_i) \
;         __builtin_amdgcn_global_load_lds((const unsigned*)((const char*)(gbase) + (voff)[_i]), (PG8_LAS unsigned*)(lds + (bufoff) + ldsw + _i * 8192), 16, 0, 0); } while (0)
; #define PG8_LDA(dst, b, h) do { _Pragma("unroll") for (int m = 0; m < 4; ++m) _Pragma("unroll") for (int k = 0; k < 2; ++k) dst[m][k] = *(const PG8_LAS bf16x8*)(lds + PG8_SA(b, h) + aoff + m * 2048 + k * 1024); } while (0)
; #define PG8_LDB(dst, b, h) do { _Pragma("unroll") for (int n = 0; n < 2; ++n) _Pragma("unroll") for (int k = 0; k < 2; ++k) dst[n][k] = *(const PG8_LAS bf16x8*)(lds + PG8_SB(b, h) + boff + n * 2048 + k * 1024); } while (0)
; #define PG8_MMA(ai, bj, At, Bt) do { __builtin_amdgcn_s_setprio(1); _Pragma("unroll") for (int m = 0; m < 4; ++m) _Pragma("unroll") for (int n = 0; n < 2; ++n) _Pragma("unroll") for (int k = 0; k < 2; ++k) \
;         acc[ai][bj][m][n] = __builtin_amdgcn_mfma_f32_16x16x32_bf16(Bt[n][k], At[m][k], acc[ai][bj][m][n], 0, 0, 0); __builtin_amdgcn_s_setprio(0); } while (0)
; #define PG8_WAIT_V(n) asm volatile("s_waitcnt vmcnt(" #n ")" ::: "memory")
; #define PG8_WAIT_L(n) asm volatile("s_waitcnt lgkmcnt(" #n ")" ::: "memory")
; #define PG8_BAR __builtin_amdgcn_s_barrier()
; #define PG8_SCHED __builtin_amdgcn_sched_barrier(0)
; template <class Epi, class Sched, bool ALIGN_EPI = false, bool SP2 = false>
; __device__ __forceinline__ void gemm_phase(PG8_LAS unsigned char* lds, const Gemm g, const Sched& S, const Epi& E) {
;     ...
;             PG8_LDB(B0, 1, 0); PG8_LDB(B1, 1, 1); PG8_SCHED; PG8_LDA(At, 1, 0); PG8_STAGE(PG8_SA(0, 1), a2 + hstep, voffA);
;             PG8_WAIT_V(8); PG8_WAIT_L(0); PG8_BAR; PG8_MMA(0, 0, At, B0); PG8_MMA(0, 1, At, B1); PG8_BAR; PG8_SCHED;
;             PG8_LDA(At, 1, 1); PG8_STAGE(PG8_SB(1, 0), b3, voffB); PG8_STAGE(PG8_SB(1, 1), b3 + hstep, voffB); PG8_STAGE(PG8_SA(1, 0), a3, voffA);
;             PG8_WAIT_V(8); PG8_WAIT_L(0); PG8_BAR; PG8_MMA(1, 0, At, B0); PG8_MMA(1, 1, At, B1); PG8_BAR; PG8_SCHED;
	s_add_i32 s53, 0, 0x18000
	s_add_i32 s54, 0, 0x1c000
	v_add_u32_e32 v162, s53, v150
	v_add_u32_e32 v178, s54, v150
	ds_read_b128 v[144:147], v162
	ds_read_b128 v[154:157], v162 offset:1024
	ds_read_b128 v[158:161], v162 offset:2048
	ds_read_b128 v[162:165], v162 offset:3072
	ds_read_b128 v[166:169], v178
	ds_read_b128 v[170:173], v178 offset:1024
	ds_read_b128 v[174:177], v178 offset:2048
	ds_read_b128 v[178:181], v178 offset:3072
	s_add_u32 s30, s30, 0x200000
	s_addc_u32 s31, s31, 0
	s_mov_b32 m0, s38
	ds_read_b128 v[182:185], v153 offset:32768
	ds_read_b128 v[186:189], v153 offset:33792
	ds_read_b128 v[190:193], v153 offset:34816
	ds_read_b128 v[194:197], v153 offset:35840
	ds_read_b128 v[198:201], v153 offset:36864
	ds_read_b128 v[202:205], v153 offset:37888
	ds_read_b128 v[206:209], v153 offset:38912
	ds_read_b128 v[210:213], v153 offset:39936
	global_load_lds_dwordx4 v128, s[30:31]
	s_mov_b32 m0, s39
	s_nop 0
	global_load_lds_dwordx4 v132, s[30:31]
	s_waitcnt vmcnt(8)
	s_waitcnt lgkmcnt(0)
	s_barrier
	s_setprio 1
	s_waitcnt lgkmcnt(0)
	v_mfma_f32_16x16x32_bf16 v[124:127], v[144:147], v[182:185], v[124:127]
	v_mfma_f32_16x16x32_bf16 v[120:123], v[158:161], v[182:185], v[120:123]
	v_mfma_f32_16x16x32_bf16 v[112:115], v[144:147], v[190:193], v[112:115]
	v_mfma_f32_16x16x32_bf16 v[104:107], v[158:161], v[190:193], v[104:107]
	v_mfma_f32_16x16x32_bf16 v[96:99], v[144:147], v[198:201], v[96:99]
	v_mfma_f32_16x16x32_bf16 v[88:91], v[158:161], v[198:201], v[88:91]
	v_mfma_f32_16x16x32_bf16 v[80:83], v[144:147], v[206:209], v[80:83]
	v_mfma_f32_16x16x32_bf16 v[72:75], v[158:161], v[206:209], v[72:75]
	v_mfma_f32_16x16x32_bf16 v[124:127], v[154:157], v[186:189], v[124:127]
	v_mfma_f32_16x16x32_bf16 v[120:123], v[162:165], v[186:189], v[120:123]
	v_mfma_f32_16x16x32_bf16 v[112:115], v[154:157], v[194:197], v[112:115]
	v_mfma_f32_16x16x32_bf16 v[104:107], v[162:165], v[194:197], v[104:107]
	v_mfma_f32_16x16x32_bf16 v[96:99], v[154:157], v[202:205], v[96:99]
	v_mfma_f32_16x16x32_bf16 v[88:91], v[162:165], v[202:205], v[88:91]
	v_mfma_f32_16x16x32_bf16 v[80:83], v[154:157], v[210:213], v[80:83]
	v_mfma_f32_16x16x32_bf16 v[72:75], v[162:165], v[210:213], v[72:75]
	s_setprio 0
	s_setprio 1
	v_mfma_f32_16x16x32_bf16 v[116:119], v[166:169], v[182:185], v[116:119]
	v_mfma_f32_16x16x32_bf16 v[108:111], v[174:177], v[182:185], v[108:111]
	v_mfma_f32_16x16x32_bf16 v[100:103], v[166:169], v[190:193], v[100:103]
	v_mfma_f32_16x16x32_bf16 v[92:95], v[174:177], v[190:193], v[92:95]
	v_mfma_f32_16x16x32_bf16 v[84:87], v[166:169], v[198:201], v[84:87]
	v_mfma_f32_16x16x32_bf16 v[76:79], v[174:177], v[198:201], v[76:79]
	v_mfma_f32_16x16x32_bf16 v[68:71], v[166:169], v[206:209], v[68:71]
	v_mfma_f32_16x16x32_bf16 v[64:67], v[174:177], v[206:209], v[64:67]
	v_mfma_f32_16x16x32_bf16 v[116:119], v[170:173], v[186:189], v[116:119]
	v_mfma_f32_16x16x32_bf16 v[108:111], v[178:181], v[186:189], v[108:111]
	v_mfma_f32_16x16x32_bf16 v[100:103], v[170:173], v[194:197], v[100:103]
	v_mfma_f32_16x16x32_bf16 v[92:95], v[178:181], v[194:197], v[92:95]
	v_mfma_f32_16x16x32_bf16 v[84:87], v[170:173], v[202:205], v[84:87]
	v_mfma_f32_16x16x32_bf16 v[76:79], v[178:181], v[202:205], v[76:79]
	v_mfma_f32_16x16x32_bf16 v[68:71], v[170:173], v[210:213], v[68:71]
	v_mfma_f32_16x16x32_bf16 v[64:67], v[178:181], v[210:213], v[64:67]
	s_setprio 0
	s_barrier
	s_add_i32 s30, s53, s36
	s_mov_b32 m0, s30
	ds_read_b128 v[182:185], v153 offset:49152
	ds_read_b128 v[186:189], v153 offset:50176
	ds_read_b128 v[190:193], v153 offset:51200
	ds_read_b128 v[194:197], v153 offset:52224
	ds_read_b128 v[198:201], v153 offset:53248
	ds_read_b128 v[202:205], v153 offset:54272
	ds_read_b128 v[206:209], v153 offset:55296
	ds_read_b128 v[210:213], v153 offset:56320
	global_load_lds_dwordx4 v130, s[98:99]
	s_add_i32 m0, s30, 0x2000
	s_add_u32 s28, s28, 0x200080
	s_addc_u32 s29, s29, 0
	s_add_i32 s30, s54, s36
	global_load_lds_dwordx4 v134, s[98:99]
	s_mov_b32 m0, s30
	s_nop 0
	global_load_lds_dwordx4 v130, s[28:29]
	s_add_i32 m0, s30, 0x2000
	s_nop 0
	global_load_lds_dwordx4 v134, s[28:29]
	s_mov_b32 m0, s41
	s_nop 0
	global_load_lds_dwordx4 v128, s[100:101]
	s_mov_b32 m0, s42
	s_nop 0
	global_load_lds_dwordx4 v132, s[100:101]
	s_waitcnt vmcnt(8)
	s_waitcnt lgkmcnt(0)
	s_barrier
	s_setprio 1
	s_waitcnt lgkmcnt(0)
	v_mfma_f32_16x16x32_bf16 v[60:63], v[144:147], v[182:185], v[60:63]
	v_mfma_f32_16x16x32_bf16 v[56:59], v[158:161], v[182:185], v[56:59]
	v_mfma_f32_16x16x32_bf16 v[48:51], v[144:147], v[190:193], v[48:51]
	v_mfma_f32_16x16x32_bf16 v[40:43], v[158:161], v[190:193], v[40:43]
	v_mfma_f32_16x16x32_bf16 v[32:35], v[144:147], v[198:201], v[32:35]
	v_mfma_f32_16x16x32_bf16 v[24:27], v[158:161], v[198:201], v[24:27]
	v_mfma_f32_16x16x32_bf16 v[16:19], v[144:147], v[206:209], v[16:19]
	v_mfma_f32_16x16x32_bf16 v[8:11], v[158:161], v[206:209], v[8:11]
	v_mfma_f32_16x16x32_bf16 v[60:63], v[154:157], v[186:189], v[60:63]
	v_mfma_f32_16x16x32_bf16 v[56:59], v[162:165], v[186:189], v[56:59]
	v_mfma_f32_16x16x32_bf16 v[48:51], v[154:157], v[194:197], v[48:51]
	v_mfma_f32_16x16x32_bf16 v[40:43], v[162:165], v[194:197], v[40:43]
	v_mfma_f32_16x16x32_bf16 v[32:35], v[154:157], v[202:205], v[32:35]
	v_mfma_f32_16x16x32_bf16 v[24:27], v[162:165], v[202:205], v[24:27]
	v_mfma_f32_16x16x32_bf16 v[16:19], v[154:157], v[210:213], v[16:19]
	v_mfma_f32_16x16x32_bf16 v[8:11], v[162:165], v[210:213], v[8:11]
	s_setprio 0
	s_setprio 1
	v_mfma_f32_16x16x32_bf16 v[52:55], v[166:169], v[182:185], v[52:55]
	v_mfma_f32_16x16x32_bf16 v[44:47], v[174:177], v[182:185], v[44:47]
	v_mfma_f32_16x16x32_bf16 v[36:39], v[166:169], v[190:193], v[36:39]
	v_mfma_f32_16x16x32_bf16 v[28:31], v[174:177], v[190:193], v[28:31]
	v_mfma_f32_16x16x32_bf16 v[20:23], v[166:169], v[198:201], v[20:23]
	v_mfma_f32_16x16x32_bf16 v[12:15], v[174:177], v[198:201], v[12:15]
	v_mfma_f32_16x16x32_bf16 v[4:7], v[166:169], v[206:209], v[4:7]
	v_mfma_f32_16x16x32_bf16 v[0:3], v[174:177], v[206:209], v[0:3]
	v_mfma_f32_16x16x32_bf16 v[52:55], v[170:173], v[186:189], v[52:55]
	v_mfma_f32_16x16x32_bf16 v[44:47], v[178:181], v[186:189], v[44:47]
	v_mfma_f32_16x16x32_bf16 v[36:39], v[170:173], v[194:197], v[36:39]
	v_mfma_f32_16x16x32_bf16 v[28:31], v[178:181], v[194:197], v[28:31]
	v_mfma_f32_16x16x32_bf16 v[20:23], v[170:173], v[202:205], v[20:23]
	v_mfma_f32_16x16x32_bf16 v[12:15], v[178:181], v[202:205], v[12:15]
	v_mfma_f32_16x16x32_bf16 v[4:7], v[170:173], v[210:213], v[4:7]
	v_mfma_f32_16x16x32_bf16 v[0:3], v[178:181], v[210:213], v[0:3]
	s_setprio 0
	s_barrier
	s_add_i32 s52, s52, 2
	s_add_u32 s26, s26, 0x100
	s_addc_u32 s27, s27, 0
	s_add_u32 s50, s50, 0x100
	s_addc_u32 s51, s51, 0
	s_cmpk_gt_u32 s52, 0x7d
	s_cbranch_scc0 .LBB0_996
	s_and_b64 vcc, exec, s[14:15]
	s_cbranch_vccz .LBB0_999
	s_barrier
